# in_proj non-rope epilogue rewritten branch-free per class; retention rg-wait counted per path; small per-XCD-slot start stagger on phases 1 and 9
# speedup vs baseline: 1.0171x; 1.0171x over previous
;     DI bool next(int i, Unit& u) const {
;         const long L = (long)i * G + c; if (L >= nwg) return false;
;         int wgid = (int)L; { const int q = nwg / NXCD, r = nwg % NXCD, xcd = wgid % NXCD, off = wgid / NXCD; wgid = (xcd < r ? xcd * (q + 1) : r * (q + 1) + (xcd - r) * q) + off; }
; __global__ void __launch_bounds__(512, 2) fwd_mega(Params p) {
;     ...
;         { pg8::Gemm g{(const bf16_t*)((unsigned char*)p.out + OB_XB), DM, (const bf16_t*)(ws + WS_WIN), MT, DIN, DM}; pg8::StaticOrder S; S.init(MT, DIN, G, cb);
;           EpiInProj E{P, p.out + O_RSTD1, (const unsigned*)(p.out + O_ROPE)}; pg8::gemm_phase<EpiInProj, true>(L, g, S, E); }
.LBB0_204:
	s_cmp_lt_i32 s66, 2
	s_cselect_b64 s[2:3], -1, 0
	s_add_u32 s82, s94, 0x3000000
	s_addc_u32 s83, s95, 0
	s_and_b64 s[0:1], s[2:3], s[0:1]
	s_andn2_b64 vcc, exec, s[0:1]
	s_cbranch_vccnz .LBB0_462
	s_and_b32 s98, s64, 7
	s_cmp_eq_u32 s98, 0
	s_cbranch_scc1 .Lstg1_done
.Lstg1_loop:
	s_sleep 16
	s_sub_u32 s98, s98, 1
	s_cmp_lg_u32 s98, 0
	s_cbranch_scc1 .Lstg1_loop
.Lstg1_done:
	s_cmpk_lt_i32 s64, 0x1d74
	s_cselect_b64 s[2:3], -1, 0
	s_cmpk_gt_i32 s64, 0x1d73
	v_readfirstlane_b32 s14, v153
	s_cbranch_scc1 .LBB0_208
	s_ashr_i32 s4, s64, 31
	s_lshr_b32 s4, s4, 29
	s_add_i32 s6, s64, s4
	s_and_b32 s4, s6, -8
	s_sub_i32 s7, s64, s4
	s_cmp_gt_i32 s7, 3
	s_cbranch_scc0 .LBB0_209
	s_mul_i32 s4, s7, 0x3ae
	s_add_i32 s8, s4, 4
	s_cbranch_execz .LBB0_210
	s_branch .LBB0_211

; DI f32x4 sigm4(f32x4 v) { f32x4 r; r.x = sigm(v.x); r.y = sigm(v.y); r.z = sigm(v.z); r.w = sigm(v.w); return r; }
;     template <int NAI> DI void run(AccRef acc, const Unit& u, int wr, int wc, int fr, int fq) const {
;     ...
;             for (int m = 0; m < 4; ++m) rsv[ai][m] = rstd[EPI_ROW(ai, m)];
; #pragma unroll
;         for (int ai = 0; ai < NAI; ++ai) {
;             if (pn < 8) {
;                 u32x4 cs[4][2];
; #pragma unroll
;                 for (int m = 0; m < 4; ++m) { const int row = EPI_ROW(ai, m); const int pos = row < MP ? (row & (SEQ - 1)) : (SEQ + ((row - MP) & 63));
;                     const unsigned* tp = rope + pos * 128 + cl; cs[m][0] = *(const u32x4*)tp; cs[m][1] = *(const u32x4*)(tp + 4); }
; #pragma unroll
;                 for (int m = 0; m < 4; ++m) { const int row = EPI_ROW(ai, m); bf16_t* prow = gbase + ((unsigned)row * pitch + (unsigned)cl);
;                     const float sc = pn >= 4 ? rsv[ai][m] * 0.0625f : rsv[ai][m];
;                     const u32x4 w0 = cs[m][0], w1 = cs[m][1];
;                     const f32x4 c0 = (f32x4){f16lo(w0.x), f16lo(w0.y), f16lo(w0.z), f16lo(w0.w)}, s0 = (f32x4){f16hi(w0.x), f16hi(w0.y), f16hi(w0.z), f16hi(w0.w)};
;                     const f32x4 c1 = (f32x4){f16lo(w1.x), f16lo(w1.y), f16lo(w1.z), f16lo(w1.w)}, s1 = (f32x4){f16hi(w1.x), f16hi(w1.y), f16hi(w1.z), f16hi(w1.w)};
;                     const f32x4 x10 = acc[ai][0][m][0] * sc, x11 = acc[ai][0][m][1] * sc, x20 = acc[ai][1][m][0] * sc, x21 = acc[ai][1][m][1] * sc;
;                     st8(prow, x10 * c0 - x20 * s0, x11 * c1 - x21 * s1);
;                     st8(prow + 128, x20 * c0 + x10 * s0, x21 * c1 + x11 * s1); }
;             } else {
; #pragma unroll
;                 for (int m = 0; m < 4; ++m) { const int row = EPI_ROW(ai, m); bf16_t* prow = gbase + ((unsigned)row * pitch + (unsigned)cl); const float rs = rsv[ai][m];
; #pragma unroll
;                     for (int bj = 0; bj < 2; ++bj) {
;                         f32x4 a = acc[ai][bj][m][0] * rs, b = acc[ai][bj][m][1] * rs;
;                         if (pn >= 12 && pn < 16) { a = a * sigm4(a); b = b * sigm4(b); }
;                         else if (pn >= 16 && pn < 20) { a = a * 0.125f; b = b * 0.125f; }
;                         else if (pn >= 21) { a = sigm4(a); b = sigm4(b); }
;                         st8(prow + bj * 128, a, b);
;                     } }
.LBB0_230:
	v_add_u32_e32 v174, s30, v208
	v_add_u32_e32 v176, 16, v174
	v_add_u32_e32 v170, 32, v174
	v_add_u32_e32 v166, 48, v174
	v_ashrrev_i32_e32 v175, 31, v174
	v_ashrrev_i32_e32 v177, 31, v176
	v_ashrrev_i32_e32 v171, 31, v170
	v_ashrrev_i32_e32 v167, 31, v166
	v_add_u32_e32 v158, 0x80, v174
	v_add_u32_e32 v160, 0x90, v174
	v_add_u32_e32 v154, 0xa0, v174
	v_add_u32_e32 v148, 0xb0, v174
	v_lshl_add_u64 v[150:151], v[174:175], 2, s[10:11]
	v_lshl_add_u64 v[156:157], v[176:177], 2, s[10:11]
	v_lshl_add_u64 v[162:163], v[170:171], 2, s[10:11]
	v_lshl_add_u64 v[164:165], v[166:167], 2, s[10:11]
	v_ashrrev_i32_e32 v159, 31, v158
	v_ashrrev_i32_e32 v161, 31, v160
	v_ashrrev_i32_e32 v155, 31, v154
	v_ashrrev_i32_e32 v149, 31, v148
	v_lshl_add_u64 v[182:183], v[158:159], 2, s[10:11]
	v_lshl_add_u64 v[184:185], v[160:161], 2, s[10:11]
	v_lshl_add_u64 v[186:187], v[154:155], 2, s[10:11]
	v_lshl_add_u64 v[188:189], v[148:149], 2, s[10:11]
	global_load_dword v180, v[150:151], off
	global_load_dword v178, v[156:157], off
	global_load_dword v172, v[162:163], off
	global_load_dword v168, v[164:165], off
	s_nop 0
	global_load_dword v164, v[182:183], off
	global_load_dword v162, v[184:185], off
	global_load_dword v156, v[186:187], off
	global_load_dword v150, v[188:189], off
	s_cmp_gt_i32 s34, 7
	s_cselect_b64 s[30:31], -1, 0
	s_cmp_eq_u32 s34, 20
	s_cselect_b32 s23, 8, 10
	s_and_b32 s21, s34, 0x7ffffffc
	s_cmp_gt_i32 s34, 20
	s_cselect_b64 s[6:7], -1, 0
	s_cmp_gt_i32 s34, 3
	s_cselect_b64 s[4:5], -1, 0
	s_cmp_lt_i32 s34, 8
	s_mov_b64 s[34:35], -1
	s_cbranch_scc1 .LBB0_272
	s_waitcnt vmcnt(0)
	s_cmp_eq_u32 s21, 12
	s_cbranch_scc1 .Lipe_silu
	s_cmp_eq_u32 s21, 16
	s_cbranch_scc1 .Lipe_s125
	s_and_b64 vcc, exec, s[6:7]
	s_cbranch_vccnz .Lipe_sigm
	v_lshl_or_b32 v136, v174, s23, v210
	v_lshl_add_u64 v[182:183], v[136:137], 1, s[28:29]
	v_pk_mul_f32 v[124:125], v[124:125], v[180:181] op_sel_hi:[1,0]
	v_pk_mul_f32 v[126:127], v[126:127], v[180:181] op_sel_hi:[1,0]
	v_pk_mul_f32 v[120:121], v[120:121], v[180:181] op_sel_hi:[1,0]
	v_pk_mul_f32 v[122:123], v[122:123], v[180:181] op_sel_hi:[1,0]
	v_cvt_pk_bf16_f32 v186, v124, v125
	v_cvt_pk_bf16_f32 v187, v126, v127
	v_cvt_pk_bf16_f32 v188, v120, v121
	v_cvt_pk_bf16_f32 v189, v122, v123
	global_store_dwordx4 v[182:183], v[186:189], off
	v_pk_mul_f32 v[116:117], v[116:117], v[180:181] op_sel_hi:[1,0]
	v_pk_mul_f32 v[118:119], v[118:119], v[180:181] op_sel_hi:[1,0]
	v_pk_mul_f32 v[112:113], v[112:113], v[180:181] op_sel_hi:[1,0]
	v_pk_mul_f32 v[114:115], v[114:115], v[180:181] op_sel_hi:[1,0]
	v_cvt_pk_bf16_f32 v190, v116, v117
	v_cvt_pk_bf16_f32 v191, v118, v119
	v_cvt_pk_bf16_f32 v192, v112, v113
	v_cvt_pk_bf16_f32 v193, v114, v115
	global_store_dwordx4 v[182:183], v[190:193], off offset:256
	v_lshl_or_b32 v136, v176, s23, v210
	v_lshl_add_u64 v[184:185], v[136:137], 1, s[28:29]
	v_pk_mul_f32 v[108:109], v[108:109], v[178:179] op_sel_hi:[1,0]
	v_pk_mul_f32 v[110:111], v[110:111], v[178:179] op_sel_hi:[1,0]
	v_pk_mul_f32 v[104:105], v[104:105], v[178:179] op_sel_hi:[1,0]
	v_pk_mul_f32 v[106:107], v[106:107], v[178:179] op_sel_hi:[1,0]
	v_cvt_pk_bf16_f32 v186, v108, v109
	v_cvt_pk_bf16_f32 v187, v110, v111
	v_cvt_pk_bf16_f32 v188, v104, v105
	v_cvt_pk_bf16_f32 v189, v106, v107
	global_store_dwordx4 v[184:185], v[186:189], off
	v_pk_mul_f32 v[100:101], v[100:101], v[178:179] op_sel_hi:[1,0]
	v_pk_mul_f32 v[102:103], v[102:103], v[178:179] op_sel_hi:[1,0]
	v_pk_mul_f32 v[96:97], v[96:97], v[178:179] op_sel_hi:[1,0]
	v_pk_mul_f32 v[98:99], v[98:99], v[178:179] op_sel_hi:[1,0]
	v_cvt_pk_bf16_f32 v190, v100, v101
	v_cvt_pk_bf16_f32 v191, v102, v103
	v_cvt_pk_bf16_f32 v192, v96, v97
	v_cvt_pk_bf16_f32 v193, v98, v99
	global_store_dwordx4 v[184:185], v[190:193], off offset:256
	v_lshl_or_b32 v136, v170, s23, v210
	v_lshl_add_u64 v[182:183], v[136:137], 1, s[28:29]
	v_pk_mul_f32 v[92:93], v[92:93], v[172:173] op_sel_hi:[1,0]
	v_pk_mul_f32 v[94:95], v[94:95], v[172:173] op_sel_hi:[1,0]
	v_pk_mul_f32 v[88:89], v[88:89], v[172:173] op_sel_hi:[1,0]
	v_pk_mul_f32 v[90:91], v[90:91], v[172:173] op_sel_hi:[1,0]
	v_cvt_pk_bf16_f32 v186, v92, v93
	v_cvt_pk_bf16_f32 v187, v94, v95
	v_cvt_pk_bf16_f32 v188, v88, v89
	v_cvt_pk_bf16_f32 v189, v90, v91
	global_store_dwordx4 v[182:183], v[186:189], off
	v_pk_mul_f32 v[84:85], v[84:85], v[172:173] op_sel_hi:[1,0]
	v_pk_mul_f32 v[86:87], v[86:87], v[172:173] op_sel_hi:[1,0]
	v_pk_mul_f32 v[80:81], v[80:81], v[172:173] op_sel_hi:[1,0]
	v_pk_mul_f32 v[82:83], v[82:83], v[172:173] op_sel_hi:[1,0]
	v_cvt_pk_bf16_f32 v190, v84, v85
	v_cvt_pk_bf16_f32 v191, v86, v87
	v_cvt_pk_bf16_f32 v192, v80, v81
	v_cvt_pk_bf16_f32 v193, v82, v83
	global_store_dwordx4 v[182:183], v[190:193], off offset:256
	v_lshl_or_b32 v136, v166, s23, v210
	v_lshl_add_u64 v[184:185], v[136:137], 1, s[28:29]
	v_pk_mul_f32 v[76:77], v[76:77], v[168:169] op_sel_hi:[1,0]
	v_pk_mul_f32 v[78:79], v[78:79], v[168:169] op_sel_hi:[1,0]
	v_pk_mul_f32 v[72:73], v[72:73], v[168:169] op_sel_hi:[1,0]
	v_pk_mul_f32 v[74:75], v[74:75], v[168:169] op_sel_hi:[1,0]
	v_cvt_pk_bf16_f32 v186, v76, v77
	v_cvt_pk_bf16_f32 v187, v78, v79
	v_cvt_pk_bf16_f32 v188, v72, v73
	v_cvt_pk_bf16_f32 v189, v74, v75
	global_store_dwordx4 v[184:185], v[186:189], off
	v_pk_mul_f32 v[68:69], v[68:69], v[168:169] op_sel_hi:[1,0]
	v_pk_mul_f32 v[70:71], v[70:71], v[168:169] op_sel_hi:[1,0]
	v_pk_mul_f32 v[64:65], v[64:65], v[168:169] op_sel_hi:[1,0]
	v_pk_mul_f32 v[66:67], v[66:67], v[168:169] op_sel_hi:[1,0]
	v_cvt_pk_bf16_f32 v190, v68, v69
	v_cvt_pk_bf16_f32 v191, v70, v71
	v_cvt_pk_bf16_f32 v192, v64, v65
	v_cvt_pk_bf16_f32 v193, v66, v67
; DI void st8(bf16_t* p, f32x4 a, f32x4 b) { u32x4 w; w.x = cvt_pk_bf16(a.x, a.y); w.y = cvt_pk_bf16(a.z, a.w); w.z = cvt_pk_bf16(b.x, b.y); w.w = cvt_pk_bf16(b.z, b.w); *(u32x4*)p = w; }
; DI f32x4 sigm4(f32x4 v) { f32x4 r; r.x = sigm(v.x); r.y = sigm(v.y); r.z = sigm(v.z); r.w = sigm(v.w); return r; }
;     template <int NAI> DI void run(AccRef acc, const Unit& u, int wr, int wc, int fr, int fq) const {
;     ...
; #pragma unroll
;                 for (int m = 0; m < 4; ++m) { const int row = EPI_ROW(ai, m); bf16_t* prow = gbase + ((unsigned)row * pitch + (unsigned)cl); const float rs = rsv[ai][m];
; #pragma unroll
;                     for (int bj = 0; bj < 2; ++bj) {
;                         f32x4 a = acc[ai][bj][m][0] * rs, b = acc[ai][bj][m][1] * rs;
;                         if (pn >= 12 && pn < 16) { a = a * sigm4(a); b = b * sigm4(b); }
;                         else if (pn >= 16 && pn < 20) { a = a * 0.125f; b = b * 0.125f; }
;                         else if (pn >= 21) { a = sigm4(a); b = sigm4(b); }
;                         st8(prow + bj * 128, a, b);
;                     } }
	global_store_dwordx4 v[184:185], v[190:193], off offset:256
	v_lshl_or_b32 v136, v158, s23, v210
	v_lshl_add_u64 v[182:183], v[136:137], 1, s[28:29]
	v_pk_mul_f32 v[60:61], v[60:61], v[164:165] op_sel_hi:[1,0]
	v_pk_mul_f32 v[62:63], v[62:63], v[164:165] op_sel_hi:[1,0]
	v_pk_mul_f32 v[56:57], v[56:57], v[164:165] op_sel_hi:[1,0]
	v_pk_mul_f32 v[58:59], v[58:59], v[164:165] op_sel_hi:[1,0]
	v_cvt_pk_bf16_f32 v186, v60, v61
	v_cvt_pk_bf16_f32 v187, v62, v63
	v_cvt_pk_bf16_f32 v188, v56, v57
	v_cvt_pk_bf16_f32 v189, v58, v59
	global_store_dwordx4 v[182:183], v[186:189], off
	v_pk_mul_f32 v[52:53], v[52:53], v[164:165] op_sel_hi:[1,0]
	v_pk_mul_f32 v[54:55], v[54:55], v[164:165] op_sel_hi:[1,0]
	v_pk_mul_f32 v[48:49], v[48:49], v[164:165] op_sel_hi:[1,0]
	v_pk_mul_f32 v[50:51], v[50:51], v[164:165] op_sel_hi:[1,0]
	v_cvt_pk_bf16_f32 v190, v52, v53
	v_cvt_pk_bf16_f32 v191, v54, v55
	v_cvt_pk_bf16_f32 v192, v48, v49
	v_cvt_pk_bf16_f32 v193, v50, v51
	global_store_dwordx4 v[182:183], v[190:193], off offset:256
	v_lshl_or_b32 v136, v160, s23, v210
	v_lshl_add_u64 v[184:185], v[136:137], 1, s[28:29]
	v_pk_mul_f32 v[44:45], v[44:45], v[162:163] op_sel_hi:[1,0]
	v_pk_mul_f32 v[46:47], v[46:47], v[162:163] op_sel_hi:[1,0]
	v_pk_mul_f32 v[40:41], v[40:41], v[162:163] op_sel_hi:[1,0]
	v_pk_mul_f32 v[42:43], v[42:43], v[162:163] op_sel_hi:[1,0]
	v_cvt_pk_bf16_f32 v186, v44, v45
	v_cvt_pk_bf16_f32 v187, v46, v47
	v_cvt_pk_bf16_f32 v188, v40, v41
	v_cvt_pk_bf16_f32 v189, v42, v43
	global_store_dwordx4 v[184:185], v[186:189], off
	v_pk_mul_f32 v[36:37], v[36:37], v[162:163] op_sel_hi:[1,0]
	v_pk_mul_f32 v[38:39], v[38:39], v[162:163] op_sel_hi:[1,0]
	v_pk_mul_f32 v[32:33], v[32:33], v[162:163] op_sel_hi:[1,0]
	v_pk_mul_f32 v[34:35], v[34:35], v[162:163] op_sel_hi:[1,0]
	v_cvt_pk_bf16_f32 v190, v36, v37
	v_cvt_pk_bf16_f32 v191, v38, v39
	v_cvt_pk_bf16_f32 v192, v32, v33
	v_cvt_pk_bf16_f32 v193, v34, v35
	global_store_dwordx4 v[184:185], v[190:193], off offset:256
	v_lshl_or_b32 v136, v154, s23, v210
	v_lshl_add_u64 v[182:183], v[136:137], 1, s[28:29]
	v_pk_mul_f32 v[28:29], v[28:29], v[156:157] op_sel_hi:[1,0]
	v_pk_mul_f32 v[30:31], v[30:31], v[156:157] op_sel_hi:[1,0]
	v_pk_mul_f32 v[24:25], v[24:25], v[156:157] op_sel_hi:[1,0]
	v_pk_mul_f32 v[26:27], v[26:27], v[156:157] op_sel_hi:[1,0]
	v_cvt_pk_bf16_f32 v186, v28, v29
	v_cvt_pk_bf16_f32 v187, v30, v31
	v_cvt_pk_bf16_f32 v188, v24, v25
	v_cvt_pk_bf16_f32 v189, v26, v27
	global_store_dwordx4 v[182:183], v[186:189], off
	v_pk_mul_f32 v[20:21], v[20:21], v[156:157] op_sel_hi:[1,0]
	v_pk_mul_f32 v[22:23], v[22:23], v[156:157] op_sel_hi:[1,0]
	v_pk_mul_f32 v[16:17], v[16:17], v[156:157] op_sel_hi:[1,0]
	v_pk_mul_f32 v[18:19], v[18:19], v[156:157] op_sel_hi:[1,0]
	v_cvt_pk_bf16_f32 v190, v20, v21
	v_cvt_pk_bf16_f32 v191, v22, v23
	v_cvt_pk_bf16_f32 v192, v16, v17
	v_cvt_pk_bf16_f32 v193, v18, v19
	global_store_dwordx4 v[182:183], v[190:193], off offset:256
	v_lshl_or_b32 v136, v148, s23, v210
	v_lshl_add_u64 v[184:185], v[136:137], 1, s[28:29]
	v_pk_mul_f32 v[12:13], v[12:13], v[150:151] op_sel_hi:[1,0]
	v_pk_mul_f32 v[14:15], v[14:15], v[150:151] op_sel_hi:[1,0]
	v_pk_mul_f32 v[8:9], v[8:9], v[150:151] op_sel_hi:[1,0]
	v_pk_mul_f32 v[10:11], v[10:11], v[150:151] op_sel_hi:[1,0]
	v_cvt_pk_bf16_f32 v186, v12, v13
	v_cvt_pk_bf16_f32 v187, v14, v15
	v_cvt_pk_bf16_f32 v188, v8, v9
	v_cvt_pk_bf16_f32 v189, v10, v11
	global_store_dwordx4 v[184:185], v[186:189], off
	v_pk_mul_f32 v[4:5], v[4:5], v[150:151] op_sel_hi:[1,0]
	v_pk_mul_f32 v[6:7], v[6:7], v[150:151] op_sel_hi:[1,0]
	v_pk_mul_f32 v[0:1], v[0:1], v[150:151] op_sel_hi:[1,0]
	v_pk_mul_f32 v[2:3], v[2:3], v[150:151] op_sel_hi:[1,0]
	v_cvt_pk_bf16_f32 v190, v4, v5
	v_cvt_pk_bf16_f32 v191, v6, v7
	v_cvt_pk_bf16_f32 v192, v0, v1
	v_cvt_pk_bf16_f32 v193, v2, v3
	global_store_dwordx4 v[184:185], v[190:193], off offset:256
	s_branch .LBB0_275
.Lipe_s125:
	v_lshl_or_b32 v136, v174, s23, v210
	v_lshl_add_u64 v[182:183], v[136:137], 1, s[28:29]
	v_mul_f32_e32 v194, 0x3e000000, v180
	v_pk_mul_f32 v[124:125], v[124:125], v[194:195] op_sel_hi:[1,0]
	v_pk_mul_f32 v[126:127], v[126:127], v[194:195] op_sel_hi:[1,0]
	v_pk_mul_f32 v[120:121], v[120:121], v[194:195] op_sel_hi:[1,0]
	v_pk_mul_f32 v[122:123], v[122:123], v[194:195] op_sel_hi:[1,0]
	v_cvt_pk_bf16_f32 v186, v124, v125
	v_cvt_pk_bf16_f32 v187, v126, v127
	v_cvt_pk_bf16_f32 v188, v120, v121
	v_cvt_pk_bf16_f32 v189, v122, v123
	global_store_dwordx4 v[182:183], v[186:189], off
	v_pk_mul_f32 v[116:117], v[116:117], v[194:195] op_sel_hi:[1,0]
	v_pk_mul_f32 v[118:119], v[118:119], v[194:195] op_sel_hi:[1,0]
	v_pk_mul_f32 v[112:113], v[112:113], v[194:195] op_sel_hi:[1,0]
	v_pk_mul_f32 v[114:115], v[114:115], v[194:195] op_sel_hi:[1,0]
	v_cvt_pk_bf16_f32 v190, v116, v117
	v_cvt_pk_bf16_f32 v191, v118, v119
	v_cvt_pk_bf16_f32 v192, v112, v113
	v_cvt_pk_bf16_f32 v193, v114, v115
	global_store_dwordx4 v[182:183], v[190:193], off offset:256
	v_lshl_or_b32 v136, v176, s23, v210
	v_lshl_add_u64 v[184:185], v[136:137], 1, s[28:29]
	v_mul_f32_e32 v196, 0x3e000000, v178
	v_pk_mul_f32 v[108:109], v[108:109], v[196:197] op_sel_hi:[1,0]
	v_pk_mul_f32 v[110:111], v[110:111], v[196:197] op_sel_hi:[1,0]
	v_pk_mul_f32 v[104:105], v[104:105], v[196:197] op_sel_hi:[1,0]
	v_pk_mul_f32 v[106:107], v[106:107], v[196:197] op_sel_hi:[1,0]
	v_cvt_pk_bf16_f32 v186, v108, v109
	v_cvt_pk_bf16_f32 v187, v110, v111
	v_cvt_pk_bf16_f32 v188, v104, v105
	v_cvt_pk_bf16_f32 v189, v106, v107
	global_store_dwordx4 v[184:185], v[186:189], off
	v_pk_mul_f32 v[100:101], v[100:101], v[196:197] op_sel_hi:[1,0]
	v_pk_mul_f32 v[102:103], v[102:103], v[196:197] op_sel_hi:[1,0]
; DI void st8(bf16_t* p, f32x4 a, f32x4 b) { u32x4 w; w.x = cvt_pk_bf16(a.x, a.y); w.y = cvt_pk_bf16(a.z, a.w); w.z = cvt_pk_bf16(b.x, b.y); w.w = cvt_pk_bf16(b.z, b.w); *(u32x4*)p = w; }
; DI f32x4 sigm4(f32x4 v) { f32x4 r; r.x = sigm(v.x); r.y = sigm(v.y); r.z = sigm(v.z); r.w = sigm(v.w); return r; }
;     template <int NAI> DI void run(AccRef acc, const Unit& u, int wr, int wc, int fr, int fq) const {
;     ...
; #pragma unroll
;                 for (int m = 0; m < 4; ++m) { const int row = EPI_ROW(ai, m); bf16_t* prow = gbase + ((unsigned)row * pitch + (unsigned)cl); const float rs = rsv[ai][m];
; #pragma unroll
;                     for (int bj = 0; bj < 2; ++bj) {
;                         f32x4 a = acc[ai][bj][m][0] * rs, b = acc[ai][bj][m][1] * rs;
;                         if (pn >= 12 && pn < 16) { a = a * sigm4(a); b = b * sigm4(b); }
;                         else if (pn >= 16 && pn < 20) { a = a * 0.125f; b = b * 0.125f; }
;                         else if (pn >= 21) { a = sigm4(a); b = sigm4(b); }
;                         st8(prow + bj * 128, a, b);
;                     } }
	v_pk_mul_f32 v[96:97], v[96:97], v[196:197] op_sel_hi:[1,0]
	v_pk_mul_f32 v[98:99], v[98:99], v[196:197] op_sel_hi:[1,0]
	v_cvt_pk_bf16_f32 v190, v100, v101
	v_cvt_pk_bf16_f32 v191, v102, v103
	v_cvt_pk_bf16_f32 v192, v96, v97
	v_cvt_pk_bf16_f32 v193, v98, v99
	global_store_dwordx4 v[184:185], v[190:193], off offset:256
	v_lshl_or_b32 v136, v170, s23, v210
	v_lshl_add_u64 v[182:183], v[136:137], 1, s[28:29]
	v_mul_f32_e32 v194, 0x3e000000, v172
	v_pk_mul_f32 v[92:93], v[92:93], v[194:195] op_sel_hi:[1,0]
	v_pk_mul_f32 v[94:95], v[94:95], v[194:195] op_sel_hi:[1,0]
	v_pk_mul_f32 v[88:89], v[88:89], v[194:195] op_sel_hi:[1,0]
	v_pk_mul_f32 v[90:91], v[90:91], v[194:195] op_sel_hi:[1,0]
	v_cvt_pk_bf16_f32 v186, v92, v93
	v_cvt_pk_bf16_f32 v187, v94, v95
	v_cvt_pk_bf16_f32 v188, v88, v89
	v_cvt_pk_bf16_f32 v189, v90, v91
	global_store_dwordx4 v[182:183], v[186:189], off
	v_pk_mul_f32 v[84:85], v[84:85], v[194:195] op_sel_hi:[1,0]
	v_pk_mul_f32 v[86:87], v[86:87], v[194:195] op_sel_hi:[1,0]
	v_pk_mul_f32 v[80:81], v[80:81], v[194:195] op_sel_hi:[1,0]
	v_pk_mul_f32 v[82:83], v[82:83], v[194:195] op_sel_hi:[1,0]
	v_cvt_pk_bf16_f32 v190, v84, v85
	v_cvt_pk_bf16_f32 v191, v86, v87
	v_cvt_pk_bf16_f32 v192, v80, v81
	v_cvt_pk_bf16_f32 v193, v82, v83
	global_store_dwordx4 v[182:183], v[190:193], off offset:256
	v_lshl_or_b32 v136, v166, s23, v210
	v_lshl_add_u64 v[184:185], v[136:137], 1, s[28:29]
	v_mul_f32_e32 v196, 0x3e000000, v168
	v_pk_mul_f32 v[76:77], v[76:77], v[196:197] op_sel_hi:[1,0]
	v_pk_mul_f32 v[78:79], v[78:79], v[196:197] op_sel_hi:[1,0]
	v_pk_mul_f32 v[72:73], v[72:73], v[196:197] op_sel_hi:[1,0]
	v_pk_mul_f32 v[74:75], v[74:75], v[196:197] op_sel_hi:[1,0]
	v_cvt_pk_bf16_f32 v186, v76, v77
	v_cvt_pk_bf16_f32 v187, v78, v79
	v_cvt_pk_bf16_f32 v188, v72, v73
	v_cvt_pk_bf16_f32 v189, v74, v75
	global_store_dwordx4 v[184:185], v[186:189], off
	v_pk_mul_f32 v[68:69], v[68:69], v[196:197] op_sel_hi:[1,0]
	v_pk_mul_f32 v[70:71], v[70:71], v[196:197] op_sel_hi:[1,0]
	v_pk_mul_f32 v[64:65], v[64:65], v[196:197] op_sel_hi:[1,0]
	v_pk_mul_f32 v[66:67], v[66:67], v[196:197] op_sel_hi:[1,0]
	v_cvt_pk_bf16_f32 v190, v68, v69
	v_cvt_pk_bf16_f32 v191, v70, v71
	v_cvt_pk_bf16_f32 v192, v64, v65
	v_cvt_pk_bf16_f32 v193, v66, v67
	global_store_dwordx4 v[184:185], v[190:193], off offset:256
	v_lshl_or_b32 v136, v158, s23, v210
	v_lshl_add_u64 v[182:183], v[136:137], 1, s[28:29]
	v_mul_f32_e32 v194, 0x3e000000, v164
	v_pk_mul_f32 v[60:61], v[60:61], v[194:195] op_sel_hi:[1,0]
	v_pk_mul_f32 v[62:63], v[62:63], v[194:195] op_sel_hi:[1,0]
	v_pk_mul_f32 v[56:57], v[56:57], v[194:195] op_sel_hi:[1,0]
	v_pk_mul_f32 v[58:59], v[58:59], v[194:195] op_sel_hi:[1,0]
	v_cvt_pk_bf16_f32 v186, v60, v61
	v_cvt_pk_bf16_f32 v187, v62, v63
	v_cvt_pk_bf16_f32 v188, v56, v57
	v_cvt_pk_bf16_f32 v189, v58, v59
	global_store_dwordx4 v[182:183], v[186:189], off
	v_pk_mul_f32 v[52:53], v[52:53], v[194:195] op_sel_hi:[1,0]
	v_pk_mul_f32 v[54:55], v[54:55], v[194:195] op_sel_hi:[1,0]
	v_pk_mul_f32 v[48:49], v[48:49], v[194:195] op_sel_hi:[1,0]
	v_pk_mul_f32 v[50:51], v[50:51], v[194:195] op_sel_hi:[1,0]
	v_cvt_pk_bf16_f32 v190, v52, v53
	v_cvt_pk_bf16_f32 v191, v54, v55
	v_cvt_pk_bf16_f32 v192, v48, v49
	v_cvt_pk_bf16_f32 v193, v50, v51
	global_store_dwordx4 v[182:183], v[190:193], off offset:256
	v_lshl_or_b32 v136, v160, s23, v210
	v_lshl_add_u64 v[184:185], v[136:137], 1, s[28:29]
	v_mul_f32_e32 v196, 0x3e000000, v162
	v_pk_mul_f32 v[44:45], v[44:45], v[196:197] op_sel_hi:[1,0]
	v_pk_mul_f32 v[46:47], v[46:47], v[196:197] op_sel_hi:[1,0]
	v_pk_mul_f32 v[40:41], v[40:41], v[196:197] op_sel_hi:[1,0]
	v_pk_mul_f32 v[42:43], v[42:43], v[196:197] op_sel_hi:[1,0]
	v_cvt_pk_bf16_f32 v186, v44, v45
	v_cvt_pk_bf16_f32 v187, v46, v47
	v_cvt_pk_bf16_f32 v188, v40, v41
	v_cvt_pk_bf16_f32 v189, v42, v43
	global_store_dwordx4 v[184:185], v[186:189], off
	v_pk_mul_f32 v[36:37], v[36:37], v[196:197] op_sel_hi:[1,0]
	v_pk_mul_f32 v[38:39], v[38:39], v[196:197] op_sel_hi:[1,0]
	v_pk_mul_f32 v[32:33], v[32:33], v[196:197] op_sel_hi:[1,0]
	v_pk_mul_f32 v[34:35], v[34:35], v[196:197] op_sel_hi:[1,0]
	v_cvt_pk_bf16_f32 v190, v36, v37
	v_cvt_pk_bf16_f32 v191, v38, v39
	v_cvt_pk_bf16_f32 v192, v32, v33
	v_cvt_pk_bf16_f32 v193, v34, v35
	global_store_dwordx4 v[184:185], v[190:193], off offset:256
	v_lshl_or_b32 v136, v154, s23, v210
	v_lshl_add_u64 v[182:183], v[136:137], 1, s[28:29]
	v_mul_f32_e32 v194, 0x3e000000, v156
	v_pk_mul_f32 v[28:29], v[28:29], v[194:195] op_sel_hi:[1,0]
	v_pk_mul_f32 v[30:31], v[30:31], v[194:195] op_sel_hi:[1,0]
	v_pk_mul_f32 v[24:25], v[24:25], v[194:195] op_sel_hi:[1,0]
	v_pk_mul_f32 v[26:27], v[26:27], v[194:195] op_sel_hi:[1,0]
	v_cvt_pk_bf16_f32 v186, v28, v29
	v_cvt_pk_bf16_f32 v187, v30, v31
	v_cvt_pk_bf16_f32 v188, v24, v25
	v_cvt_pk_bf16_f32 v189, v26, v27
	global_store_dwordx4 v[182:183], v[186:189], off
	v_pk_mul_f32 v[20:21], v[20:21], v[194:195] op_sel_hi:[1,0]
	v_pk_mul_f32 v[22:23], v[22:23], v[194:195] op_sel_hi:[1,0]
	v_pk_mul_f32 v[16:17], v[16:17], v[194:195] op_sel_hi:[1,0]
	v_pk_mul_f32 v[18:19], v[18:19], v[194:195] op_sel_hi:[1,0]
	v_cvt_pk_bf16_f32 v190, v20, v21
	v_cvt_pk_bf16_f32 v191, v22, v23
	v_cvt_pk_bf16_f32 v192, v16, v17
	v_cvt_pk_bf16_f32 v193, v18, v19
	global_store_dwordx4 v[182:183], v[190:193], off offset:256
	v_lshl_or_b32 v136, v148, s23, v210
	v_lshl_add_u64 v[184:185], v[136:137], 1, s[28:29]
	v_mul_f32_e32 v196, 0x3e000000, v150
	v_pk_mul_f32 v[12:13], v[12:13], v[196:197] op_sel_hi:[1,0]
	v_pk_mul_f32 v[14:15], v[14:15], v[196:197] op_sel_hi:[1,0]
	v_pk_mul_f32 v[8:9], v[8:9], v[196:197] op_sel_hi:[1,0]
	v_pk_mul_f32 v[10:11], v[10:11], v[196:197] op_sel_hi:[1,0]
	v_cvt_pk_bf16_f32 v186, v12, v13
	v_cvt_pk_bf16_f32 v187, v14, v15
	v_cvt_pk_bf16_f32 v188, v8, v9
	v_cvt_pk_bf16_f32 v189, v10, v11
	global_store_dwordx4 v[184:185], v[186:189], off
	v_pk_mul_f32 v[4:5], v[4:5], v[196:197] op_sel_hi:[1,0]
	v_pk_mul_f32 v[6:7], v[6:7], v[196:197] op_sel_hi:[1,0]
	v_pk_mul_f32 v[0:1], v[0:1], v[196:197] op_sel_hi:[1,0]
	v_pk_mul_f32 v[2:3], v[2:3], v[196:197] op_sel_hi:[1,0]
	v_cvt_pk_bf16_f32 v190, v4, v5
	v_cvt_pk_bf16_f32 v191, v6, v7
	v_cvt_pk_bf16_f32 v192, v0, v1
	v_cvt_pk_bf16_f32 v193, v2, v3
	global_store_dwordx4 v[184:185], v[190:193], off offset:256
	s_branch .LBB0_275
; DI void st8(bf16_t* p, f32x4 a, f32x4 b) { u32x4 w; w.x = cvt_pk_bf16(a.x, a.y); w.y = cvt_pk_bf16(a.z, a.w); w.z = cvt_pk_bf16(b.x, b.y); w.w = cvt_pk_bf16(b.z, b.w); *(u32x4*)p = w; }
; DI float sigm(float x) { return __builtin_amdgcn_rcpf(1.f + __builtin_amdgcn_exp2f(-x * LOG2E)); }
; DI f32x4 sigm4(f32x4 v) { f32x4 r; r.x = sigm(v.x); r.y = sigm(v.y); r.z = sigm(v.z); r.w = sigm(v.w); return r; }
;     template <int NAI> DI void run(AccRef acc, const Unit& u, int wr, int wc, int fr, int fq) const {
;     ...
; #pragma unroll
;                 for (int m = 0; m < 4; ++m) { const int row = EPI_ROW(ai, m); bf16_t* prow = gbase + ((unsigned)row * pitch + (unsigned)cl); const float rs = rsv[ai][m];
; #pragma unroll
;                     for (int bj = 0; bj < 2; ++bj) {
;                         f32x4 a = acc[ai][bj][m][0] * rs, b = acc[ai][bj][m][1] * rs;
;                         if (pn >= 12 && pn < 16) { a = a * sigm4(a); b = b * sigm4(b); }
;                         else if (pn >= 16 && pn < 20) { a = a * 0.125f; b = b * 0.125f; }
;                         else if (pn >= 21) { a = sigm4(a); b = sigm4(b); }
;                         st8(prow + bj * 128, a, b);
.Lipe_sigm:
	v_lshl_or_b32 v136, v174, s23, v210
	v_lshl_add_u64 v[182:183], v[136:137], 1, s[28:29]
	v_pk_mul_f32 v[124:125], v[124:125], v[180:181] op_sel_hi:[1,0]
	v_pk_mul_f32 v[126:127], v[126:127], v[180:181] op_sel_hi:[1,0]
	v_pk_mul_f32 v[120:121], v[120:121], v[180:181] op_sel_hi:[1,0]
	v_pk_mul_f32 v[122:123], v[122:123], v[180:181] op_sel_hi:[1,0]
	v_mul_f32_e32 v214, 0xbfb8aa3b, v124
	v_mul_f32_e32 v215, 0xbfb8aa3b, v125
	v_mul_f32_e32 v216, 0xbfb8aa3b, v126
	v_mul_f32_e32 v217, 0xbfb8aa3b, v127
	v_mul_f32_e32 v218, 0xbfb8aa3b, v120
	v_mul_f32_e32 v219, 0xbfb8aa3b, v121
	v_mul_f32_e32 v220, 0xbfb8aa3b, v122
	v_mul_f32_e32 v221, 0xbfb8aa3b, v123
	v_exp_f32_e32 v214, v214
	v_exp_f32_e32 v215, v215
	v_exp_f32_e32 v216, v216
	v_exp_f32_e32 v217, v217
	v_exp_f32_e32 v218, v218
	v_exp_f32_e32 v219, v219
	v_exp_f32_e32 v220, v220
	v_exp_f32_e32 v221, v221
	v_add_f32_e32 v214, 1.0, v214
	v_add_f32_e32 v215, 1.0, v215
	v_add_f32_e32 v216, 1.0, v216
	v_add_f32_e32 v217, 1.0, v217
	v_add_f32_e32 v218, 1.0, v218
	v_add_f32_e32 v219, 1.0, v219
	v_add_f32_e32 v220, 1.0, v220
	v_add_f32_e32 v221, 1.0, v221
	v_rcp_f32_e32 v214, v214
	v_rcp_f32_e32 v215, v215
	v_rcp_f32_e32 v216, v216
	v_rcp_f32_e32 v217, v217
	v_rcp_f32_e32 v218, v218
	v_rcp_f32_e32 v219, v219
	v_rcp_f32_e32 v220, v220
	v_rcp_f32_e32 v221, v221
	v_cvt_pk_bf16_f32 v186, v214, v215
	v_cvt_pk_bf16_f32 v187, v216, v217
	v_cvt_pk_bf16_f32 v188, v218, v219
	v_cvt_pk_bf16_f32 v189, v220, v221
	global_store_dwordx4 v[182:183], v[186:189], off
	v_pk_mul_f32 v[116:117], v[116:117], v[180:181] op_sel_hi:[1,0]
	v_pk_mul_f32 v[118:119], v[118:119], v[180:181] op_sel_hi:[1,0]
	v_pk_mul_f32 v[112:113], v[112:113], v[180:181] op_sel_hi:[1,0]
	v_pk_mul_f32 v[114:115], v[114:115], v[180:181] op_sel_hi:[1,0]
	v_mul_f32_e32 v222, 0xbfb8aa3b, v116
	v_mul_f32_e32 v223, 0xbfb8aa3b, v117
	v_mul_f32_e32 v224, 0xbfb8aa3b, v118
	v_mul_f32_e32 v225, 0xbfb8aa3b, v119
	v_mul_f32_e32 v226, 0xbfb8aa3b, v112
	v_mul_f32_e32 v227, 0xbfb8aa3b, v113
	v_mul_f32_e32 v228, 0xbfb8aa3b, v114
	v_mul_f32_e32 v229, 0xbfb8aa3b, v115
	v_exp_f32_e32 v222, v222
	v_exp_f32_e32 v223, v223
	v_exp_f32_e32 v224, v224
	v_exp_f32_e32 v225, v225
	v_exp_f32_e32 v226, v226
	v_exp_f32_e32 v227, v227
	v_exp_f32_e32 v228, v228
	v_exp_f32_e32 v229, v229
	v_add_f32_e32 v222, 1.0, v222
	v_add_f32_e32 v223, 1.0, v223
	v_add_f32_e32 v224, 1.0, v224
	v_add_f32_e32 v225, 1.0, v225
	v_add_f32_e32 v226, 1.0, v226
	v_add_f32_e32 v227, 1.0, v227
	v_add_f32_e32 v228, 1.0, v228
	v_add_f32_e32 v229, 1.0, v229
	v_rcp_f32_e32 v222, v222
	v_rcp_f32_e32 v223, v223
	v_rcp_f32_e32 v224, v224
	v_rcp_f32_e32 v225, v225
	v_rcp_f32_e32 v226, v226
	v_rcp_f32_e32 v227, v227
	v_rcp_f32_e32 v228, v228
	v_rcp_f32_e32 v229, v229
	v_cvt_pk_bf16_f32 v190, v222, v223
	v_cvt_pk_bf16_f32 v191, v224, v225
	v_cvt_pk_bf16_f32 v192, v226, v227
	v_cvt_pk_bf16_f32 v193, v228, v229
	global_store_dwordx4 v[182:183], v[190:193], off offset:256
	v_lshl_or_b32 v136, v176, s23, v210
	v_lshl_add_u64 v[184:185], v[136:137], 1, s[28:29]
	v_pk_mul_f32 v[108:109], v[108:109], v[178:179] op_sel_hi:[1,0]
	v_pk_mul_f32 v[110:111], v[110:111], v[178:179] op_sel_hi:[1,0]
	v_pk_mul_f32 v[104:105], v[104:105], v[178:179] op_sel_hi:[1,0]
	v_pk_mul_f32 v[106:107], v[106:107], v[178:179] op_sel_hi:[1,0]
	v_mul_f32_e32 v214, 0xbfb8aa3b, v108
	v_mul_f32_e32 v215, 0xbfb8aa3b, v109
	v_mul_f32_e32 v216, 0xbfb8aa3b, v110
	v_mul_f32_e32 v217, 0xbfb8aa3b, v111
	v_mul_f32_e32 v218, 0xbfb8aa3b, v104
	v_mul_f32_e32 v219, 0xbfb8aa3b, v105
	v_mul_f32_e32 v220, 0xbfb8aa3b, v106
	v_mul_f32_e32 v221, 0xbfb8aa3b, v107
	v_exp_f32_e32 v214, v214
	v_exp_f32_e32 v215, v215
	v_exp_f32_e32 v216, v216
	v_exp_f32_e32 v217, v217
	v_exp_f32_e32 v218, v218
	v_exp_f32_e32 v219, v219
	v_exp_f32_e32 v220, v220
	v_exp_f32_e32 v221, v221
	v_add_f32_e32 v214, 1.0, v214
	v_add_f32_e32 v215, 1.0, v215
	v_add_f32_e32 v216, 1.0, v216
	v_add_f32_e32 v217, 1.0, v217
	v_add_f32_e32 v218, 1.0, v218
	v_add_f32_e32 v219, 1.0, v219
	v_add_f32_e32 v220, 1.0, v220
	v_add_f32_e32 v221, 1.0, v221
	v_rcp_f32_e32 v214, v214
	v_rcp_f32_e32 v215, v215
	v_rcp_f32_e32 v216, v216
	v_rcp_f32_e32 v217, v217
	v_rcp_f32_e32 v218, v218
	v_rcp_f32_e32 v219, v219
	v_rcp_f32_e32 v220, v220
	v_rcp_f32_e32 v221, v221
	v_cvt_pk_bf16_f32 v186, v214, v215
	v_cvt_pk_bf16_f32 v187, v216, v217
	v_cvt_pk_bf16_f32 v188, v218, v219
	v_cvt_pk_bf16_f32 v189, v220, v221
	global_store_dwordx4 v[184:185], v[186:189], off
	v_pk_mul_f32 v[100:101], v[100:101], v[178:179] op_sel_hi:[1,0]
	v_pk_mul_f32 v[102:103], v[102:103], v[178:179] op_sel_hi:[1,0]
	v_pk_mul_f32 v[96:97], v[96:97], v[178:179] op_sel_hi:[1,0]
	v_pk_mul_f32 v[98:99], v[98:99], v[178:179] op_sel_hi:[1,0]
	v_mul_f32_e32 v222, 0xbfb8aa3b, v100
	v_mul_f32_e32 v223, 0xbfb8aa3b, v101
	v_mul_f32_e32 v224, 0xbfb8aa3b, v102
	v_mul_f32_e32 v225, 0xbfb8aa3b, v103
	v_mul_f32_e32 v226, 0xbfb8aa3b, v96
	v_mul_f32_e32 v227, 0xbfb8aa3b, v97
	v_mul_f32_e32 v228, 0xbfb8aa3b, v98
	v_mul_f32_e32 v229, 0xbfb8aa3b, v99
	v_exp_f32_e32 v222, v222
	v_exp_f32_e32 v223, v223
	v_exp_f32_e32 v224, v224
	v_exp_f32_e32 v225, v225
	v_exp_f32_e32 v226, v226
	v_exp_f32_e32 v227, v227
	v_exp_f32_e32 v228, v228
	v_exp_f32_e32 v229, v229
	v_add_f32_e32 v222, 1.0, v222
	v_add_f32_e32 v223, 1.0, v223
	v_add_f32_e32 v224, 1.0, v224
	v_add_f32_e32 v225, 1.0, v225
	v_add_f32_e32 v226, 1.0, v226
	v_add_f32_e32 v227, 1.0, v227
	v_add_f32_e32 v228, 1.0, v228
	v_add_f32_e32 v229, 1.0, v229
	v_rcp_f32_e32 v222, v222
	v_rcp_f32_e32 v223, v223
	v_rcp_f32_e32 v224, v224
	v_rcp_f32_e32 v225, v225
	v_rcp_f32_e32 v226, v226
	v_rcp_f32_e32 v227, v227
; DI void st8(bf16_t* p, f32x4 a, f32x4 b) { u32x4 w; w.x = cvt_pk_bf16(a.x, a.y); w.y = cvt_pk_bf16(a.z, a.w); w.z = cvt_pk_bf16(b.x, b.y); w.w = cvt_pk_bf16(b.z, b.w); *(u32x4*)p = w; }
; DI float sigm(float x) { return __builtin_amdgcn_rcpf(1.f + __builtin_amdgcn_exp2f(-x * LOG2E)); }
; DI f32x4 sigm4(f32x4 v) { f32x4 r; r.x = sigm(v.x); r.y = sigm(v.y); r.z = sigm(v.z); r.w = sigm(v.w); return r; }
;     template <int NAI> DI void run(AccRef acc, const Unit& u, int wr, int wc, int fr, int fq) const {
;     ...
; #pragma unroll
;                 for (int m = 0; m < 4; ++m) { const int row = EPI_ROW(ai, m); bf16_t* prow = gbase + ((unsigned)row * pitch + (unsigned)cl); const float rs = rsv[ai][m];
; #pragma unroll
;                     for (int bj = 0; bj < 2; ++bj) {
;                         f32x4 a = acc[ai][bj][m][0] * rs, b = acc[ai][bj][m][1] * rs;
;                         if (pn >= 12 && pn < 16) { a = a * sigm4(a); b = b * sigm4(b); }
;                         else if (pn >= 16 && pn < 20) { a = a * 0.125f; b = b * 0.125f; }
;                         else if (pn >= 21) { a = sigm4(a); b = sigm4(b); }
;                         st8(prow + bj * 128, a, b);
	v_rcp_f32_e32 v228, v228
	v_rcp_f32_e32 v229, v229
	v_cvt_pk_bf16_f32 v190, v222, v223
	v_cvt_pk_bf16_f32 v191, v224, v225
	v_cvt_pk_bf16_f32 v192, v226, v227
	v_cvt_pk_bf16_f32 v193, v228, v229
	global_store_dwordx4 v[184:185], v[190:193], off offset:256
	v_lshl_or_b32 v136, v170, s23, v210
	v_lshl_add_u64 v[182:183], v[136:137], 1, s[28:29]
	v_pk_mul_f32 v[92:93], v[92:93], v[172:173] op_sel_hi:[1,0]
	v_pk_mul_f32 v[94:95], v[94:95], v[172:173] op_sel_hi:[1,0]
	v_pk_mul_f32 v[88:89], v[88:89], v[172:173] op_sel_hi:[1,0]
	v_pk_mul_f32 v[90:91], v[90:91], v[172:173] op_sel_hi:[1,0]
	v_mul_f32_e32 v214, 0xbfb8aa3b, v92
	v_mul_f32_e32 v215, 0xbfb8aa3b, v93
	v_mul_f32_e32 v216, 0xbfb8aa3b, v94
	v_mul_f32_e32 v217, 0xbfb8aa3b, v95
	v_mul_f32_e32 v218, 0xbfb8aa3b, v88
	v_mul_f32_e32 v219, 0xbfb8aa3b, v89
	v_mul_f32_e32 v220, 0xbfb8aa3b, v90
	v_mul_f32_e32 v221, 0xbfb8aa3b, v91
	v_exp_f32_e32 v214, v214
	v_exp_f32_e32 v215, v215
	v_exp_f32_e32 v216, v216
	v_exp_f32_e32 v217, v217
	v_exp_f32_e32 v218, v218
	v_exp_f32_e32 v219, v219
	v_exp_f32_e32 v220, v220
	v_exp_f32_e32 v221, v221
	v_add_f32_e32 v214, 1.0, v214
	v_add_f32_e32 v215, 1.0, v215
	v_add_f32_e32 v216, 1.0, v216
	v_add_f32_e32 v217, 1.0, v217
	v_add_f32_e32 v218, 1.0, v218
	v_add_f32_e32 v219, 1.0, v219
	v_add_f32_e32 v220, 1.0, v220
	v_add_f32_e32 v221, 1.0, v221
	v_rcp_f32_e32 v214, v214
	v_rcp_f32_e32 v215, v215
	v_rcp_f32_e32 v216, v216
	v_rcp_f32_e32 v217, v217
	v_rcp_f32_e32 v218, v218
	v_rcp_f32_e32 v219, v219
	v_rcp_f32_e32 v220, v220
	v_rcp_f32_e32 v221, v221
	v_cvt_pk_bf16_f32 v186, v214, v215
	v_cvt_pk_bf16_f32 v187, v216, v217
	v_cvt_pk_bf16_f32 v188, v218, v219
	v_cvt_pk_bf16_f32 v189, v220, v221
	global_store_dwordx4 v[182:183], v[186:189], off
	v_pk_mul_f32 v[84:85], v[84:85], v[172:173] op_sel_hi:[1,0]
	v_pk_mul_f32 v[86:87], v[86:87], v[172:173] op_sel_hi:[1,0]
	v_pk_mul_f32 v[80:81], v[80:81], v[172:173] op_sel_hi:[1,0]
	v_pk_mul_f32 v[82:83], v[82:83], v[172:173] op_sel_hi:[1,0]
	v_mul_f32_e32 v222, 0xbfb8aa3b, v84
	v_mul_f32_e32 v223, 0xbfb8aa3b, v85
	v_mul_f32_e32 v224, 0xbfb8aa3b, v86
	v_mul_f32_e32 v225, 0xbfb8aa3b, v87
	v_mul_f32_e32 v226, 0xbfb8aa3b, v80
	v_mul_f32_e32 v227, 0xbfb8aa3b, v81
	v_mul_f32_e32 v228, 0xbfb8aa3b, v82
	v_mul_f32_e32 v229, 0xbfb8aa3b, v83
	v_exp_f32_e32 v222, v222
	v_exp_f32_e32 v223, v223
	v_exp_f32_e32 v224, v224
	v_exp_f32_e32 v225, v225
	v_exp_f32_e32 v226, v226
	v_exp_f32_e32 v227, v227
	v_exp_f32_e32 v228, v228
	v_exp_f32_e32 v229, v229
	v_add_f32_e32 v222, 1.0, v222
	v_add_f32_e32 v223, 1.0, v223
	v_add_f32_e32 v224, 1.0, v224
	v_add_f32_e32 v225, 1.0, v225
	v_add_f32_e32 v226, 1.0, v226
	v_add_f32_e32 v227, 1.0, v227
	v_add_f32_e32 v228, 1.0, v228
	v_add_f32_e32 v229, 1.0, v229
	v_rcp_f32_e32 v222, v222
	v_rcp_f32_e32 v223, v223
	v_rcp_f32_e32 v224, v224
	v_rcp_f32_e32 v225, v225
	v_rcp_f32_e32 v226, v226
	v_rcp_f32_e32 v227, v227
	v_rcp_f32_e32 v228, v228
	v_rcp_f32_e32 v229, v229
	v_cvt_pk_bf16_f32 v190, v222, v223
	v_cvt_pk_bf16_f32 v191, v224, v225
	v_cvt_pk_bf16_f32 v192, v226, v227
	v_cvt_pk_bf16_f32 v193, v228, v229
	global_store_dwordx4 v[182:183], v[190:193], off offset:256
	v_lshl_or_b32 v136, v166, s23, v210
	v_lshl_add_u64 v[184:185], v[136:137], 1, s[28:29]
	v_pk_mul_f32 v[76:77], v[76:77], v[168:169] op_sel_hi:[1,0]
	v_pk_mul_f32 v[78:79], v[78:79], v[168:169] op_sel_hi:[1,0]
	v_pk_mul_f32 v[72:73], v[72:73], v[168:169] op_sel_hi:[1,0]
	v_pk_mul_f32 v[74:75], v[74:75], v[168:169] op_sel_hi:[1,0]
	v_mul_f32_e32 v214, 0xbfb8aa3b, v76
	v_mul_f32_e32 v215, 0xbfb8aa3b, v77
	v_mul_f32_e32 v216, 0xbfb8aa3b, v78
	v_mul_f32_e32 v217, 0xbfb8aa3b, v79
	v_mul_f32_e32 v218, 0xbfb8aa3b, v72
	v_mul_f32_e32 v219, 0xbfb8aa3b, v73
	v_mul_f32_e32 v220, 0xbfb8aa3b, v74
	v_mul_f32_e32 v221, 0xbfb8aa3b, v75
	v_exp_f32_e32 v214, v214
	v_exp_f32_e32 v215, v215
	v_exp_f32_e32 v216, v216
	v_exp_f32_e32 v217, v217
	v_exp_f32_e32 v218, v218
	v_exp_f32_e32 v219, v219
	v_exp_f32_e32 v220, v220
	v_exp_f32_e32 v221, v221
	v_add_f32_e32 v214, 1.0, v214
	v_add_f32_e32 v215, 1.0, v215
	v_add_f32_e32 v216, 1.0, v216
	v_add_f32_e32 v217, 1.0, v217
	v_add_f32_e32 v218, 1.0, v218
	v_add_f32_e32 v219, 1.0, v219
	v_add_f32_e32 v220, 1.0, v220
	v_add_f32_e32 v221, 1.0, v221
	v_rcp_f32_e32 v214, v214
	v_rcp_f32_e32 v215, v215
	v_rcp_f32_e32 v216, v216
	v_rcp_f32_e32 v217, v217
	v_rcp_f32_e32 v218, v218
	v_rcp_f32_e32 v219, v219
	v_rcp_f32_e32 v220, v220
	v_rcp_f32_e32 v221, v221
	v_cvt_pk_bf16_f32 v186, v214, v215
	v_cvt_pk_bf16_f32 v187, v216, v217
	v_cvt_pk_bf16_f32 v188, v218, v219
	v_cvt_pk_bf16_f32 v189, v220, v221
	global_store_dwordx4 v[184:185], v[186:189], off
	v_pk_mul_f32 v[68:69], v[68:69], v[168:169] op_sel_hi:[1,0]
	v_pk_mul_f32 v[70:71], v[70:71], v[168:169] op_sel_hi:[1,0]
	v_pk_mul_f32 v[64:65], v[64:65], v[168:169] op_sel_hi:[1,0]
	v_pk_mul_f32 v[66:67], v[66:67], v[168:169] op_sel_hi:[1,0]
	v_mul_f32_e32 v222, 0xbfb8aa3b, v68
	v_mul_f32_e32 v223, 0xbfb8aa3b, v69
	v_mul_f32_e32 v224, 0xbfb8aa3b, v70
	v_mul_f32_e32 v225, 0xbfb8aa3b, v71
	v_mul_f32_e32 v226, 0xbfb8aa3b, v64
	v_mul_f32_e32 v227, 0xbfb8aa3b, v65
	v_mul_f32_e32 v228, 0xbfb8aa3b, v66
	v_mul_f32_e32 v229, 0xbfb8aa3b, v67
	v_exp_f32_e32 v222, v222
	v_exp_f32_e32 v223, v223
	v_exp_f32_e32 v224, v224
	v_exp_f32_e32 v225, v225
	v_exp_f32_e32 v226, v226
	v_exp_f32_e32 v227, v227
	v_exp_f32_e32 v228, v228
	v_exp_f32_e32 v229, v229
	v_add_f32_e32 v222, 1.0, v222
	v_add_f32_e32 v223, 1.0, v223
	v_add_f32_e32 v224, 1.0, v224
	v_add_f32_e32 v225, 1.0, v225
	v_add_f32_e32 v226, 1.0, v226
	v_add_f32_e32 v227, 1.0, v227
	v_add_f32_e32 v228, 1.0, v228
	v_add_f32_e32 v229, 1.0, v229
; DI void st8(bf16_t* p, f32x4 a, f32x4 b) { u32x4 w; w.x = cvt_pk_bf16(a.x, a.y); w.y = cvt_pk_bf16(a.z, a.w); w.z = cvt_pk_bf16(b.x, b.y); w.w = cvt_pk_bf16(b.z, b.w); *(u32x4*)p = w; }
; DI float sigm(float x) { return __builtin_amdgcn_rcpf(1.f + __builtin_amdgcn_exp2f(-x * LOG2E)); }
; DI f32x4 sigm4(f32x4 v) { f32x4 r; r.x = sigm(v.x); r.y = sigm(v.y); r.z = sigm(v.z); r.w = sigm(v.w); return r; }
;     template <int NAI> DI void run(AccRef acc, const Unit& u, int wr, int wc, int fr, int fq) const {
;     ...
; #pragma unroll
;                 for (int m = 0; m < 4; ++m) { const int row = EPI_ROW(ai, m); bf16_t* prow = gbase + ((unsigned)row * pitch + (unsigned)cl); const float rs = rsv[ai][m];
; #pragma unroll
;                     for (int bj = 0; bj < 2; ++bj) {
;                         f32x4 a = acc[ai][bj][m][0] * rs, b = acc[ai][bj][m][1] * rs;
;                         if (pn >= 12 && pn < 16) { a = a * sigm4(a); b = b * sigm4(b); }
;                         else if (pn >= 16 && pn < 20) { a = a * 0.125f; b = b * 0.125f; }
;                         else if (pn >= 21) { a = sigm4(a); b = sigm4(b); }
;                         st8(prow + bj * 128, a, b);
	v_rcp_f32_e32 v222, v222
	v_rcp_f32_e32 v223, v223
	v_rcp_f32_e32 v224, v224
	v_rcp_f32_e32 v225, v225
	v_rcp_f32_e32 v226, v226
	v_rcp_f32_e32 v227, v227
	v_rcp_f32_e32 v228, v228
	v_rcp_f32_e32 v229, v229
	v_cvt_pk_bf16_f32 v190, v222, v223
	v_cvt_pk_bf16_f32 v191, v224, v225
	v_cvt_pk_bf16_f32 v192, v226, v227
	v_cvt_pk_bf16_f32 v193, v228, v229
	global_store_dwordx4 v[184:185], v[190:193], off offset:256
	v_lshl_or_b32 v136, v158, s23, v210
	v_lshl_add_u64 v[182:183], v[136:137], 1, s[28:29]
	v_pk_mul_f32 v[60:61], v[60:61], v[164:165] op_sel_hi:[1,0]
	v_pk_mul_f32 v[62:63], v[62:63], v[164:165] op_sel_hi:[1,0]
	v_pk_mul_f32 v[56:57], v[56:57], v[164:165] op_sel_hi:[1,0]
	v_pk_mul_f32 v[58:59], v[58:59], v[164:165] op_sel_hi:[1,0]
	v_mul_f32_e32 v214, 0xbfb8aa3b, v60
	v_mul_f32_e32 v215, 0xbfb8aa3b, v61
	v_mul_f32_e32 v216, 0xbfb8aa3b, v62
	v_mul_f32_e32 v217, 0xbfb8aa3b, v63
	v_mul_f32_e32 v218, 0xbfb8aa3b, v56
	v_mul_f32_e32 v219, 0xbfb8aa3b, v57
	v_mul_f32_e32 v220, 0xbfb8aa3b, v58
	v_mul_f32_e32 v221, 0xbfb8aa3b, v59
	v_exp_f32_e32 v214, v214
	v_exp_f32_e32 v215, v215
	v_exp_f32_e32 v216, v216
	v_exp_f32_e32 v217, v217
	v_exp_f32_e32 v218, v218
	v_exp_f32_e32 v219, v219
	v_exp_f32_e32 v220, v220
	v_exp_f32_e32 v221, v221
	v_add_f32_e32 v214, 1.0, v214
	v_add_f32_e32 v215, 1.0, v215
	v_add_f32_e32 v216, 1.0, v216
	v_add_f32_e32 v217, 1.0, v217
	v_add_f32_e32 v218, 1.0, v218
	v_add_f32_e32 v219, 1.0, v219
	v_add_f32_e32 v220, 1.0, v220
	v_add_f32_e32 v221, 1.0, v221
	v_rcp_f32_e32 v214, v214
	v_rcp_f32_e32 v215, v215
	v_rcp_f32_e32 v216, v216
	v_rcp_f32_e32 v217, v217
	v_rcp_f32_e32 v218, v218
	v_rcp_f32_e32 v219, v219
	v_rcp_f32_e32 v220, v220
	v_rcp_f32_e32 v221, v221
	v_cvt_pk_bf16_f32 v186, v214, v215
	v_cvt_pk_bf16_f32 v187, v216, v217
	v_cvt_pk_bf16_f32 v188, v218, v219
	v_cvt_pk_bf16_f32 v189, v220, v221
	global_store_dwordx4 v[182:183], v[186:189], off
	v_pk_mul_f32 v[52:53], v[52:53], v[164:165] op_sel_hi:[1,0]
	v_pk_mul_f32 v[54:55], v[54:55], v[164:165] op_sel_hi:[1,0]
	v_pk_mul_f32 v[48:49], v[48:49], v[164:165] op_sel_hi:[1,0]
	v_pk_mul_f32 v[50:51], v[50:51], v[164:165] op_sel_hi:[1,0]
	v_mul_f32_e32 v222, 0xbfb8aa3b, v52
	v_mul_f32_e32 v223, 0xbfb8aa3b, v53
	v_mul_f32_e32 v224, 0xbfb8aa3b, v54
	v_mul_f32_e32 v225, 0xbfb8aa3b, v55
	v_mul_f32_e32 v226, 0xbfb8aa3b, v48
	v_mul_f32_e32 v227, 0xbfb8aa3b, v49
	v_mul_f32_e32 v228, 0xbfb8aa3b, v50
	v_mul_f32_e32 v229, 0xbfb8aa3b, v51
	v_exp_f32_e32 v222, v222
	v_exp_f32_e32 v223, v223
	v_exp_f32_e32 v224, v224
	v_exp_f32_e32 v225, v225
	v_exp_f32_e32 v226, v226
	v_exp_f32_e32 v227, v227
	v_exp_f32_e32 v228, v228
	v_exp_f32_e32 v229, v229
	v_add_f32_e32 v222, 1.0, v222
	v_add_f32_e32 v223, 1.0, v223
	v_add_f32_e32 v224, 1.0, v224
	v_add_f32_e32 v225, 1.0, v225
	v_add_f32_e32 v226, 1.0, v226
	v_add_f32_e32 v227, 1.0, v227
	v_add_f32_e32 v228, 1.0, v228
	v_add_f32_e32 v229, 1.0, v229
	v_rcp_f32_e32 v222, v222
	v_rcp_f32_e32 v223, v223
	v_rcp_f32_e32 v224, v224
	v_rcp_f32_e32 v225, v225
	v_rcp_f32_e32 v226, v226
	v_rcp_f32_e32 v227, v227
	v_rcp_f32_e32 v228, v228
	v_rcp_f32_e32 v229, v229
	v_cvt_pk_bf16_f32 v190, v222, v223
	v_cvt_pk_bf16_f32 v191, v224, v225
	v_cvt_pk_bf16_f32 v192, v226, v227
	v_cvt_pk_bf16_f32 v193, v228, v229
	global_store_dwordx4 v[182:183], v[190:193], off offset:256
	v_lshl_or_b32 v136, v160, s23, v210
	v_lshl_add_u64 v[184:185], v[136:137], 1, s[28:29]
	v_pk_mul_f32 v[44:45], v[44:45], v[162:163] op_sel_hi:[1,0]
	v_pk_mul_f32 v[46:47], v[46:47], v[162:163] op_sel_hi:[1,0]
	v_pk_mul_f32 v[40:41], v[40:41], v[162:163] op_sel_hi:[1,0]
	v_pk_mul_f32 v[42:43], v[42:43], v[162:163] op_sel_hi:[1,0]
	v_mul_f32_e32 v214, 0xbfb8aa3b, v44
	v_mul_f32_e32 v215, 0xbfb8aa3b, v45
	v_mul_f32_e32 v216, 0xbfb8aa3b, v46
	v_mul_f32_e32 v217, 0xbfb8aa3b, v47
	v_mul_f32_e32 v218, 0xbfb8aa3b, v40
	v_mul_f32_e32 v219, 0xbfb8aa3b, v41
	v_mul_f32_e32 v220, 0xbfb8aa3b, v42
	v_mul_f32_e32 v221, 0xbfb8aa3b, v43
	v_exp_f32_e32 v214, v214
	v_exp_f32_e32 v215, v215
	v_exp_f32_e32 v216, v216
	v_exp_f32_e32 v217, v217
	v_exp_f32_e32 v218, v218
	v_exp_f32_e32 v219, v219
	v_exp_f32_e32 v220, v220
	v_exp_f32_e32 v221, v221
	v_add_f32_e32 v214, 1.0, v214
	v_add_f32_e32 v215, 1.0, v215
	v_add_f32_e32 v216, 1.0, v216
	v_add_f32_e32 v217, 1.0, v217
	v_add_f32_e32 v218, 1.0, v218
	v_add_f32_e32 v219, 1.0, v219
	v_add_f32_e32 v220, 1.0, v220
	v_add_f32_e32 v221, 1.0, v221
	v_rcp_f32_e32 v214, v214
	v_rcp_f32_e32 v215, v215
	v_rcp_f32_e32 v216, v216
	v_rcp_f32_e32 v217, v217
	v_rcp_f32_e32 v218, v218
	v_rcp_f32_e32 v219, v219
	v_rcp_f32_e32 v220, v220
	v_rcp_f32_e32 v221, v221
	v_cvt_pk_bf16_f32 v186, v214, v215
	v_cvt_pk_bf16_f32 v187, v216, v217
	v_cvt_pk_bf16_f32 v188, v218, v219
	v_cvt_pk_bf16_f32 v189, v220, v221
	global_store_dwordx4 v[184:185], v[186:189], off
	v_pk_mul_f32 v[36:37], v[36:37], v[162:163] op_sel_hi:[1,0]
	v_pk_mul_f32 v[38:39], v[38:39], v[162:163] op_sel_hi:[1,0]
	v_pk_mul_f32 v[32:33], v[32:33], v[162:163] op_sel_hi:[1,0]
	v_pk_mul_f32 v[34:35], v[34:35], v[162:163] op_sel_hi:[1,0]
	v_mul_f32_e32 v222, 0xbfb8aa3b, v36
	v_mul_f32_e32 v223, 0xbfb8aa3b, v37
	v_mul_f32_e32 v224, 0xbfb8aa3b, v38
	v_mul_f32_e32 v225, 0xbfb8aa3b, v39
	v_mul_f32_e32 v226, 0xbfb8aa3b, v32
	v_mul_f32_e32 v227, 0xbfb8aa3b, v33
	v_mul_f32_e32 v228, 0xbfb8aa3b, v34
	v_mul_f32_e32 v229, 0xbfb8aa3b, v35
	v_exp_f32_e32 v222, v222
	v_exp_f32_e32 v223, v223
	v_exp_f32_e32 v224, v224
	v_exp_f32_e32 v225, v225
	v_exp_f32_e32 v226, v226
	v_exp_f32_e32 v227, v227
	v_exp_f32_e32 v228, v228
	v_exp_f32_e32 v229, v229
	v_add_f32_e32 v222, 1.0, v222
	v_add_f32_e32 v223, 1.0, v223
	v_add_f32_e32 v224, 1.0, v224
; DI void st8(bf16_t* p, f32x4 a, f32x4 b) { u32x4 w; w.x = cvt_pk_bf16(a.x, a.y); w.y = cvt_pk_bf16(a.z, a.w); w.z = cvt_pk_bf16(b.x, b.y); w.w = cvt_pk_bf16(b.z, b.w); *(u32x4*)p = w; }
; DI float sigm(float x) { return __builtin_amdgcn_rcpf(1.f + __builtin_amdgcn_exp2f(-x * LOG2E)); }
; DI f32x4 sigm4(f32x4 v) { f32x4 r; r.x = sigm(v.x); r.y = sigm(v.y); r.z = sigm(v.z); r.w = sigm(v.w); return r; }
;     template <int NAI> DI void run(AccRef acc, const Unit& u, int wr, int wc, int fr, int fq) const {
;     ...
; #pragma unroll
;                 for (int m = 0; m < 4; ++m) { const int row = EPI_ROW(ai, m); bf16_t* prow = gbase + ((unsigned)row * pitch + (unsigned)cl); const float rs = rsv[ai][m];
; #pragma unroll
;                     for (int bj = 0; bj < 2; ++bj) {
;                         f32x4 a = acc[ai][bj][m][0] * rs, b = acc[ai][bj][m][1] * rs;
;                         if (pn >= 12 && pn < 16) { a = a * sigm4(a); b = b * sigm4(b); }
;                         else if (pn >= 16 && pn < 20) { a = a * 0.125f; b = b * 0.125f; }
;                         else if (pn >= 21) { a = sigm4(a); b = sigm4(b); }
;                         st8(prow + bj * 128, a, b);
	v_add_f32_e32 v225, 1.0, v225
	v_add_f32_e32 v226, 1.0, v226
	v_add_f32_e32 v227, 1.0, v227
	v_add_f32_e32 v228, 1.0, v228
	v_add_f32_e32 v229, 1.0, v229
	v_rcp_f32_e32 v222, v222
	v_rcp_f32_e32 v223, v223
	v_rcp_f32_e32 v224, v224
	v_rcp_f32_e32 v225, v225
	v_rcp_f32_e32 v226, v226
	v_rcp_f32_e32 v227, v227
	v_rcp_f32_e32 v228, v228
	v_rcp_f32_e32 v229, v229
	v_cvt_pk_bf16_f32 v190, v222, v223
	v_cvt_pk_bf16_f32 v191, v224, v225
	v_cvt_pk_bf16_f32 v192, v226, v227
	v_cvt_pk_bf16_f32 v193, v228, v229
	global_store_dwordx4 v[184:185], v[190:193], off offset:256
	v_lshl_or_b32 v136, v154, s23, v210
	v_lshl_add_u64 v[182:183], v[136:137], 1, s[28:29]
	v_pk_mul_f32 v[28:29], v[28:29], v[156:157] op_sel_hi:[1,0]
	v_pk_mul_f32 v[30:31], v[30:31], v[156:157] op_sel_hi:[1,0]
	v_pk_mul_f32 v[24:25], v[24:25], v[156:157] op_sel_hi:[1,0]
	v_pk_mul_f32 v[26:27], v[26:27], v[156:157] op_sel_hi:[1,0]
	v_mul_f32_e32 v214, 0xbfb8aa3b, v28
	v_mul_f32_e32 v215, 0xbfb8aa3b, v29
	v_mul_f32_e32 v216, 0xbfb8aa3b, v30
	v_mul_f32_e32 v217, 0xbfb8aa3b, v31
	v_mul_f32_e32 v218, 0xbfb8aa3b, v24
	v_mul_f32_e32 v219, 0xbfb8aa3b, v25
	v_mul_f32_e32 v220, 0xbfb8aa3b, v26
	v_mul_f32_e32 v221, 0xbfb8aa3b, v27
	v_exp_f32_e32 v214, v214
	v_exp_f32_e32 v215, v215
	v_exp_f32_e32 v216, v216
	v_exp_f32_e32 v217, v217
	v_exp_f32_e32 v218, v218
	v_exp_f32_e32 v219, v219
	v_exp_f32_e32 v220, v220
	v_exp_f32_e32 v221, v221
	v_add_f32_e32 v214, 1.0, v214
	v_add_f32_e32 v215, 1.0, v215
	v_add_f32_e32 v216, 1.0, v216
	v_add_f32_e32 v217, 1.0, v217
	v_add_f32_e32 v218, 1.0, v218
	v_add_f32_e32 v219, 1.0, v219
	v_add_f32_e32 v220, 1.0, v220
	v_add_f32_e32 v221, 1.0, v221
	v_rcp_f32_e32 v214, v214
	v_rcp_f32_e32 v215, v215
	v_rcp_f32_e32 v216, v216
	v_rcp_f32_e32 v217, v217
	v_rcp_f32_e32 v218, v218
	v_rcp_f32_e32 v219, v219
	v_rcp_f32_e32 v220, v220
	v_rcp_f32_e32 v221, v221
	v_cvt_pk_bf16_f32 v186, v214, v215
	v_cvt_pk_bf16_f32 v187, v216, v217
	v_cvt_pk_bf16_f32 v188, v218, v219
	v_cvt_pk_bf16_f32 v189, v220, v221
	global_store_dwordx4 v[182:183], v[186:189], off
	v_pk_mul_f32 v[20:21], v[20:21], v[156:157] op_sel_hi:[1,0]
	v_pk_mul_f32 v[22:23], v[22:23], v[156:157] op_sel_hi:[1,0]
	v_pk_mul_f32 v[16:17], v[16:17], v[156:157] op_sel_hi:[1,0]
	v_pk_mul_f32 v[18:19], v[18:19], v[156:157] op_sel_hi:[1,0]
	v_mul_f32_e32 v222, 0xbfb8aa3b, v20
	v_mul_f32_e32 v223, 0xbfb8aa3b, v21
	v_mul_f32_e32 v224, 0xbfb8aa3b, v22
	v_mul_f32_e32 v225, 0xbfb8aa3b, v23
	v_mul_f32_e32 v226, 0xbfb8aa3b, v16
	v_mul_f32_e32 v227, 0xbfb8aa3b, v17
	v_mul_f32_e32 v228, 0xbfb8aa3b, v18
	v_mul_f32_e32 v229, 0xbfb8aa3b, v19
	v_exp_f32_e32 v222, v222
	v_exp_f32_e32 v223, v223
	v_exp_f32_e32 v224, v224
	v_exp_f32_e32 v225, v225
	v_exp_f32_e32 v226, v226
	v_exp_f32_e32 v227, v227
	v_exp_f32_e32 v228, v228
	v_exp_f32_e32 v229, v229
	v_add_f32_e32 v222, 1.0, v222
	v_add_f32_e32 v223, 1.0, v223
	v_add_f32_e32 v224, 1.0, v224
	v_add_f32_e32 v225, 1.0, v225
	v_add_f32_e32 v226, 1.0, v226
	v_add_f32_e32 v227, 1.0, v227
	v_add_f32_e32 v228, 1.0, v228
	v_add_f32_e32 v229, 1.0, v229
	v_rcp_f32_e32 v222, v222
	v_rcp_f32_e32 v223, v223
	v_rcp_f32_e32 v224, v224
	v_rcp_f32_e32 v225, v225
	v_rcp_f32_e32 v226, v226
	v_rcp_f32_e32 v227, v227
	v_rcp_f32_e32 v228, v228
	v_rcp_f32_e32 v229, v229
	v_cvt_pk_bf16_f32 v190, v222, v223
	v_cvt_pk_bf16_f32 v191, v224, v225
	v_cvt_pk_bf16_f32 v192, v226, v227
	v_cvt_pk_bf16_f32 v193, v228, v229
	global_store_dwordx4 v[182:183], v[190:193], off offset:256
	v_lshl_or_b32 v136, v148, s23, v210
	v_lshl_add_u64 v[184:185], v[136:137], 1, s[28:29]
	v_pk_mul_f32 v[12:13], v[12:13], v[150:151] op_sel_hi:[1,0]
	v_pk_mul_f32 v[14:15], v[14:15], v[150:151] op_sel_hi:[1,0]
	v_pk_mul_f32 v[8:9], v[8:9], v[150:151] op_sel_hi:[1,0]
	v_pk_mul_f32 v[10:11], v[10:11], v[150:151] op_sel_hi:[1,0]
	v_mul_f32_e32 v214, 0xbfb8aa3b, v12
	v_mul_f32_e32 v215, 0xbfb8aa3b, v13
	v_mul_f32_e32 v216, 0xbfb8aa3b, v14
	v_mul_f32_e32 v217, 0xbfb8aa3b, v15
	v_mul_f32_e32 v218, 0xbfb8aa3b, v8
	v_mul_f32_e32 v219, 0xbfb8aa3b, v9
	v_mul_f32_e32 v220, 0xbfb8aa3b, v10
	v_mul_f32_e32 v221, 0xbfb8aa3b, v11
	v_exp_f32_e32 v214, v214
	v_exp_f32_e32 v215, v215
	v_exp_f32_e32 v216, v216
	v_exp_f32_e32 v217, v217
	v_exp_f32_e32 v218, v218
	v_exp_f32_e32 v219, v219
	v_exp_f32_e32 v220, v220
	v_exp_f32_e32 v221, v221
	v_add_f32_e32 v214, 1.0, v214
	v_add_f32_e32 v215, 1.0, v215
	v_add_f32_e32 v216, 1.0, v216
	v_add_f32_e32 v217, 1.0, v217
	v_add_f32_e32 v218, 1.0, v218
	v_add_f32_e32 v219, 1.0, v219
	v_add_f32_e32 v220, 1.0, v220
	v_add_f32_e32 v221, 1.0, v221
	v_rcp_f32_e32 v214, v214
	v_rcp_f32_e32 v215, v215
	v_rcp_f32_e32 v216, v216
	v_rcp_f32_e32 v217, v217
	v_rcp_f32_e32 v218, v218
	v_rcp_f32_e32 v219, v219
	v_rcp_f32_e32 v220, v220
	v_rcp_f32_e32 v221, v221
	v_cvt_pk_bf16_f32 v186, v214, v215
	v_cvt_pk_bf16_f32 v187, v216, v217
	v_cvt_pk_bf16_f32 v188, v218, v219
	v_cvt_pk_bf16_f32 v189, v220, v221
	global_store_dwordx4 v[184:185], v[186:189], off
	v_pk_mul_f32 v[4:5], v[4:5], v[150:151] op_sel_hi:[1,0]
	v_pk_mul_f32 v[6:7], v[6:7], v[150:151] op_sel_hi:[1,0]
	v_pk_mul_f32 v[0:1], v[0:1], v[150:151] op_sel_hi:[1,0]
	v_pk_mul_f32 v[2:3], v[2:3], v[150:151] op_sel_hi:[1,0]
	v_mul_f32_e32 v222, 0xbfb8aa3b, v4
	v_mul_f32_e32 v223, 0xbfb8aa3b, v5
	v_mul_f32_e32 v224, 0xbfb8aa3b, v6
	v_mul_f32_e32 v225, 0xbfb8aa3b, v7
	v_mul_f32_e32 v226, 0xbfb8aa3b, v0
	v_mul_f32_e32 v227, 0xbfb8aa3b, v1
	v_mul_f32_e32 v228, 0xbfb8aa3b, v2
	v_mul_f32_e32 v229, 0xbfb8aa3b, v3
	v_exp_f32_e32 v222, v222
	v_exp_f32_e32 v223, v223
	v_exp_f32_e32 v224, v224
	v_exp_f32_e32 v225, v225
	v_exp_f32_e32 v226, v226
	v_exp_f32_e32 v227, v227
	v_exp_f32_e32 v228, v228
	v_exp_f32_e32 v229, v229
	v_add_f32_e32 v222, 1.0, v222
	v_add_f32_e32 v223, 1.0, v223
	v_add_f32_e32 v224, 1.0, v224
	v_add_f32_e32 v225, 1.0, v225
	v_add_f32_e32 v226, 1.0, v226
	v_add_f32_e32 v227, 1.0, v227
	v_add_f32_e32 v228, 1.0, v228
	v_add_f32_e32 v229, 1.0, v229
	v_rcp_f32_e32 v222, v222
	v_rcp_f32_e32 v223, v223
	v_rcp_f32_e32 v224, v224
	v_rcp_f32_e32 v225, v225
	v_rcp_f32_e32 v226, v226
	v_rcp_f32_e32 v227, v227
	v_rcp_f32_e32 v228, v228
	v_rcp_f32_e32 v229, v229
	v_cvt_pk_bf16_f32 v190, v222, v223
	v_cvt_pk_bf16_f32 v191, v224, v225
	v_cvt_pk_bf16_f32 v192, v226, v227
	v_cvt_pk_bf16_f32 v193, v228, v229
	global_store_dwordx4 v[184:185], v[190:193], off offset:256
	s_branch .LBB0_275
; DI void st8(bf16_t* p, f32x4 a, f32x4 b) { u32x4 w; w.x = cvt_pk_bf16(a.x, a.y); w.y = cvt_pk_bf16(a.z, a.w); w.z = cvt_pk_bf16(b.x, b.y); w.w = cvt_pk_bf16(b.z, b.w); *(u32x4*)p = w; }
; DI float sigm(float x) { return __builtin_amdgcn_rcpf(1.f + __builtin_amdgcn_exp2f(-x * LOG2E)); }
; DI f32x4 sigm4(f32x4 v) { f32x4 r; r.x = sigm(v.x); r.y = sigm(v.y); r.z = sigm(v.z); r.w = sigm(v.w); return r; }
;     template <int NAI> DI void run(AccRef acc, const Unit& u, int wr, int wc, int fr, int fq) const {
;     ...
; #pragma unroll
;                 for (int m = 0; m < 4; ++m) { const int row = EPI_ROW(ai, m); bf16_t* prow = gbase + ((unsigned)row * pitch + (unsigned)cl); const float rs = rsv[ai][m];
; #pragma unroll
;                     for (int bj = 0; bj < 2; ++bj) {
;                         f32x4 a = acc[ai][bj][m][0] * rs, b = acc[ai][bj][m][1] * rs;
;                         if (pn >= 12 && pn < 16) { a = a * sigm4(a); b = b * sigm4(b); }
;                         else if (pn >= 16 && pn < 20) { a = a * 0.125f; b = b * 0.125f; }
;                         else if (pn >= 21) { a = sigm4(a); b = sigm4(b); }
;                         st8(prow + bj * 128, a, b);
.Lipe_silu:
	v_lshl_or_b32 v136, v174, s23, v210
	v_lshl_add_u64 v[182:183], v[136:137], 1, s[28:29]
	v_pk_mul_f32 v[124:125], v[124:125], v[180:181] op_sel_hi:[1,0]
	v_pk_mul_f32 v[126:127], v[126:127], v[180:181] op_sel_hi:[1,0]
	v_pk_mul_f32 v[120:121], v[120:121], v[180:181] op_sel_hi:[1,0]
	v_pk_mul_f32 v[122:123], v[122:123], v[180:181] op_sel_hi:[1,0]
	v_mul_f32_e32 v214, 0xbfb8aa3b, v124
	v_mul_f32_e32 v215, 0xbfb8aa3b, v125
	v_mul_f32_e32 v216, 0xbfb8aa3b, v126
	v_mul_f32_e32 v217, 0xbfb8aa3b, v127
	v_mul_f32_e32 v218, 0xbfb8aa3b, v120
	v_mul_f32_e32 v219, 0xbfb8aa3b, v121
	v_mul_f32_e32 v220, 0xbfb8aa3b, v122
	v_mul_f32_e32 v221, 0xbfb8aa3b, v123
	v_exp_f32_e32 v214, v214
	v_exp_f32_e32 v215, v215
	v_exp_f32_e32 v216, v216
	v_exp_f32_e32 v217, v217
	v_exp_f32_e32 v218, v218
	v_exp_f32_e32 v219, v219
	v_exp_f32_e32 v220, v220
	v_exp_f32_e32 v221, v221
	v_add_f32_e32 v214, 1.0, v214
	v_add_f32_e32 v215, 1.0, v215
	v_add_f32_e32 v216, 1.0, v216
	v_add_f32_e32 v217, 1.0, v217
	v_add_f32_e32 v218, 1.0, v218
	v_add_f32_e32 v219, 1.0, v219
	v_add_f32_e32 v220, 1.0, v220
	v_add_f32_e32 v221, 1.0, v221
	v_rcp_f32_e32 v214, v214
	v_rcp_f32_e32 v215, v215
	v_rcp_f32_e32 v216, v216
	v_rcp_f32_e32 v217, v217
	v_rcp_f32_e32 v218, v218
	v_rcp_f32_e32 v219, v219
	v_rcp_f32_e32 v220, v220
	v_rcp_f32_e32 v221, v221
	v_pk_mul_f32 v[214:215], v[124:125], v[214:215]
	v_pk_mul_f32 v[216:217], v[126:127], v[216:217]
	v_pk_mul_f32 v[218:219], v[120:121], v[218:219]
	v_pk_mul_f32 v[220:221], v[122:123], v[220:221]
	v_cvt_pk_bf16_f32 v186, v214, v215
	v_cvt_pk_bf16_f32 v187, v216, v217
	v_cvt_pk_bf16_f32 v188, v218, v219
	v_cvt_pk_bf16_f32 v189, v220, v221
	global_store_dwordx4 v[182:183], v[186:189], off
	v_pk_mul_f32 v[116:117], v[116:117], v[180:181] op_sel_hi:[1,0]
	v_pk_mul_f32 v[118:119], v[118:119], v[180:181] op_sel_hi:[1,0]
	v_pk_mul_f32 v[112:113], v[112:113], v[180:181] op_sel_hi:[1,0]
	v_pk_mul_f32 v[114:115], v[114:115], v[180:181] op_sel_hi:[1,0]
	v_mul_f32_e32 v222, 0xbfb8aa3b, v116
	v_mul_f32_e32 v223, 0xbfb8aa3b, v117
	v_mul_f32_e32 v224, 0xbfb8aa3b, v118
	v_mul_f32_e32 v225, 0xbfb8aa3b, v119
	v_mul_f32_e32 v226, 0xbfb8aa3b, v112
	v_mul_f32_e32 v227, 0xbfb8aa3b, v113
	v_mul_f32_e32 v228, 0xbfb8aa3b, v114
	v_mul_f32_e32 v229, 0xbfb8aa3b, v115
	v_exp_f32_e32 v222, v222
	v_exp_f32_e32 v223, v223
	v_exp_f32_e32 v224, v224
	v_exp_f32_e32 v225, v225
	v_exp_f32_e32 v226, v226
	v_exp_f32_e32 v227, v227
	v_exp_f32_e32 v228, v228
	v_exp_f32_e32 v229, v229
	v_add_f32_e32 v222, 1.0, v222
	v_add_f32_e32 v223, 1.0, v223
	v_add_f32_e32 v224, 1.0, v224
	v_add_f32_e32 v225, 1.0, v225
	v_add_f32_e32 v226, 1.0, v226
	v_add_f32_e32 v227, 1.0, v227
	v_add_f32_e32 v228, 1.0, v228
	v_add_f32_e32 v229, 1.0, v229
	v_rcp_f32_e32 v222, v222
	v_rcp_f32_e32 v223, v223
	v_rcp_f32_e32 v224, v224
	v_rcp_f32_e32 v225, v225
	v_rcp_f32_e32 v226, v226
	v_rcp_f32_e32 v227, v227
	v_rcp_f32_e32 v228, v228
	v_rcp_f32_e32 v229, v229
	v_pk_mul_f32 v[222:223], v[116:117], v[222:223]
	v_pk_mul_f32 v[224:225], v[118:119], v[224:225]
	v_pk_mul_f32 v[226:227], v[112:113], v[226:227]
	v_pk_mul_f32 v[228:229], v[114:115], v[228:229]
	v_cvt_pk_bf16_f32 v190, v222, v223
	v_cvt_pk_bf16_f32 v191, v224, v225
	v_cvt_pk_bf16_f32 v192, v226, v227
	v_cvt_pk_bf16_f32 v193, v228, v229
	global_store_dwordx4 v[182:183], v[190:193], off offset:256
	v_lshl_or_b32 v136, v176, s23, v210
	v_lshl_add_u64 v[184:185], v[136:137], 1, s[28:29]
	v_pk_mul_f32 v[108:109], v[108:109], v[178:179] op_sel_hi:[1,0]
	v_pk_mul_f32 v[110:111], v[110:111], v[178:179] op_sel_hi:[1,0]
	v_pk_mul_f32 v[104:105], v[104:105], v[178:179] op_sel_hi:[1,0]
	v_pk_mul_f32 v[106:107], v[106:107], v[178:179] op_sel_hi:[1,0]
	v_mul_f32_e32 v214, 0xbfb8aa3b, v108
	v_mul_f32_e32 v215, 0xbfb8aa3b, v109
	v_mul_f32_e32 v216, 0xbfb8aa3b, v110
	v_mul_f32_e32 v217, 0xbfb8aa3b, v111
	v_mul_f32_e32 v218, 0xbfb8aa3b, v104
	v_mul_f32_e32 v219, 0xbfb8aa3b, v105
	v_mul_f32_e32 v220, 0xbfb8aa3b, v106
	v_mul_f32_e32 v221, 0xbfb8aa3b, v107
	v_exp_f32_e32 v214, v214
	v_exp_f32_e32 v215, v215
	v_exp_f32_e32 v216, v216
	v_exp_f32_e32 v217, v217
	v_exp_f32_e32 v218, v218
	v_exp_f32_e32 v219, v219
	v_exp_f32_e32 v220, v220
	v_exp_f32_e32 v221, v221
	v_add_f32_e32 v214, 1.0, v214
	v_add_f32_e32 v215, 1.0, v215
	v_add_f32_e32 v216, 1.0, v216
	v_add_f32_e32 v217, 1.0, v217
	v_add_f32_e32 v218, 1.0, v218
	v_add_f32_e32 v219, 1.0, v219
	v_add_f32_e32 v220, 1.0, v220
	v_add_f32_e32 v221, 1.0, v221
	v_rcp_f32_e32 v214, v214
	v_rcp_f32_e32 v215, v215
	v_rcp_f32_e32 v216, v216
	v_rcp_f32_e32 v217, v217
	v_rcp_f32_e32 v218, v218
	v_rcp_f32_e32 v219, v219
	v_rcp_f32_e32 v220, v220
	v_rcp_f32_e32 v221, v221
	v_pk_mul_f32 v[214:215], v[108:109], v[214:215]
	v_pk_mul_f32 v[216:217], v[110:111], v[216:217]
	v_pk_mul_f32 v[218:219], v[104:105], v[218:219]
	v_pk_mul_f32 v[220:221], v[106:107], v[220:221]
	v_cvt_pk_bf16_f32 v186, v214, v215
	v_cvt_pk_bf16_f32 v187, v216, v217
	v_cvt_pk_bf16_f32 v188, v218, v219
	v_cvt_pk_bf16_f32 v189, v220, v221
	global_store_dwordx4 v[184:185], v[186:189], off
	v_pk_mul_f32 v[100:101], v[100:101], v[178:179] op_sel_hi:[1,0]
	v_pk_mul_f32 v[102:103], v[102:103], v[178:179] op_sel_hi:[1,0]
	v_pk_mul_f32 v[96:97], v[96:97], v[178:179] op_sel_hi:[1,0]
	v_pk_mul_f32 v[98:99], v[98:99], v[178:179] op_sel_hi:[1,0]
	v_mul_f32_e32 v222, 0xbfb8aa3b, v100
	v_mul_f32_e32 v223, 0xbfb8aa3b, v101
	v_mul_f32_e32 v224, 0xbfb8aa3b, v102
	v_mul_f32_e32 v225, 0xbfb8aa3b, v103
	v_mul_f32_e32 v226, 0xbfb8aa3b, v96
	v_mul_f32_e32 v227, 0xbfb8aa3b, v97
	v_mul_f32_e32 v228, 0xbfb8aa3b, v98
	v_mul_f32_e32 v229, 0xbfb8aa3b, v99
	v_exp_f32_e32 v222, v222
; DI void st8(bf16_t* p, f32x4 a, f32x4 b) { u32x4 w; w.x = cvt_pk_bf16(a.x, a.y); w.y = cvt_pk_bf16(a.z, a.w); w.z = cvt_pk_bf16(b.x, b.y); w.w = cvt_pk_bf16(b.z, b.w); *(u32x4*)p = w; }
; DI float sigm(float x) { return __builtin_amdgcn_rcpf(1.f + __builtin_amdgcn_exp2f(-x * LOG2E)); }
; DI f32x4 sigm4(f32x4 v) { f32x4 r; r.x = sigm(v.x); r.y = sigm(v.y); r.z = sigm(v.z); r.w = sigm(v.w); return r; }
;     template <int NAI> DI void run(AccRef acc, const Unit& u, int wr, int wc, int fr, int fq) const {
;     ...
; #pragma unroll
;                 for (int m = 0; m < 4; ++m) { const int row = EPI_ROW(ai, m); bf16_t* prow = gbase + ((unsigned)row * pitch + (unsigned)cl); const float rs = rsv[ai][m];
; #pragma unroll
;                     for (int bj = 0; bj < 2; ++bj) {
;                         f32x4 a = acc[ai][bj][m][0] * rs, b = acc[ai][bj][m][1] * rs;
;                         if (pn >= 12 && pn < 16) { a = a * sigm4(a); b = b * sigm4(b); }
;                         else if (pn >= 16 && pn < 20) { a = a * 0.125f; b = b * 0.125f; }
;                         else if (pn >= 21) { a = sigm4(a); b = sigm4(b); }
;                         st8(prow + bj * 128, a, b);
	v_exp_f32_e32 v223, v223
	v_exp_f32_e32 v224, v224
	v_exp_f32_e32 v225, v225
	v_exp_f32_e32 v226, v226
	v_exp_f32_e32 v227, v227
	v_exp_f32_e32 v228, v228
	v_exp_f32_e32 v229, v229
	v_add_f32_e32 v222, 1.0, v222
	v_add_f32_e32 v223, 1.0, v223
	v_add_f32_e32 v224, 1.0, v224
	v_add_f32_e32 v225, 1.0, v225
	v_add_f32_e32 v226, 1.0, v226
	v_add_f32_e32 v227, 1.0, v227
	v_add_f32_e32 v228, 1.0, v228
	v_add_f32_e32 v229, 1.0, v229
	v_rcp_f32_e32 v222, v222
	v_rcp_f32_e32 v223, v223
	v_rcp_f32_e32 v224, v224
	v_rcp_f32_e32 v225, v225
	v_rcp_f32_e32 v226, v226
	v_rcp_f32_e32 v227, v227
	v_rcp_f32_e32 v228, v228
	v_rcp_f32_e32 v229, v229
	v_pk_mul_f32 v[222:223], v[100:101], v[222:223]
	v_pk_mul_f32 v[224:225], v[102:103], v[224:225]
	v_pk_mul_f32 v[226:227], v[96:97], v[226:227]
	v_pk_mul_f32 v[228:229], v[98:99], v[228:229]
	v_cvt_pk_bf16_f32 v190, v222, v223
	v_cvt_pk_bf16_f32 v191, v224, v225
	v_cvt_pk_bf16_f32 v192, v226, v227
	v_cvt_pk_bf16_f32 v193, v228, v229
	global_store_dwordx4 v[184:185], v[190:193], off offset:256
	v_lshl_or_b32 v136, v170, s23, v210
	v_lshl_add_u64 v[182:183], v[136:137], 1, s[28:29]
	v_pk_mul_f32 v[92:93], v[92:93], v[172:173] op_sel_hi:[1,0]
	v_pk_mul_f32 v[94:95], v[94:95], v[172:173] op_sel_hi:[1,0]
	v_pk_mul_f32 v[88:89], v[88:89], v[172:173] op_sel_hi:[1,0]
	v_pk_mul_f32 v[90:91], v[90:91], v[172:173] op_sel_hi:[1,0]
	v_mul_f32_e32 v214, 0xbfb8aa3b, v92
	v_mul_f32_e32 v215, 0xbfb8aa3b, v93
	v_mul_f32_e32 v216, 0xbfb8aa3b, v94
	v_mul_f32_e32 v217, 0xbfb8aa3b, v95
	v_mul_f32_e32 v218, 0xbfb8aa3b, v88
	v_mul_f32_e32 v219, 0xbfb8aa3b, v89
	v_mul_f32_e32 v220, 0xbfb8aa3b, v90
	v_mul_f32_e32 v221, 0xbfb8aa3b, v91
	v_exp_f32_e32 v214, v214
	v_exp_f32_e32 v215, v215
	v_exp_f32_e32 v216, v216
	v_exp_f32_e32 v217, v217
	v_exp_f32_e32 v218, v218
	v_exp_f32_e32 v219, v219
	v_exp_f32_e32 v220, v220
	v_exp_f32_e32 v221, v221
	v_add_f32_e32 v214, 1.0, v214
	v_add_f32_e32 v215, 1.0, v215
	v_add_f32_e32 v216, 1.0, v216
	v_add_f32_e32 v217, 1.0, v217
	v_add_f32_e32 v218, 1.0, v218
	v_add_f32_e32 v219, 1.0, v219
	v_add_f32_e32 v220, 1.0, v220
	v_add_f32_e32 v221, 1.0, v221
	v_rcp_f32_e32 v214, v214
	v_rcp_f32_e32 v215, v215
	v_rcp_f32_e32 v216, v216
	v_rcp_f32_e32 v217, v217
	v_rcp_f32_e32 v218, v218
	v_rcp_f32_e32 v219, v219
	v_rcp_f32_e32 v220, v220
	v_rcp_f32_e32 v221, v221
	v_pk_mul_f32 v[214:215], v[92:93], v[214:215]
	v_pk_mul_f32 v[216:217], v[94:95], v[216:217]
	v_pk_mul_f32 v[218:219], v[88:89], v[218:219]
	v_pk_mul_f32 v[220:221], v[90:91], v[220:221]
	v_cvt_pk_bf16_f32 v186, v214, v215
	v_cvt_pk_bf16_f32 v187, v216, v217
	v_cvt_pk_bf16_f32 v188, v218, v219
	v_cvt_pk_bf16_f32 v189, v220, v221
	global_store_dwordx4 v[182:183], v[186:189], off
	v_pk_mul_f32 v[84:85], v[84:85], v[172:173] op_sel_hi:[1,0]
	v_pk_mul_f32 v[86:87], v[86:87], v[172:173] op_sel_hi:[1,0]
	v_pk_mul_f32 v[80:81], v[80:81], v[172:173] op_sel_hi:[1,0]
	v_pk_mul_f32 v[82:83], v[82:83], v[172:173] op_sel_hi:[1,0]
	v_mul_f32_e32 v222, 0xbfb8aa3b, v84
	v_mul_f32_e32 v223, 0xbfb8aa3b, v85
	v_mul_f32_e32 v224, 0xbfb8aa3b, v86
	v_mul_f32_e32 v225, 0xbfb8aa3b, v87
	v_mul_f32_e32 v226, 0xbfb8aa3b, v80
	v_mul_f32_e32 v227, 0xbfb8aa3b, v81
	v_mul_f32_e32 v228, 0xbfb8aa3b, v82
	v_mul_f32_e32 v229, 0xbfb8aa3b, v83
	v_exp_f32_e32 v222, v222
	v_exp_f32_e32 v223, v223
	v_exp_f32_e32 v224, v224
	v_exp_f32_e32 v225, v225
	v_exp_f32_e32 v226, v226
	v_exp_f32_e32 v227, v227
	v_exp_f32_e32 v228, v228
	v_exp_f32_e32 v229, v229
	v_add_f32_e32 v222, 1.0, v222
	v_add_f32_e32 v223, 1.0, v223
	v_add_f32_e32 v224, 1.0, v224
	v_add_f32_e32 v225, 1.0, v225
	v_add_f32_e32 v226, 1.0, v226
	v_add_f32_e32 v227, 1.0, v227
	v_add_f32_e32 v228, 1.0, v228
	v_add_f32_e32 v229, 1.0, v229
	v_rcp_f32_e32 v222, v222
	v_rcp_f32_e32 v223, v223
	v_rcp_f32_e32 v224, v224
	v_rcp_f32_e32 v225, v225
	v_rcp_f32_e32 v226, v226
	v_rcp_f32_e32 v227, v227
	v_rcp_f32_e32 v228, v228
	v_rcp_f32_e32 v229, v229
	v_pk_mul_f32 v[222:223], v[84:85], v[222:223]
	v_pk_mul_f32 v[224:225], v[86:87], v[224:225]
	v_pk_mul_f32 v[226:227], v[80:81], v[226:227]
	v_pk_mul_f32 v[228:229], v[82:83], v[228:229]
	v_cvt_pk_bf16_f32 v190, v222, v223
	v_cvt_pk_bf16_f32 v191, v224, v225
	v_cvt_pk_bf16_f32 v192, v226, v227
	v_cvt_pk_bf16_f32 v193, v228, v229
	global_store_dwordx4 v[182:183], v[190:193], off offset:256
	v_lshl_or_b32 v136, v166, s23, v210
	v_lshl_add_u64 v[184:185], v[136:137], 1, s[28:29]
	v_pk_mul_f32 v[76:77], v[76:77], v[168:169] op_sel_hi:[1,0]
	v_pk_mul_f32 v[78:79], v[78:79], v[168:169] op_sel_hi:[1,0]
	v_pk_mul_f32 v[72:73], v[72:73], v[168:169] op_sel_hi:[1,0]
	v_pk_mul_f32 v[74:75], v[74:75], v[168:169] op_sel_hi:[1,0]
	v_mul_f32_e32 v214, 0xbfb8aa3b, v76
	v_mul_f32_e32 v215, 0xbfb8aa3b, v77
	v_mul_f32_e32 v216, 0xbfb8aa3b, v78
	v_mul_f32_e32 v217, 0xbfb8aa3b, v79
	v_mul_f32_e32 v218, 0xbfb8aa3b, v72
	v_mul_f32_e32 v219, 0xbfb8aa3b, v73
	v_mul_f32_e32 v220, 0xbfb8aa3b, v74
	v_mul_f32_e32 v221, 0xbfb8aa3b, v75
	v_exp_f32_e32 v214, v214
	v_exp_f32_e32 v215, v215
	v_exp_f32_e32 v216, v216
	v_exp_f32_e32 v217, v217
	v_exp_f32_e32 v218, v218
	v_exp_f32_e32 v219, v219
	v_exp_f32_e32 v220, v220
	v_exp_f32_e32 v221, v221
	v_add_f32_e32 v214, 1.0, v214
	v_add_f32_e32 v215, 1.0, v215
	v_add_f32_e32 v216, 1.0, v216
	v_add_f32_e32 v217, 1.0, v217
	v_add_f32_e32 v218, 1.0, v218
	v_add_f32_e32 v219, 1.0, v219
	v_add_f32_e32 v220, 1.0, v220
	v_add_f32_e32 v221, 1.0, v221
	v_rcp_f32_e32 v214, v214
	v_rcp_f32_e32 v215, v215
	v_rcp_f32_e32 v216, v216
	v_rcp_f32_e32 v217, v217
	v_rcp_f32_e32 v218, v218
	v_rcp_f32_e32 v219, v219
	v_rcp_f32_e32 v220, v220
	v_rcp_f32_e32 v221, v221
	v_pk_mul_f32 v[214:215], v[76:77], v[214:215]
; DI void st8(bf16_t* p, f32x4 a, f32x4 b) { u32x4 w; w.x = cvt_pk_bf16(a.x, a.y); w.y = cvt_pk_bf16(a.z, a.w); w.z = cvt_pk_bf16(b.x, b.y); w.w = cvt_pk_bf16(b.z, b.w); *(u32x4*)p = w; }
; DI float sigm(float x) { return __builtin_amdgcn_rcpf(1.f + __builtin_amdgcn_exp2f(-x * LOG2E)); }
; DI f32x4 sigm4(f32x4 v) { f32x4 r; r.x = sigm(v.x); r.y = sigm(v.y); r.z = sigm(v.z); r.w = sigm(v.w); return r; }
;     template <int NAI> DI void run(AccRef acc, const Unit& u, int wr, int wc, int fr, int fq) const {
;     ...
; #pragma unroll
;                 for (int m = 0; m < 4; ++m) { const int row = EPI_ROW(ai, m); bf16_t* prow = gbase + ((unsigned)row * pitch + (unsigned)cl); const float rs = rsv[ai][m];
; #pragma unroll
;                     for (int bj = 0; bj < 2; ++bj) {
;                         f32x4 a = acc[ai][bj][m][0] * rs, b = acc[ai][bj][m][1] * rs;
;                         if (pn >= 12 && pn < 16) { a = a * sigm4(a); b = b * sigm4(b); }
;                         else if (pn >= 16 && pn < 20) { a = a * 0.125f; b = b * 0.125f; }
;                         else if (pn >= 21) { a = sigm4(a); b = sigm4(b); }
;                         st8(prow + bj * 128, a, b);
	v_pk_mul_f32 v[216:217], v[78:79], v[216:217]
	v_pk_mul_f32 v[218:219], v[72:73], v[218:219]
	v_pk_mul_f32 v[220:221], v[74:75], v[220:221]
	v_cvt_pk_bf16_f32 v186, v214, v215
	v_cvt_pk_bf16_f32 v187, v216, v217
	v_cvt_pk_bf16_f32 v188, v218, v219
	v_cvt_pk_bf16_f32 v189, v220, v221
	global_store_dwordx4 v[184:185], v[186:189], off
	v_pk_mul_f32 v[68:69], v[68:69], v[168:169] op_sel_hi:[1,0]
	v_pk_mul_f32 v[70:71], v[70:71], v[168:169] op_sel_hi:[1,0]
	v_pk_mul_f32 v[64:65], v[64:65], v[168:169] op_sel_hi:[1,0]
	v_pk_mul_f32 v[66:67], v[66:67], v[168:169] op_sel_hi:[1,0]
	v_mul_f32_e32 v222, 0xbfb8aa3b, v68
	v_mul_f32_e32 v223, 0xbfb8aa3b, v69
	v_mul_f32_e32 v224, 0xbfb8aa3b, v70
	v_mul_f32_e32 v225, 0xbfb8aa3b, v71
	v_mul_f32_e32 v226, 0xbfb8aa3b, v64
	v_mul_f32_e32 v227, 0xbfb8aa3b, v65
	v_mul_f32_e32 v228, 0xbfb8aa3b, v66
	v_mul_f32_e32 v229, 0xbfb8aa3b, v67
	v_exp_f32_e32 v222, v222
	v_exp_f32_e32 v223, v223
	v_exp_f32_e32 v224, v224
	v_exp_f32_e32 v225, v225
	v_exp_f32_e32 v226, v226
	v_exp_f32_e32 v227, v227
	v_exp_f32_e32 v228, v228
	v_exp_f32_e32 v229, v229
	v_add_f32_e32 v222, 1.0, v222
	v_add_f32_e32 v223, 1.0, v223
	v_add_f32_e32 v224, 1.0, v224
	v_add_f32_e32 v225, 1.0, v225
	v_add_f32_e32 v226, 1.0, v226
	v_add_f32_e32 v227, 1.0, v227
	v_add_f32_e32 v228, 1.0, v228
	v_add_f32_e32 v229, 1.0, v229
	v_rcp_f32_e32 v222, v222
	v_rcp_f32_e32 v223, v223
	v_rcp_f32_e32 v224, v224
	v_rcp_f32_e32 v225, v225
	v_rcp_f32_e32 v226, v226
	v_rcp_f32_e32 v227, v227
	v_rcp_f32_e32 v228, v228
	v_rcp_f32_e32 v229, v229
	v_pk_mul_f32 v[222:223], v[68:69], v[222:223]
	v_pk_mul_f32 v[224:225], v[70:71], v[224:225]
	v_pk_mul_f32 v[226:227], v[64:65], v[226:227]
	v_pk_mul_f32 v[228:229], v[66:67], v[228:229]
	v_cvt_pk_bf16_f32 v190, v222, v223
	v_cvt_pk_bf16_f32 v191, v224, v225
	v_cvt_pk_bf16_f32 v192, v226, v227
	v_cvt_pk_bf16_f32 v193, v228, v229
	global_store_dwordx4 v[184:185], v[190:193], off offset:256
	v_lshl_or_b32 v136, v158, s23, v210
	v_lshl_add_u64 v[182:183], v[136:137], 1, s[28:29]
	v_pk_mul_f32 v[60:61], v[60:61], v[164:165] op_sel_hi:[1,0]
	v_pk_mul_f32 v[62:63], v[62:63], v[164:165] op_sel_hi:[1,0]
	v_pk_mul_f32 v[56:57], v[56:57], v[164:165] op_sel_hi:[1,0]
	v_pk_mul_f32 v[58:59], v[58:59], v[164:165] op_sel_hi:[1,0]
	v_mul_f32_e32 v214, 0xbfb8aa3b, v60
	v_mul_f32_e32 v215, 0xbfb8aa3b, v61
	v_mul_f32_e32 v216, 0xbfb8aa3b, v62
	v_mul_f32_e32 v217, 0xbfb8aa3b, v63
	v_mul_f32_e32 v218, 0xbfb8aa3b, v56
	v_mul_f32_e32 v219, 0xbfb8aa3b, v57
	v_mul_f32_e32 v220, 0xbfb8aa3b, v58
	v_mul_f32_e32 v221, 0xbfb8aa3b, v59
	v_exp_f32_e32 v214, v214
	v_exp_f32_e32 v215, v215
	v_exp_f32_e32 v216, v216
	v_exp_f32_e32 v217, v217
	v_exp_f32_e32 v218, v218
	v_exp_f32_e32 v219, v219
	v_exp_f32_e32 v220, v220
	v_exp_f32_e32 v221, v221
	v_add_f32_e32 v214, 1.0, v214
	v_add_f32_e32 v215, 1.0, v215
	v_add_f32_e32 v216, 1.0, v216
	v_add_f32_e32 v217, 1.0, v217
	v_add_f32_e32 v218, 1.0, v218
	v_add_f32_e32 v219, 1.0, v219
	v_add_f32_e32 v220, 1.0, v220
	v_add_f32_e32 v221, 1.0, v221
	v_rcp_f32_e32 v214, v214
	v_rcp_f32_e32 v215, v215
	v_rcp_f32_e32 v216, v216
	v_rcp_f32_e32 v217, v217
	v_rcp_f32_e32 v218, v218
	v_rcp_f32_e32 v219, v219
	v_rcp_f32_e32 v220, v220
	v_rcp_f32_e32 v221, v221
	v_pk_mul_f32 v[214:215], v[60:61], v[214:215]
	v_pk_mul_f32 v[216:217], v[62:63], v[216:217]
	v_pk_mul_f32 v[218:219], v[56:57], v[218:219]
	v_pk_mul_f32 v[220:221], v[58:59], v[220:221]
	v_cvt_pk_bf16_f32 v186, v214, v215
	v_cvt_pk_bf16_f32 v187, v216, v217
	v_cvt_pk_bf16_f32 v188, v218, v219
	v_cvt_pk_bf16_f32 v189, v220, v221
	global_store_dwordx4 v[182:183], v[186:189], off
	v_pk_mul_f32 v[52:53], v[52:53], v[164:165] op_sel_hi:[1,0]
	v_pk_mul_f32 v[54:55], v[54:55], v[164:165] op_sel_hi:[1,0]
	v_pk_mul_f32 v[48:49], v[48:49], v[164:165] op_sel_hi:[1,0]
	v_pk_mul_f32 v[50:51], v[50:51], v[164:165] op_sel_hi:[1,0]
	v_mul_f32_e32 v222, 0xbfb8aa3b, v52
	v_mul_f32_e32 v223, 0xbfb8aa3b, v53
	v_mul_f32_e32 v224, 0xbfb8aa3b, v54
	v_mul_f32_e32 v225, 0xbfb8aa3b, v55
	v_mul_f32_e32 v226, 0xbfb8aa3b, v48
	v_mul_f32_e32 v227, 0xbfb8aa3b, v49
	v_mul_f32_e32 v228, 0xbfb8aa3b, v50
	v_mul_f32_e32 v229, 0xbfb8aa3b, v51
	v_exp_f32_e32 v222, v222
	v_exp_f32_e32 v223, v223
	v_exp_f32_e32 v224, v224
	v_exp_f32_e32 v225, v225
	v_exp_f32_e32 v226, v226
	v_exp_f32_e32 v227, v227
	v_exp_f32_e32 v228, v228
	v_exp_f32_e32 v229, v229
	v_add_f32_e32 v222, 1.0, v222
	v_add_f32_e32 v223, 1.0, v223
	v_add_f32_e32 v224, 1.0, v224
	v_add_f32_e32 v225, 1.0, v225
	v_add_f32_e32 v226, 1.0, v226
	v_add_f32_e32 v227, 1.0, v227
	v_add_f32_e32 v228, 1.0, v228
	v_add_f32_e32 v229, 1.0, v229
	v_rcp_f32_e32 v222, v222
	v_rcp_f32_e32 v223, v223
	v_rcp_f32_e32 v224, v224
	v_rcp_f32_e32 v225, v225
	v_rcp_f32_e32 v226, v226
	v_rcp_f32_e32 v227, v227
	v_rcp_f32_e32 v228, v228
	v_rcp_f32_e32 v229, v229
	v_pk_mul_f32 v[222:223], v[52:53], v[222:223]
	v_pk_mul_f32 v[224:225], v[54:55], v[224:225]
	v_pk_mul_f32 v[226:227], v[48:49], v[226:227]
	v_pk_mul_f32 v[228:229], v[50:51], v[228:229]
	v_cvt_pk_bf16_f32 v190, v222, v223
	v_cvt_pk_bf16_f32 v191, v224, v225
	v_cvt_pk_bf16_f32 v192, v226, v227
	v_cvt_pk_bf16_f32 v193, v228, v229
	global_store_dwordx4 v[182:183], v[190:193], off offset:256
	v_lshl_or_b32 v136, v160, s23, v210
	v_lshl_add_u64 v[184:185], v[136:137], 1, s[28:29]
	v_pk_mul_f32 v[44:45], v[44:45], v[162:163] op_sel_hi:[1,0]
	v_pk_mul_f32 v[46:47], v[46:47], v[162:163] op_sel_hi:[1,0]
	v_pk_mul_f32 v[40:41], v[40:41], v[162:163] op_sel_hi:[1,0]
	v_pk_mul_f32 v[42:43], v[42:43], v[162:163] op_sel_hi:[1,0]
	v_mul_f32_e32 v214, 0xbfb8aa3b, v44
	v_mul_f32_e32 v215, 0xbfb8aa3b, v45
	v_mul_f32_e32 v216, 0xbfb8aa3b, v46
; DI void st8(bf16_t* p, f32x4 a, f32x4 b) { u32x4 w; w.x = cvt_pk_bf16(a.x, a.y); w.y = cvt_pk_bf16(a.z, a.w); w.z = cvt_pk_bf16(b.x, b.y); w.w = cvt_pk_bf16(b.z, b.w); *(u32x4*)p = w; }
; DI float sigm(float x) { return __builtin_amdgcn_rcpf(1.f + __builtin_amdgcn_exp2f(-x * LOG2E)); }
; DI f32x4 sigm4(f32x4 v) { f32x4 r; r.x = sigm(v.x); r.y = sigm(v.y); r.z = sigm(v.z); r.w = sigm(v.w); return r; }
;     template <int NAI> DI void run(AccRef acc, const Unit& u, int wr, int wc, int fr, int fq) const {
;     ...
; #pragma unroll
;                 for (int m = 0; m < 4; ++m) { const int row = EPI_ROW(ai, m); bf16_t* prow = gbase + ((unsigned)row * pitch + (unsigned)cl); const float rs = rsv[ai][m];
; #pragma unroll
;                     for (int bj = 0; bj < 2; ++bj) {
;                         f32x4 a = acc[ai][bj][m][0] * rs, b = acc[ai][bj][m][1] * rs;
;                         if (pn >= 12 && pn < 16) { a = a * sigm4(a); b = b * sigm4(b); }
;                         else if (pn >= 16 && pn < 20) { a = a * 0.125f; b = b * 0.125f; }
;                         else if (pn >= 21) { a = sigm4(a); b = sigm4(b); }
;                         st8(prow + bj * 128, a, b);
	v_mul_f32_e32 v217, 0xbfb8aa3b, v47
	v_mul_f32_e32 v218, 0xbfb8aa3b, v40
	v_mul_f32_e32 v219, 0xbfb8aa3b, v41
	v_mul_f32_e32 v220, 0xbfb8aa3b, v42
	v_mul_f32_e32 v221, 0xbfb8aa3b, v43
	v_exp_f32_e32 v214, v214
	v_exp_f32_e32 v215, v215
	v_exp_f32_e32 v216, v216
	v_exp_f32_e32 v217, v217
	v_exp_f32_e32 v218, v218
	v_exp_f32_e32 v219, v219
	v_exp_f32_e32 v220, v220
	v_exp_f32_e32 v221, v221
	v_add_f32_e32 v214, 1.0, v214
	v_add_f32_e32 v215, 1.0, v215
	v_add_f32_e32 v216, 1.0, v216
	v_add_f32_e32 v217, 1.0, v217
	v_add_f32_e32 v218, 1.0, v218
	v_add_f32_e32 v219, 1.0, v219
	v_add_f32_e32 v220, 1.0, v220
	v_add_f32_e32 v221, 1.0, v221
	v_rcp_f32_e32 v214, v214
	v_rcp_f32_e32 v215, v215
	v_rcp_f32_e32 v216, v216
	v_rcp_f32_e32 v217, v217
	v_rcp_f32_e32 v218, v218
	v_rcp_f32_e32 v219, v219
	v_rcp_f32_e32 v220, v220
	v_rcp_f32_e32 v221, v221
	v_pk_mul_f32 v[214:215], v[44:45], v[214:215]
	v_pk_mul_f32 v[216:217], v[46:47], v[216:217]
	v_pk_mul_f32 v[218:219], v[40:41], v[218:219]
	v_pk_mul_f32 v[220:221], v[42:43], v[220:221]
	v_cvt_pk_bf16_f32 v186, v214, v215
	v_cvt_pk_bf16_f32 v187, v216, v217
	v_cvt_pk_bf16_f32 v188, v218, v219
	v_cvt_pk_bf16_f32 v189, v220, v221
	global_store_dwordx4 v[184:185], v[186:189], off
	v_pk_mul_f32 v[36:37], v[36:37], v[162:163] op_sel_hi:[1,0]
	v_pk_mul_f32 v[38:39], v[38:39], v[162:163] op_sel_hi:[1,0]
	v_pk_mul_f32 v[32:33], v[32:33], v[162:163] op_sel_hi:[1,0]
	v_pk_mul_f32 v[34:35], v[34:35], v[162:163] op_sel_hi:[1,0]
	v_mul_f32_e32 v222, 0xbfb8aa3b, v36
	v_mul_f32_e32 v223, 0xbfb8aa3b, v37
	v_mul_f32_e32 v224, 0xbfb8aa3b, v38
	v_mul_f32_e32 v225, 0xbfb8aa3b, v39
	v_mul_f32_e32 v226, 0xbfb8aa3b, v32
	v_mul_f32_e32 v227, 0xbfb8aa3b, v33
	v_mul_f32_e32 v228, 0xbfb8aa3b, v34
	v_mul_f32_e32 v229, 0xbfb8aa3b, v35
	v_exp_f32_e32 v222, v222
	v_exp_f32_e32 v223, v223
	v_exp_f32_e32 v224, v224
	v_exp_f32_e32 v225, v225
	v_exp_f32_e32 v226, v226
	v_exp_f32_e32 v227, v227
	v_exp_f32_e32 v228, v228
	v_exp_f32_e32 v229, v229
	v_add_f32_e32 v222, 1.0, v222
	v_add_f32_e32 v223, 1.0, v223
	v_add_f32_e32 v224, 1.0, v224
	v_add_f32_e32 v225, 1.0, v225
	v_add_f32_e32 v226, 1.0, v226
	v_add_f32_e32 v227, 1.0, v227
	v_add_f32_e32 v228, 1.0, v228
	v_add_f32_e32 v229, 1.0, v229
	v_rcp_f32_e32 v222, v222
	v_rcp_f32_e32 v223, v223
	v_rcp_f32_e32 v224, v224
	v_rcp_f32_e32 v225, v225
	v_rcp_f32_e32 v226, v226
	v_rcp_f32_e32 v227, v227
	v_rcp_f32_e32 v228, v228
	v_rcp_f32_e32 v229, v229
	v_pk_mul_f32 v[222:223], v[36:37], v[222:223]
	v_pk_mul_f32 v[224:225], v[38:39], v[224:225]
	v_pk_mul_f32 v[226:227], v[32:33], v[226:227]
	v_pk_mul_f32 v[228:229], v[34:35], v[228:229]
	v_cvt_pk_bf16_f32 v190, v222, v223
	v_cvt_pk_bf16_f32 v191, v224, v225
	v_cvt_pk_bf16_f32 v192, v226, v227
	v_cvt_pk_bf16_f32 v193, v228, v229
	global_store_dwordx4 v[184:185], v[190:193], off offset:256
	v_lshl_or_b32 v136, v154, s23, v210
	v_lshl_add_u64 v[182:183], v[136:137], 1, s[28:29]
	v_pk_mul_f32 v[28:29], v[28:29], v[156:157] op_sel_hi:[1,0]
	v_pk_mul_f32 v[30:31], v[30:31], v[156:157] op_sel_hi:[1,0]
	v_pk_mul_f32 v[24:25], v[24:25], v[156:157] op_sel_hi:[1,0]
	v_pk_mul_f32 v[26:27], v[26:27], v[156:157] op_sel_hi:[1,0]
	v_mul_f32_e32 v214, 0xbfb8aa3b, v28
	v_mul_f32_e32 v215, 0xbfb8aa3b, v29
	v_mul_f32_e32 v216, 0xbfb8aa3b, v30
	v_mul_f32_e32 v217, 0xbfb8aa3b, v31
	v_mul_f32_e32 v218, 0xbfb8aa3b, v24
	v_mul_f32_e32 v219, 0xbfb8aa3b, v25
	v_mul_f32_e32 v220, 0xbfb8aa3b, v26
	v_mul_f32_e32 v221, 0xbfb8aa3b, v27
	v_exp_f32_e32 v214, v214
	v_exp_f32_e32 v215, v215
	v_exp_f32_e32 v216, v216
	v_exp_f32_e32 v217, v217
	v_exp_f32_e32 v218, v218
	v_exp_f32_e32 v219, v219
	v_exp_f32_e32 v220, v220
	v_exp_f32_e32 v221, v221
	v_add_f32_e32 v214, 1.0, v214
	v_add_f32_e32 v215, 1.0, v215
	v_add_f32_e32 v216, 1.0, v216
	v_add_f32_e32 v217, 1.0, v217
	v_add_f32_e32 v218, 1.0, v218
	v_add_f32_e32 v219, 1.0, v219
	v_add_f32_e32 v220, 1.0, v220
	v_add_f32_e32 v221, 1.0, v221
	v_rcp_f32_e32 v214, v214
	v_rcp_f32_e32 v215, v215
	v_rcp_f32_e32 v216, v216
	v_rcp_f32_e32 v217, v217
	v_rcp_f32_e32 v218, v218
	v_rcp_f32_e32 v219, v219
	v_rcp_f32_e32 v220, v220
	v_rcp_f32_e32 v221, v221
	v_pk_mul_f32 v[214:215], v[28:29], v[214:215]
	v_pk_mul_f32 v[216:217], v[30:31], v[216:217]
	v_pk_mul_f32 v[218:219], v[24:25], v[218:219]
	v_pk_mul_f32 v[220:221], v[26:27], v[220:221]
	v_cvt_pk_bf16_f32 v186, v214, v215
	v_cvt_pk_bf16_f32 v187, v216, v217
	v_cvt_pk_bf16_f32 v188, v218, v219
	v_cvt_pk_bf16_f32 v189, v220, v221
	global_store_dwordx4 v[182:183], v[186:189], off
	v_pk_mul_f32 v[20:21], v[20:21], v[156:157] op_sel_hi:[1,0]
	v_pk_mul_f32 v[22:23], v[22:23], v[156:157] op_sel_hi:[1,0]
	v_pk_mul_f32 v[16:17], v[16:17], v[156:157] op_sel_hi:[1,0]
	v_pk_mul_f32 v[18:19], v[18:19], v[156:157] op_sel_hi:[1,0]
	v_mul_f32_e32 v222, 0xbfb8aa3b, v20
	v_mul_f32_e32 v223, 0xbfb8aa3b, v21
	v_mul_f32_e32 v224, 0xbfb8aa3b, v22
	v_mul_f32_e32 v225, 0xbfb8aa3b, v23
; DI void st8(bf16_t* p, f32x4 a, f32x4 b) { u32x4 w; w.x = cvt_pk_bf16(a.x, a.y); w.y = cvt_pk_bf16(a.z, a.w); w.z = cvt_pk_bf16(b.x, b.y); w.w = cvt_pk_bf16(b.z, b.w); *(u32x4*)p = w; }
; DI f32x4 sigm4(f32x4 v) { f32x4 r; r.x = sigm(v.x); r.y = sigm(v.y); r.z = sigm(v.z); r.w = sigm(v.w); return r; }
;     template <int NAI> DI void run(AccRef acc, const Unit& u, int wr, int wc, int fr, int fq) const {
;     ...
;             if (pn < 8) {
;                 u32x4 cs[4][2];
; #pragma unroll
;                 for (int m = 0; m < 4; ++m) { const int row = EPI_ROW(ai, m); const int pos = row < MP ? (row & (SEQ - 1)) : (SEQ + ((row - MP) & 63));
;                     const unsigned* tp = rope + pos * 128 + cl; cs[m][0] = *(const u32x4*)tp; cs[m][1] = *(const u32x4*)(tp + 4); }
;     ...
; #pragma unroll
;                 for (int m = 0; m < 4; ++m) { const int row = EPI_ROW(ai, m); bf16_t* prow = gbase + ((unsigned)row * pitch + (unsigned)cl); const float rs = rsv[ai][m];
; #pragma unroll
;                     for (int bj = 0; bj < 2; ++bj) {
;                         f32x4 a = acc[ai][bj][m][0] * rs, b = acc[ai][bj][m][1] * rs;
;                         if (pn >= 12 && pn < 16) { a = a * sigm4(a); b = b * sigm4(b); }
;                         else if (pn >= 16 && pn < 20) { a = a * 0.125f; b = b * 0.125f; }
;                         else if (pn >= 21) { a = sigm4(a); b = sigm4(b); }
;                         st8(prow + bj * 128, a, b);
	v_mul_f32_e32 v226, 0xbfb8aa3b, v16
	v_mul_f32_e32 v227, 0xbfb8aa3b, v17
	v_mul_f32_e32 v228, 0xbfb8aa3b, v18
	v_mul_f32_e32 v229, 0xbfb8aa3b, v19
	v_exp_f32_e32 v222, v222
	v_exp_f32_e32 v223, v223
	v_exp_f32_e32 v224, v224
	v_exp_f32_e32 v225, v225
	v_exp_f32_e32 v226, v226
	v_exp_f32_e32 v227, v227
	v_exp_f32_e32 v228, v228
	v_exp_f32_e32 v229, v229
	v_add_f32_e32 v222, 1.0, v222
	v_add_f32_e32 v223, 1.0, v223
	v_add_f32_e32 v224, 1.0, v224
	v_add_f32_e32 v225, 1.0, v225
	v_add_f32_e32 v226, 1.0, v226
	v_add_f32_e32 v227, 1.0, v227
	v_add_f32_e32 v228, 1.0, v228
	v_add_f32_e32 v229, 1.0, v229
	v_rcp_f32_e32 v222, v222
	v_rcp_f32_e32 v223, v223
	v_rcp_f32_e32 v224, v224
	v_rcp_f32_e32 v225, v225
	v_rcp_f32_e32 v226, v226
	v_rcp_f32_e32 v227, v227
	v_rcp_f32_e32 v228, v228
	v_rcp_f32_e32 v229, v229
	v_pk_mul_f32 v[222:223], v[20:21], v[222:223]
	v_pk_mul_f32 v[224:225], v[22:23], v[224:225]
	v_pk_mul_f32 v[226:227], v[16:17], v[226:227]
	v_pk_mul_f32 v[228:229], v[18:19], v[228:229]
	v_cvt_pk_bf16_f32 v190, v222, v223
	v_cvt_pk_bf16_f32 v191, v224, v225
	v_cvt_pk_bf16_f32 v192, v226, v227
	v_cvt_pk_bf16_f32 v193, v228, v229
	global_store_dwordx4 v[182:183], v[190:193], off offset:256
	v_lshl_or_b32 v136, v148, s23, v210
	v_lshl_add_u64 v[184:185], v[136:137], 1, s[28:29]
	v_pk_mul_f32 v[12:13], v[12:13], v[150:151] op_sel_hi:[1,0]
	v_pk_mul_f32 v[14:15], v[14:15], v[150:151] op_sel_hi:[1,0]
	v_pk_mul_f32 v[8:9], v[8:9], v[150:151] op_sel_hi:[1,0]
	v_pk_mul_f32 v[10:11], v[10:11], v[150:151] op_sel_hi:[1,0]
	v_mul_f32_e32 v214, 0xbfb8aa3b, v12
	v_mul_f32_e32 v215, 0xbfb8aa3b, v13
	v_mul_f32_e32 v216, 0xbfb8aa3b, v14
	v_mul_f32_e32 v217, 0xbfb8aa3b, v15
	v_mul_f32_e32 v218, 0xbfb8aa3b, v8
	v_mul_f32_e32 v219, 0xbfb8aa3b, v9
	v_mul_f32_e32 v220, 0xbfb8aa3b, v10
	v_mul_f32_e32 v221, 0xbfb8aa3b, v11
	v_exp_f32_e32 v214, v214
	v_exp_f32_e32 v215, v215
	v_exp_f32_e32 v216, v216
	v_exp_f32_e32 v217, v217
	v_exp_f32_e32 v218, v218
	v_exp_f32_e32 v219, v219
	v_exp_f32_e32 v220, v220
	v_exp_f32_e32 v221, v221
	v_add_f32_e32 v214, 1.0, v214
	v_add_f32_e32 v215, 1.0, v215
	v_add_f32_e32 v216, 1.0, v216
	v_add_f32_e32 v217, 1.0, v217
	v_add_f32_e32 v218, 1.0, v218
	v_add_f32_e32 v219, 1.0, v219
	v_add_f32_e32 v220, 1.0, v220
	v_add_f32_e32 v221, 1.0, v221
	v_rcp_f32_e32 v214, v214
	v_rcp_f32_e32 v215, v215
	v_rcp_f32_e32 v216, v216
	v_rcp_f32_e32 v217, v217
	v_rcp_f32_e32 v218, v218
	v_rcp_f32_e32 v219, v219
	v_rcp_f32_e32 v220, v220
	v_rcp_f32_e32 v221, v221
	v_pk_mul_f32 v[214:215], v[12:13], v[214:215]
	v_pk_mul_f32 v[216:217], v[14:15], v[216:217]
	v_pk_mul_f32 v[218:219], v[8:9], v[218:219]
	v_pk_mul_f32 v[220:221], v[10:11], v[220:221]
	v_cvt_pk_bf16_f32 v186, v214, v215
	v_cvt_pk_bf16_f32 v187, v216, v217
	v_cvt_pk_bf16_f32 v188, v218, v219
	v_cvt_pk_bf16_f32 v189, v220, v221
	global_store_dwordx4 v[184:185], v[186:189], off
	v_pk_mul_f32 v[4:5], v[4:5], v[150:151] op_sel_hi:[1,0]
	v_pk_mul_f32 v[6:7], v[6:7], v[150:151] op_sel_hi:[1,0]
	v_pk_mul_f32 v[0:1], v[0:1], v[150:151] op_sel_hi:[1,0]
	v_pk_mul_f32 v[2:3], v[2:3], v[150:151] op_sel_hi:[1,0]
	v_mul_f32_e32 v222, 0xbfb8aa3b, v4
	v_mul_f32_e32 v223, 0xbfb8aa3b, v5
	v_mul_f32_e32 v224, 0xbfb8aa3b, v6
	v_mul_f32_e32 v225, 0xbfb8aa3b, v7
	v_mul_f32_e32 v226, 0xbfb8aa3b, v0
	v_mul_f32_e32 v227, 0xbfb8aa3b, v1
	v_mul_f32_e32 v228, 0xbfb8aa3b, v2
	v_mul_f32_e32 v229, 0xbfb8aa3b, v3
	v_exp_f32_e32 v222, v222
	v_exp_f32_e32 v223, v223
	v_exp_f32_e32 v224, v224
	v_exp_f32_e32 v225, v225
	v_exp_f32_e32 v226, v226
	v_exp_f32_e32 v227, v227
	v_exp_f32_e32 v228, v228
	v_exp_f32_e32 v229, v229
	v_add_f32_e32 v222, 1.0, v222
	v_add_f32_e32 v223, 1.0, v223
	v_add_f32_e32 v224, 1.0, v224
	v_add_f32_e32 v225, 1.0, v225
	v_add_f32_e32 v226, 1.0, v226
	v_add_f32_e32 v227, 1.0, v227
	v_add_f32_e32 v228, 1.0, v228
	v_add_f32_e32 v229, 1.0, v229
	v_rcp_f32_e32 v222, v222
	v_rcp_f32_e32 v223, v223
	v_rcp_f32_e32 v224, v224
	v_rcp_f32_e32 v225, v225
	v_rcp_f32_e32 v226, v226
	v_rcp_f32_e32 v227, v227
	v_rcp_f32_e32 v228, v228
	v_rcp_f32_e32 v229, v229
	v_pk_mul_f32 v[222:223], v[4:5], v[222:223]
	v_pk_mul_f32 v[224:225], v[6:7], v[224:225]
	v_pk_mul_f32 v[226:227], v[0:1], v[226:227]
	v_pk_mul_f32 v[228:229], v[2:3], v[228:229]
	v_cvt_pk_bf16_f32 v190, v222, v223
	v_cvt_pk_bf16_f32 v191, v224, v225
	v_cvt_pk_bf16_f32 v192, v226, v227
	v_cvt_pk_bf16_f32 v193, v228, v229
	global_store_dwordx4 v[184:185], v[190:193], off offset:256
	s_branch .LBB0_275
.LBB0_272:
	v_and_b32_e32 v136, 63, v176
	v_and_b32_e32 v149, 63, v170
	v_and_b32_e32 v151, 63, v166
	v_and_b32_e32 v155, 63, v174
	s_and_b64 vcc, exec, s[34:35]
	v_or_b32_e32 v161, 0x1000, v155
	v_or_b32_e32 v159, 0x1000, v136
	v_or_b32_e32 v155, 0x1000, v149
	v_or_b32_e32 v149, 0x1000, v151
	s_cbranch_vccnz .LBB0_280
	s_andn2_b64 vcc, exec, s[30:31]
	s_mov_b64 s[30:31], -1
.LBB0_274:
	s_and_b64 vcc, exec, s[30:31]
	s_cbranch_vccnz .LBB0_322

; DI void st8(bf16_t* p, f32x4 a, f32x4 b) { u32x4 w; w.x = cvt_pk_bf16(a.x, a.y); w.y = cvt_pk_bf16(a.z, a.w); w.z = cvt_pk_bf16(b.x, b.y); w.w = cvt_pk_bf16(b.z, b.w); *(u32x4*)p = w; }
; DI float f16lo(unsigned w) { return (float)__builtin_bit_cast(h16x2, w).x; }
; DI float f16hi(unsigned w) { return (float)__builtin_bit_cast(h16x2, w).y; }
;     template <int NAI> DI void run(AccRef acc, const Unit& u, int wr, int wc, int fr, int fq) const {
;     ...
;                 for (int m = 0; m < 4; ++m) { const int row = EPI_ROW(ai, m); const int pos = row < MP ? (row & (SEQ - 1)) : (SEQ + ((row - MP) & 63));
;                     const unsigned* tp = rope + pos * 128 + cl; cs[m][0] = *(const u32x4*)tp; cs[m][1] = *(const u32x4*)(tp + 4); }
; #pragma unroll
;                 for (int m = 0; m < 4; ++m) { const int row = EPI_ROW(ai, m); bf16_t* prow = gbase + ((unsigned)row * pitch + (unsigned)cl);
;                     const float sc = pn >= 4 ? rsv[ai][m] * 0.0625f : rsv[ai][m];
;                     const u32x4 w0 = cs[m][0], w1 = cs[m][1];
;                     const f32x4 c0 = (f32x4){f16lo(w0.x), f16lo(w0.y), f16lo(w0.z), f16lo(w0.w)}, s0 = (f32x4){f16hi(w0.x), f16hi(w0.y), f16hi(w0.z), f16hi(w0.w)};
;                     const f32x4 c1 = (f32x4){f16lo(w1.x), f16lo(w1.y), f16lo(w1.z), f16lo(w1.w)}, s1 = (f32x4){f16hi(w1.x), f16hi(w1.y), f16hi(w1.z), f16hi(w1.w)};
;                     const f32x4 x10 = acc[ai][0][m][0] * sc, x11 = acc[ai][0][m][1] * sc, x20 = acc[ai][1][m][0] * sc, x21 = acc[ai][1][m][1] * sc;
;                     st8(prow, x10 * c0 - x20 * s0, x11 * c1 - x21 * s1);
;                     st8(prow + 128, x20 * c0 + x10 * s0, x21 * c1 + x11 * s1); }
.LBB0_280:
	v_and_b32_e32 v136, 0xfff, v174
	v_cmp_gt_i32_e32 vcc, s48, v174
	s_waitcnt vmcnt(0)
	v_mul_f32_e32 v157, 0x3d800000, v180
	v_mul_f32_e32 v163, 0x3d800000, v178
	v_cndmask_b32_e32 v136, v161, v136, vcc
	v_lshlrev_b32_e32 v136, 9, v136
	v_lshl_add_u64 v[186:187], v[138:139], 0, v[136:137]
	global_load_dwordx4 v[182:185], v[186:187], off
	s_nop 0
	global_load_dwordx4 v[186:189], v[186:187], off offset:16
	v_and_b32_e32 v136, 0xfff, v176
	v_cmp_gt_i32_e32 vcc, s48, v176
	v_cndmask_b32_e64 v198, v178, v163, s[4:5]
	v_and_b32_e32 v151, 0xfff, v166
	v_cndmask_b32_e32 v136, v159, v136, vcc
	v_lshlrev_b32_e32 v136, 9, v136
	v_lshl_add_u64 v[194:195], v[138:139], 0, v[136:137]
	global_load_dwordx4 v[190:193], v[194:195], off
	v_and_b32_e32 v136, 0xfff, v170
	global_load_dwordx4 v[194:197], v[194:195], off offset:16
	v_cmp_gt_i32_e32 vcc, s48, v170
	v_pk_mul_f32 v[102:103], v[102:103], v[198:199] op_sel_hi:[1,0]
	v_pk_mul_f32 v[100:101], v[100:101], v[198:199] op_sel_hi:[1,0]
	v_cndmask_b32_e32 v165, v155, v136, vcc
	v_cndmask_b32_e64 v136, v180, v157, s[4:5]
	v_pk_mul_f32 v[178:179], v[126:127], v[136:137] op_sel_hi:[1,0]
	v_pk_mul_f32 v[180:181], v[124:125], v[136:137] op_sel_hi:[1,0]
	v_pk_mul_f32 v[214:215], v[122:123], v[136:137] op_sel_hi:[1,0]
	v_pk_mul_f32 v[216:217], v[120:121], v[136:137] op_sel_hi:[1,0]
	v_pk_mul_f32 v[218:219], v[118:119], v[136:137] op_sel_hi:[1,0]
	v_pk_mul_f32 v[220:221], v[116:117], v[136:137] op_sel_hi:[1,0]
	v_pk_mul_f32 v[222:223], v[114:115], v[136:137] op_sel_hi:[1,0]
	v_pk_mul_f32 v[224:225], v[112:113], v[136:137] op_sel_hi:[1,0]
	v_lshlrev_b32_e32 v136, 9, v165
	v_lshl_add_u64 v[116:117], v[138:139], 0, v[136:137]
	global_load_dwordx4 v[112:115], v[116:117], off
	s_nop 0
	global_load_dwordx4 v[116:119], v[116:117], off offset:16
	v_cmp_gt_i32_e32 vcc, s48, v166
	v_pk_mul_f32 v[110:111], v[110:111], v[198:199] op_sel_hi:[1,0]
	v_pk_mul_f32 v[108:109], v[108:109], v[198:199] op_sel_hi:[1,0]
	v_cndmask_b32_e32 v151, v149, v151, vcc
	v_lshlrev_b32_e32 v136, 9, v151
	v_lshl_add_u64 v[124:125], v[138:139], 0, v[136:137]
	global_load_dwordx4 v[120:123], v[124:125], off
	s_nop 0
	global_load_dwordx4 v[124:127], v[124:125], off offset:16
	v_lshl_or_b32 v136, v174, 10, v210
	v_lshl_add_u64 v[226:227], v[136:137], 1, s[28:29]
	v_lshl_or_b32 v136, v176, 10, v210
	v_pk_mul_f32 v[106:107], v[106:107], v[198:199] op_sel_hi:[1,0]
	v_pk_mul_f32 v[104:105], v[104:105], v[198:199] op_sel_hi:[1,0]
	v_lshl_add_u64 v[228:229], v[136:137], 1, s[28:29]
	v_lshl_or_b32 v136, v170, 10, v210
	s_waitcnt vmcnt(7)
	v_cvt_f32_f16_e32 v174, v182
	v_cvt_f32_f16_e32 v175, v183
	v_cvt_f32_f16_e32 v176, v184
	v_cvt_f32_f16_e32 v177, v185
	v_cvt_f32_f16_sdwa v182, v182 dst_sel:DWORD dst_unused:UNUSED_PAD src0_sel:WORD_1
	v_cvt_f32_f16_sdwa v183, v183 dst_sel:DWORD dst_unused:UNUSED_PAD src0_sel:WORD_1
	v_cvt_f32_f16_sdwa v184, v184 dst_sel:DWORD dst_unused:UNUSED_PAD src0_sel:WORD_1
	v_cvt_f32_f16_sdwa v185, v185 dst_sel:DWORD dst_unused:UNUSED_PAD src0_sel:WORD_1
	s_waitcnt vmcnt(6)
	v_cvt_f32_f16_e32 v230, v186
	v_cvt_f32_f16_e32 v231, v187
	v_cvt_f32_f16_e32 v232, v188
	v_cvt_f32_f16_e32 v233, v189
	v_cvt_f32_f16_sdwa v186, v186 dst_sel:DWORD dst_unused:UNUSED_PAD src0_sel:WORD_1
	v_cvt_f32_f16_sdwa v187, v187 dst_sel:DWORD dst_unused:UNUSED_PAD src0_sel:WORD_1
	v_cvt_f32_f16_sdwa v188, v188 dst_sel:DWORD dst_unused:UNUSED_PAD src0_sel:WORD_1
	v_cvt_f32_f16_sdwa v189, v189 dst_sel:DWORD dst_unused:UNUSED_PAD src0_sel:WORD_1
	v_pk_mul_f32 v[238:239], v[220:221], v[182:183]
	v_pk_mul_f32 v[240:241], v[218:219], v[184:185]
	v_pk_mul_f32 v[242:243], v[224:225], v[186:187]
	v_pk_mul_f32 v[244:245], v[222:223], v[188:189]
	v_pk_mul_f32 v[220:221], v[220:221], v[174:175]
	v_pk_mul_f32 v[218:219], v[218:219], v[176:177]
	v_pk_mul_f32 v[224:225], v[224:225], v[230:231]
	v_pk_mul_f32 v[222:223], v[222:223], v[232:233]
	v_pk_fma_f32 v[176:177], v[178:179], v[176:177], v[240:241] neg_lo:[0,0,1] neg_hi:[0,0,1]
	v_pk_fma_f32 v[174:175], v[180:181], v[174:175], v[238:239] neg_lo:[0,0,1] neg_hi:[0,0,1]
	v_pk_fma_f32 v[232:233], v[214:215], v[232:233], v[244:245] neg_lo:[0,0,1] neg_hi:[0,0,1]
	v_pk_fma_f32 v[230:231], v[216:217], v[230:231], v[242:243] neg_lo:[0,0,1] neg_hi:[0,0,1]
	v_pk_fma_f32 v[184:185], v[178:179], v[184:185], v[218:219]
	v_pk_fma_f32 v[178:179], v[180:181], v[182:183], v[220:221]
	v_pk_fma_f32 v[182:183], v[214:215], v[188:189], v[222:223]
	v_pk_fma_f32 v[180:181], v[216:217], v[186:187], v[224:225]
	v_cvt_pk_bf16_f32 v174, v174, v175
	v_cvt_pk_bf16_f32 v175, v176, v177
	v_cvt_pk_bf16_f32 v176, v230, v231
	v_cvt_pk_bf16_f32 v177, v232, v233
	v_cvt_pk_bf16_f32 v180, v180, v181
	v_cvt_pk_bf16_f32 v181, v182, v183
	s_waitcnt vmcnt(5)
	v_cvt_f32_f16_e32 v234, v190
	v_cvt_f32_f16_e32 v235, v191
	v_cvt_f32_f16_sdwa v190, v190 dst_sel:DWORD dst_unused:UNUSED_PAD src0_sel:WORD_1
	v_cvt_f32_f16_sdwa v191, v191 dst_sel:DWORD dst_unused:UNUSED_PAD src0_sel:WORD_1
	v_cvt_pk_bf16_f32 v178, v178, v179
	v_cvt_pk_bf16_f32 v179, v184, v185
	global_store_dwordx4 v[226:227], v[174:177], off
	global_store_dwordx4 v[226:227], v[178:181], off offset:256
	s_waitcnt vmcnt(6)
; DI void st8(bf16_t* p, f32x4 a, f32x4 b) { u32x4 w; w.x = cvt_pk_bf16(a.x, a.y); w.y = cvt_pk_bf16(a.z, a.w); w.z = cvt_pk_bf16(b.x, b.y); w.w = cvt_pk_bf16(b.z, b.w); *(u32x4*)p = w; }
; DI float f16lo(unsigned w) { return (float)__builtin_bit_cast(h16x2, w).x; }
; DI float f16hi(unsigned w) { return (float)__builtin_bit_cast(h16x2, w).y; }
;     template <int NAI> DI void run(AccRef acc, const Unit& u, int wr, int wc, int fr, int fq) const {
;     ...
;                 for (int m = 0; m < 4; ++m) { const int row = EPI_ROW(ai, m); bf16_t* prow = gbase + ((unsigned)row * pitch + (unsigned)cl);
;                     const float sc = pn >= 4 ? rsv[ai][m] * 0.0625f : rsv[ai][m];
;                     const u32x4 w0 = cs[m][0], w1 = cs[m][1];
;                     const f32x4 c0 = (f32x4){f16lo(w0.x), f16lo(w0.y), f16lo(w0.z), f16lo(w0.w)}, s0 = (f32x4){f16hi(w0.x), f16hi(w0.y), f16hi(w0.z), f16hi(w0.w)};
;                     const f32x4 c1 = (f32x4){f16lo(w1.x), f16lo(w1.y), f16lo(w1.z), f16lo(w1.w)}, s1 = (f32x4){f16hi(w1.x), f16hi(w1.y), f16hi(w1.z), f16hi(w1.w)};
;                     const f32x4 x10 = acc[ai][0][m][0] * sc, x11 = acc[ai][0][m][1] * sc, x20 = acc[ai][1][m][0] * sc, x21 = acc[ai][1][m][1] * sc;
;                     st8(prow, x10 * c0 - x20 * s0, x11 * c1 - x21 * s1);
;                     st8(prow + 128, x20 * c0 + x10 * s0, x21 * c1 + x11 * s1); }
	v_cvt_f32_f16_sdwa v182, v196 dst_sel:DWORD dst_unused:UNUSED_PAD src0_sel:WORD_1
	v_cvt_f32_f16_sdwa v174, v192 dst_sel:DWORD dst_unused:UNUSED_PAD src0_sel:WORD_1
	v_cvt_f32_f16_sdwa v175, v193 dst_sel:DWORD dst_unused:UNUSED_PAD src0_sel:WORD_1
	v_cvt_f32_f16_sdwa v180, v194 dst_sel:DWORD dst_unused:UNUSED_PAD src0_sel:WORD_1
	v_cvt_f32_f16_sdwa v181, v195 dst_sel:DWORD dst_unused:UNUSED_PAD src0_sel:WORD_1
	v_cvt_f32_f16_sdwa v183, v197 dst_sel:DWORD dst_unused:UNUSED_PAD src0_sel:WORD_1
	v_cvt_f32_f16_e32 v236, v192
	v_cvt_f32_f16_e32 v237, v193
	v_cvt_f32_f16_e32 v176, v194
	v_cvt_f32_f16_e32 v177, v195
	v_cvt_f32_f16_e32 v178, v196
	v_cvt_f32_f16_e32 v179, v197
	v_pk_mul_f32 v[184:185], v[98:99], v[198:199] op_sel_hi:[1,0]
	v_pk_mul_f32 v[186:187], v[96:97], v[198:199] op_sel_hi:[1,0]
	v_pk_mul_f32 v[96:97], v[100:101], v[190:191]
	v_pk_mul_f32 v[98:99], v[102:103], v[174:175]
	v_pk_mul_f32 v[188:189], v[186:187], v[180:181]
	v_pk_mul_f32 v[192:193], v[184:185], v[182:183]
	v_pk_fma_f32 v[98:99], v[110:111], v[236:237], v[98:99] neg_lo:[0,0,1] neg_hi:[0,0,1]
	v_pk_fma_f32 v[96:97], v[108:109], v[234:235], v[96:97] neg_lo:[0,0,1] neg_hi:[0,0,1]
	v_pk_fma_f32 v[192:193], v[106:107], v[178:179], v[192:193] neg_lo:[0,0,1] neg_hi:[0,0,1]
	v_pk_fma_f32 v[188:189], v[104:105], v[176:177], v[188:189] neg_lo:[0,0,1] neg_hi:[0,0,1]
	v_cvt_pk_bf16_f32 v96, v96, v97
	v_cvt_pk_bf16_f32 v97, v98, v99
	v_cvt_pk_bf16_f32 v98, v188, v189
	v_cvt_pk_bf16_f32 v99, v192, v193
	global_store_dwordx4 v[228:229], v[96:99], off
	s_nop 1
	v_pk_mul_f32 v[96:97], v[100:101], v[234:235]
	v_pk_mul_f32 v[98:99], v[102:103], v[236:237]
	v_pk_mul_f32 v[100:101], v[186:187], v[176:177]
	v_pk_mul_f32 v[102:103], v[184:185], v[178:179]
	v_pk_fma_f32 v[98:99], v[110:111], v[174:175], v[98:99]
	v_pk_fma_f32 v[96:97], v[108:109], v[190:191], v[96:97]
	v_pk_fma_f32 v[102:103], v[106:107], v[182:183], v[102:103]
	v_pk_fma_f32 v[100:101], v[104:105], v[180:181], v[100:101]
	v_cvt_pk_bf16_f32 v96, v96, v97
	v_cvt_pk_bf16_f32 v97, v98, v99
	v_cvt_pk_bf16_f32 v98, v100, v101
	v_cvt_pk_bf16_f32 v99, v102, v103
	s_waitcnt vmcnt(6)
	v_cvt_f32_f16_e32 v100, v112
	v_cvt_f32_f16_e32 v101, v113
	v_cvt_f32_f16_e32 v102, v114
	v_cvt_f32_f16_e32 v103, v115
	v_cvt_f32_f16_sdwa v104, v112 dst_sel:DWORD dst_unused:UNUSED_PAD src0_sel:WORD_1
	v_cvt_f32_f16_sdwa v105, v113 dst_sel:DWORD dst_unused:UNUSED_PAD src0_sel:WORD_1
	v_cvt_f32_f16_sdwa v106, v114 dst_sel:DWORD dst_unused:UNUSED_PAD src0_sel:WORD_1
	v_cvt_f32_f16_sdwa v107, v115 dst_sel:DWORD dst_unused:UNUSED_PAD src0_sel:WORD_1
	s_waitcnt vmcnt(5)
	v_cvt_f32_f16_sdwa v112, v116 dst_sel:DWORD dst_unused:UNUSED_PAD src0_sel:WORD_1
	v_cvt_f32_f16_sdwa v113, v117 dst_sel:DWORD dst_unused:UNUSED_PAD src0_sel:WORD_1
	v_cvt_f32_f16_sdwa v114, v118 dst_sel:DWORD dst_unused:UNUSED_PAD src0_sel:WORD_1
	v_cvt_f32_f16_sdwa v115, v119 dst_sel:DWORD dst_unused:UNUSED_PAD src0_sel:WORD_1
	global_store_dwordx4 v[228:229], v[96:99], off offset:256
	v_cvt_f32_f16_e32 v108, v116
	v_cvt_f32_f16_e32 v109, v117
	v_mul_f32_e32 v98, 0x3d800000, v172
	v_cvt_f32_f16_e32 v110, v118
	v_cvt_f32_f16_e32 v111, v119
	v_cndmask_b32_e64 v98, v172, v98, s[4:5]
	v_pk_mul_f32 v[94:95], v[94:95], v[98:99] op_sel_hi:[1,0]
	v_pk_mul_f32 v[92:93], v[92:93], v[98:99] op_sel_hi:[1,0]
	v_pk_mul_f32 v[90:91], v[90:91], v[98:99] op_sel_hi:[1,0]
	v_pk_mul_f32 v[88:89], v[88:89], v[98:99] op_sel_hi:[1,0]
	v_pk_mul_f32 v[86:87], v[86:87], v[98:99] op_sel_hi:[1,0]
	v_pk_mul_f32 v[84:85], v[84:85], v[98:99] op_sel_hi:[1,0]
	v_pk_mul_f32 v[116:117], v[82:83], v[98:99] op_sel_hi:[1,0]
	v_pk_mul_f32 v[98:99], v[80:81], v[98:99] op_sel_hi:[1,0]
	v_pk_mul_f32 v[80:81], v[84:85], v[104:105]
	v_pk_mul_f32 v[82:83], v[86:87], v[106:107]
	v_pk_mul_f32 v[118:119], v[98:99], v[112:113]
	v_pk_mul_f32 v[170:171], v[116:117], v[114:115]
	v_pk_fma_f32 v[82:83], v[94:95], v[102:103], v[82:83] neg_lo:[0,0,1] neg_hi:[0,0,1]
	v_pk_fma_f32 v[80:81], v[92:93], v[100:101], v[80:81] neg_lo:[0,0,1] neg_hi:[0,0,1]
	v_pk_fma_f32 v[170:171], v[90:91], v[110:111], v[170:171] neg_lo:[0,0,1] neg_hi:[0,0,1]
	v_pk_fma_f32 v[118:119], v[88:89], v[108:109], v[118:119] neg_lo:[0,0,1] neg_hi:[0,0,1]
	v_lshl_add_u64 v[96:97], v[136:137], 1, s[28:29]
	v_cvt_pk_bf16_f32 v80, v80, v81
	v_cvt_pk_bf16_f32 v81, v82, v83
	v_cvt_pk_bf16_f32 v82, v118, v119
	v_cvt_pk_bf16_f32 v83, v170, v171
	global_store_dwordx4 v[96:97], v[80:83], off
	v_lshl_or_b32 v136, v166, 10, v210
	s_nop 0
	v_pk_mul_f32 v[80:81], v[84:85], v[100:101]
	v_pk_mul_f32 v[82:83], v[86:87], v[102:103]
	v_pk_mul_f32 v[84:85], v[98:99], v[108:109]
	v_pk_mul_f32 v[86:87], v[116:117], v[110:111]
	v_pk_fma_f32 v[82:83], v[94:95], v[106:107], v[82:83]
	v_pk_fma_f32 v[80:81], v[92:93], v[104:105], v[80:81]
	v_pk_fma_f32 v[86:87], v[90:91], v[114:115], v[86:87]
	v_pk_fma_f32 v[84:85], v[88:89], v[112:113], v[84:85]
	v_cvt_pk_bf16_f32 v80, v80, v81
	v_cvt_pk_bf16_f32 v81, v82, v83
	v_cvt_pk_bf16_f32 v82, v84, v85
	v_cvt_pk_bf16_f32 v83, v86, v87
	global_store_dwordx4 v[96:97], v[80:83], off offset:256
	s_waitcnt vmcnt(7)
; DI void st8(bf16_t* p, f32x4 a, f32x4 b) { u32x4 w; w.x = cvt_pk_bf16(a.x, a.y); w.y = cvt_pk_bf16(a.z, a.w); w.z = cvt_pk_bf16(b.x, b.y); w.w = cvt_pk_bf16(b.z, b.w); *(u32x4*)p = w; }
; DI float f16lo(unsigned w) { return (float)__builtin_bit_cast(h16x2, w).x; }
; DI float f16hi(unsigned w) { return (float)__builtin_bit_cast(h16x2, w).y; }
;     template <int NAI> DI void run(AccRef acc, const Unit& u, int wr, int wc, int fr, int fq) const {
;     ...
;                 for (int m = 0; m < 4; ++m) { const int row = EPI_ROW(ai, m); bf16_t* prow = gbase + ((unsigned)row * pitch + (unsigned)cl);
;                     const float sc = pn >= 4 ? rsv[ai][m] * 0.0625f : rsv[ai][m];
;                     const u32x4 w0 = cs[m][0], w1 = cs[m][1];
;                     const f32x4 c0 = (f32x4){f16lo(w0.x), f16lo(w0.y), f16lo(w0.z), f16lo(w0.w)}, s0 = (f32x4){f16hi(w0.x), f16hi(w0.y), f16hi(w0.z), f16hi(w0.w)};
;                     const f32x4 c1 = (f32x4){f16lo(w1.x), f16lo(w1.y), f16lo(w1.z), f16lo(w1.w)}, s1 = (f32x4){f16hi(w1.x), f16hi(w1.y), f16hi(w1.z), f16hi(w1.w)};
;                     const f32x4 x10 = acc[ai][0][m][0] * sc, x11 = acc[ai][0][m][1] * sc, x20 = acc[ai][1][m][0] * sc, x21 = acc[ai][1][m][1] * sc;
;                     st8(prow, x10 * c0 - x20 * s0, x11 * c1 - x21 * s1);
;                     st8(prow + 128, x20 * c0 + x10 * s0, x21 * c1 + x11 * s1); }
	v_cvt_f32_f16_sdwa v88, v120 dst_sel:DWORD dst_unused:UNUSED_PAD src0_sel:WORD_1
	v_cvt_f32_f16_sdwa v89, v121 dst_sel:DWORD dst_unused:UNUSED_PAD src0_sel:WORD_1
	v_cvt_f32_f16_sdwa v90, v122 dst_sel:DWORD dst_unused:UNUSED_PAD src0_sel:WORD_1
	v_cvt_f32_f16_sdwa v91, v123 dst_sel:DWORD dst_unused:UNUSED_PAD src0_sel:WORD_1
	s_waitcnt vmcnt(6)
	v_cvt_f32_f16_sdwa v96, v124 dst_sel:DWORD dst_unused:UNUSED_PAD src0_sel:WORD_1
	v_cvt_f32_f16_sdwa v97, v125 dst_sel:DWORD dst_unused:UNUSED_PAD src0_sel:WORD_1
	v_cvt_f32_f16_sdwa v98, v126 dst_sel:DWORD dst_unused:UNUSED_PAD src0_sel:WORD_1
	v_cvt_f32_f16_sdwa v99, v127 dst_sel:DWORD dst_unused:UNUSED_PAD src0_sel:WORD_1
	v_mul_f32_e32 v82, 0x3d800000, v168
	v_cvt_f32_f16_e32 v84, v120
	v_cvt_f32_f16_e32 v85, v121
	v_cvt_f32_f16_e32 v86, v122
	v_cvt_f32_f16_e32 v87, v123
	v_cvt_f32_f16_e32 v92, v124
	v_cvt_f32_f16_e32 v93, v125
	v_cvt_f32_f16_e32 v94, v126
	v_cvt_f32_f16_e32 v95, v127
	v_cndmask_b32_e64 v82, v168, v82, s[4:5]
	v_pk_mul_f32 v[78:79], v[78:79], v[82:83] op_sel_hi:[1,0]
	v_pk_mul_f32 v[76:77], v[76:77], v[82:83] op_sel_hi:[1,0]
	v_pk_mul_f32 v[74:75], v[74:75], v[82:83] op_sel_hi:[1,0]
	v_pk_mul_f32 v[72:73], v[72:73], v[82:83] op_sel_hi:[1,0]
	v_pk_mul_f32 v[70:71], v[70:71], v[82:83] op_sel_hi:[1,0]
	v_pk_mul_f32 v[68:69], v[68:69], v[82:83] op_sel_hi:[1,0]
	v_pk_mul_f32 v[100:101], v[66:67], v[82:83] op_sel_hi:[1,0]
	v_pk_mul_f32 v[82:83], v[64:65], v[82:83] op_sel_hi:[1,0]
	v_pk_mul_f32 v[64:65], v[68:69], v[88:89]
	v_pk_mul_f32 v[66:67], v[70:71], v[90:91]
	v_pk_mul_f32 v[102:103], v[82:83], v[96:97]
	v_pk_mul_f32 v[104:105], v[100:101], v[98:99]
	v_pk_fma_f32 v[66:67], v[78:79], v[86:87], v[66:67] neg_lo:[0,0,1] neg_hi:[0,0,1]
	v_pk_fma_f32 v[64:65], v[76:77], v[84:85], v[64:65] neg_lo:[0,0,1] neg_hi:[0,0,1]
	v_pk_fma_f32 v[104:105], v[74:75], v[94:95], v[104:105] neg_lo:[0,0,1] neg_hi:[0,0,1]
	v_pk_fma_f32 v[102:103], v[72:73], v[92:93], v[102:103] neg_lo:[0,0,1] neg_hi:[0,0,1]
	v_lshl_add_u64 v[80:81], v[136:137], 1, s[28:29]
	v_cvt_pk_bf16_f32 v64, v64, v65
	v_cvt_pk_bf16_f32 v65, v66, v67
	v_cvt_pk_bf16_f32 v66, v102, v103
	v_cvt_pk_bf16_f32 v67, v104, v105
	global_store_dwordx4 v[80:81], v[64:67], off
	s_nop 1
	v_pk_mul_f32 v[64:65], v[68:69], v[84:85]
	v_pk_mul_f32 v[66:67], v[70:71], v[86:87]
	v_pk_mul_f32 v[68:69], v[82:83], v[92:93]
	v_pk_mul_f32 v[70:71], v[100:101], v[94:95]
	v_pk_fma_f32 v[66:67], v[78:79], v[90:91], v[66:67]
	v_pk_fma_f32 v[64:65], v[76:77], v[88:89], v[64:65]
	v_pk_fma_f32 v[70:71], v[74:75], v[98:99], v[70:71]
	v_pk_fma_f32 v[68:69], v[72:73], v[96:97], v[68:69]
	v_cvt_pk_bf16_f32 v64, v64, v65
	v_cvt_pk_bf16_f32 v65, v66, v67
	v_cvt_pk_bf16_f32 v66, v68, v69
	v_cvt_pk_bf16_f32 v67, v70, v71
	global_store_dwordx4 v[80:81], v[64:67], off offset:256
	s_andn2_b64 vcc, exec, s[30:31]
	s_mov_b64 s[30:31], -1
	s_branch .LBB0_274

; #define PG8_WAIT_V(n) asm volatile("s_waitcnt vmcnt(" #n ")" ::: "memory")
; #define PG8_BAR __builtin_amdgcn_s_barrier()
; template <class Epi, bool ALIGN_EPI>
; DI void gemm_phase(lptr lds, const Gemm g, const StaticOrder& S, const Epi& E) {
;     ...
;         if constexpr (ALIGN_EPI) { if (wr == 1) PG8_BAR; }
;     }
;     PG8_WAIT_V(0);
;     if constexpr (!ALIGN_EPI) { if (wr == 0) PG8_BAR; }
;     PG8_BAR;
.LBB0_323:
	s_andn2_b64 vcc, exec, s[8:9]
	s_cbranch_vccnz .LBB0_216
	s_barrier
	s_branch .LBB0_216
.LBB0_437:
	s_waitcnt vmcnt(0)
	s_barrier

; DI bf16x8 tr_pair(lptr p0, lptr p1) { const s16x4 a = ldstr(p0), b = ldstr(p1); return (bf16x8){a.x, a.y, a.z, a.w, b.x, b.y, b.z, b.w}; }
; DI bf16x8 pack8(f32x4 a, f32x4 b) { u32x4 w; w.x = cvt_pk_bf16(a.x, a.y); w.y = cvt_pk_bf16(a.z, a.w); w.z = cvt_pk_bf16(b.x, b.y); w.w = cvt_pk_bf16(b.z, b.w); return __builtin_bit_cast(bf16x8, w); }
; DI f32x4 mfma16(bf16x8 a, bf16x8 b, f32x4 c) { return __builtin_amdgcn_mfma_f32_16x16x32_bf16(a, b, c, 0, 0, 0); }
; DI float ex2(float x) { return __builtin_amdgcn_exp2f(x); }
;     ...
;         bf16x8 qf[8];
; #pragma unroll
;         for (int ks = 0; ks < 8; ++ks) qf[ks] = lds16(L + R_QS + (16 * nt + l15) * QP + (32 * ks + 8 * g4) * 2);
;         f32x4 accS[4];
; #pragma unroll
;         for (int jt = 0; jt < 4; ++jt) { accS[jt] = (f32x4){0.f, 0.f, 0.f, 0.f};
; #pragma unroll
;             for (int ks = 0; ks < 8; ++ks) accS[jt] = mfma16(lds16(L + R_KS + (16 * jt + l15) * QP + (32 * ks + 8 * g4) * 2), qf[ks], accS[jt]); }
;         const int il = 16 * nt + l15;
; #pragma unroll
;         for (int jt = 0; jt < 4; ++jt) { const int j0 = 16 * jt + 4 * g4;
;             accS[jt].x *= ex2(fabsf((float)(il - j0)) * l2g); accS[jt].y *= ex2(fabsf((float)(il - j0 - 1)) * l2g);
;             accS[jt].z *= ex2(fabsf((float)(il - j0 - 2)) * l2g); accS[jt].w *= ex2(fabsf((float)(il - j0 - 3)) * l2g); }
;         bf16x8 pS[2]; pS[0] = pack8(accS[0], accS[1]); pS[1] = pack8(accS[2], accS[3]);
;         const float qdec = ex2((float)(il + 1) * l2g);
;         const size_t orow = (size_t)(rowb + ch * 64 + il);
;         float ssq = 0.f;
; #pragma unroll
;         for (int mi = 0; mi < 2; ++mi) { const int mt = mtb + mi; const int cb = (16 * mt + 4 * (l15 & 3)) * 2;
;             f32x4 aI = (f32x4){0.f, 0.f, 0.f, 0.f}, aC = (f32x4){0.f, 0.f, 0.f, 0.f};
; #pragma unroll
;             for (int kk = 0; kk < 2; ++kk) { lptr v0 = L + R_VS + (32 * kk + 4 * g4 + (l15 >> 2)) * VP2 + cb; aI = mfma16(tr_pair(v0, v0 + 16 * VP2), pS[kk], aI); }
; #pragma unroll
;             for (int ks = 0; ks < 8; ++ks) { lptr s0 = L + R_ST + (32 * ks + 8 * g4 + (l15 >> 2)) * VP + cb; aC = mfma16(tr_pair(s0, s0 + 4 * VP), qf[ks], aC); }
.LBB0_565:
	ds_read_b128 v[72:75], v197 offset:33792
	ds_read_b128 v[100:103], v196
	ds_read_b128 v[96:99], v196 offset:64
	ds_read_b128 v[76:79], v197 offset:33856
	ds_read_b128 v[80:83], v197 offset:42240
	ds_read_b128 v[214:217], v197 offset:42304
	v_add_u32_e32 v0, v188, v187
	s_waitcnt lgkmcnt(4)
	v_mfma_f32_16x16x32_bf16 v[72:75], v[72:75], v[100:103], 0
	s_andn2_b64 vcc, exec, s[0:1]
	s_waitcnt lgkmcnt(1)
	v_mfma_f32_16x16x32_bf16 v[218:221], v[80:83], v[100:103], 0
	ds_read_b128 v[80:83], v197 offset:33920
	ds_read_b128 v[88:91], v197 offset:33984
	ds_read_b128 v[92:95], v196 offset:128
	ds_read_b128 v[84:87], v196 offset:192
	v_mfma_f32_16x16x32_bf16 v[72:75], v[76:79], v[96:99], v[72:75]
	s_waitcnt lgkmcnt(1)
	v_mfma_f32_16x16x32_bf16 v[72:75], v[80:83], v[92:95], v[72:75]
	ds_read_b128 v[80:83], v197 offset:34048
	ds_read_b128 v[222:225], v197 offset:34112
	s_waitcnt lgkmcnt(2)
	v_mfma_f32_16x16x32_bf16 v[72:75], v[88:91], v[84:87], v[72:75]
	ds_read_b128 v[88:91], v196 offset:256
	ds_read_b128 v[76:79], v196 offset:320
	ds_read_b128 v[226:229], v197 offset:34176
	ds_read_b128 v[230:233], v197 offset:34240
	s_waitcnt lgkmcnt(3)
	v_mfma_f32_16x16x32_bf16 v[72:75], v[80:83], v[88:91], v[72:75]
	s_waitcnt lgkmcnt(2)
	v_mfma_f32_16x16x32_bf16 v[222:225], v[222:225], v[76:79], v[72:75]
	ds_read_b128 v[80:83], v196 offset:384
	s_nop 4
	ds_read_b128 v[72:75], v196 offset:448
	ds_read_b128 v[234:237], v198 offset:33920
	s_waitcnt lgkmcnt(2)
	v_mfma_f32_16x16x32_bf16 v[222:225], v[226:229], v[80:83], v[222:225]
	ds_read_b128 v[226:229], v197 offset:42368
	v_mfma_f32_16x16x32_bf16 v[214:217], v[214:217], v[96:99], v[218:221]
	s_nop 2
	ds_read_b128 v[218:221], v197 offset:42432
	s_waitcnt lgkmcnt(1)
	v_mfma_f32_16x16x32_bf16 v[214:217], v[226:229], v[92:95], v[214:217]
	ds_read_b128 v[226:229], v197 offset:42496
	s_waitcnt lgkmcnt(1)
	v_mfma_f32_16x16x32_bf16 v[214:217], v[218:221], v[84:87], v[214:217]
	ds_read_b128 v[218:221], v197 offset:42560
	s_waitcnt lgkmcnt(1)
	v_mfma_f32_16x16x32_bf16 v[214:217], v[226:229], v[88:91], v[214:217]
	ds_read_b128 v[226:229], v197 offset:42624
	s_waitcnt lgkmcnt(1)
	v_mfma_f32_16x16x32_bf16 v[214:217], v[218:221], v[76:79], v[214:217]
	ds_read_b128 v[218:221], v197 offset:42688
	s_waitcnt lgkmcnt(1)
	v_mfma_f32_16x16x32_bf16 v[214:217], v[226:229], v[80:83], v[214:217]
	ds_read_b128 v[226:229], v197 offset:50688
	s_waitcnt lgkmcnt(1)
	v_mfma_f32_16x16x32_bf16 v[214:217], v[218:221], v[72:75], v[214:217]
	ds_read_b128 v[218:221], v197 offset:50752
	v_mfma_f32_16x16x32_bf16 v[222:225], v[230:233], v[72:75], v[222:225]
	ds_read_b128 v[230:233], v197 offset:50816
	s_nop 4
	v_pk_mul_f32 v[250:251], v[140:141], v[214:215]
	v_pk_mul_f32 v[252:253], v[142:143], v[216:217]
	s_waitcnt lgkmcnt(2)
	v_mfma_f32_16x16x32_bf16 v[226:229], v[226:229], v[100:103], 0
	s_waitcnt lgkmcnt(1)
	v_mfma_f32_16x16x32_bf16 v[218:221], v[218:221], v[96:99], v[226:229]
	v_mul_f32_e64 v246, v136, v222
	v_mul_f32_e64 v247, v137, v223
	v_pk_mul_f32 v[248:249], v[138:139], v[224:225]
	s_nop 2
	ds_read_b128 v[226:229], v197 offset:50880
	s_waitcnt lgkmcnt(1)
	v_mfma_f32_16x16x32_bf16 v[218:221], v[230:233], v[92:95], v[218:221]
	ds_read_b128 v[230:233], v197 offset:50944
	s_waitcnt lgkmcnt(1)
	v_mfma_f32_16x16x32_bf16 v[218:221], v[226:229], v[84:87], v[218:221]
	ds_read_b128 v[226:229], v197 offset:51008
	s_waitcnt lgkmcnt(1)
	v_mfma_f32_16x16x32_bf16 v[218:221], v[230:233], v[88:91], v[218:221]
	ds_read_b128 v[230:233], v197 offset:51072
	s_waitcnt lgkmcnt(1)
	v_mfma_f32_16x16x32_bf16 v[218:221], v[226:229], v[76:79], v[218:221]
	ds_read_b128 v[226:229], v197 offset:51136
	s_waitcnt lgkmcnt(1)
	v_mfma_f32_16x16x32_bf16 v[218:221], v[230:233], v[80:83], v[218:221]
	ds_read_b128 v[230:233], v198 offset:33792
	s_waitcnt lgkmcnt(1)
	v_mfma_f32_16x16x32_bf16 v[218:221], v[226:229], v[72:75], v[218:221]
	ds_read_b128 v[226:229], v198 offset:33856
	s_waitcnt lgkmcnt(1)
	v_mfma_f32_16x16x32_bf16 v[230:233], v[230:233], v[100:103], 0
	s_waitcnt lgkmcnt(0)
	v_mfma_f32_16x16x32_bf16 v[226:229], v[226:229], v[96:99], v[230:233]
	s_nop 5
	ds_read_b128 v[230:233], v198 offset:33984
	v_mfma_f32_16x16x32_bf16 v[226:229], v[234:237], v[92:95], v[226:229]
	ds_read_b128 v[234:237], v198 offset:34048
	s_waitcnt lgkmcnt(1)
	v_mfma_f32_16x16x32_bf16 v[226:229], v[230:233], v[84:87], v[226:229]
	ds_read_b128 v[230:233], v198 offset:34112
	ds_read_b128 v[238:241], v198 offset:34176
	ds_read_b128 v[242:245], v198 offset:34240
	ds_read_b64_tr_b16 v[214:215], v200
	ds_read_b64_tr_b16 v[216:217], v200 offset:576
	s_waitcnt lgkmcnt(5)
	v_mfma_f32_16x16x32_bf16 v[226:229], v[234:237], v[88:91], v[226:229]
	s_waitcnt lgkmcnt(4)
	v_mfma_f32_16x16x32_bf16 v[222:225], v[230:233], v[76:79], v[226:229]
	s_nop 5
	ds_read_b64_tr_b16 v[226:227], v200 offset:4608
	ds_read_b64_tr_b16 v[228:229], v200 offset:5184
	s_waitcnt lgkmcnt(2)
; DI float bf_lo(unsigned w) { return __uint_as_float(w << 16); }
; DI float bf_hi(unsigned w) { return __uint_as_float(w & 0xffff0000u); }
; DI float dot4(f32x4 a) { return (a.x * a.x + a.y * a.y) + (a.z * a.z + a.w * a.w); }
; DI bf16x8 tr_pair(lptr p0, lptr p1) { const s16x4 a = ldstr(p0), b = ldstr(p1); return (bf16x8){a.x, a.y, a.z, a.w, b.x, b.y, b.z, b.w}; }
; DI u32x2 pack4(f32x4 a) { u32x2 w; w.x = cvt_pk_bf16(a.x, a.y); w.y = cvt_pk_bf16(a.z, a.w); return w; }
; DI f32x4 mfma16(bf16x8 a, bf16x8 b, f32x4 c) { return __builtin_amdgcn_mfma_f32_16x16x32_bf16(a, b, c, 0, 0, 0); }
;     ...
;             for (int kk = 0; kk < 2; ++kk) { lptr v0 = L + R_VS + (32 * kk + 4 * g4 + (l15 >> 2)) * VP2 + cb; aI = mfma16(tr_pair(v0, v0 + 16 * VP2), pS[kk], aI); }
; #pragma unroll
;             for (int ks = 0; ks < 8; ++ks) { lptr s0 = L + R_ST + (32 * ks + 8 * g4 + (l15 >> 2)) * VP + cb; aC = mfma16(tr_pair(s0, s0 + 4 * VP), qf[ks], aC); }
;             const f32x4 o = aI + aC * qdec;
;             const f32x4 og = (f32x4){o.x * bf_lo(rgc[mi].x), o.y * bf_hi(rgc[mi].x), o.z * bf_lo(rgc[mi].y), o.w * bf_hi(rgc[mi].y)};
;             if (!dry || o.x == 1.2345e30f) *(u32x2*)(Vb + ((unsigned)ch * 65536u + ooff + 16 * mi)) = pack4(og);
;             ssq += dot4(o); }
;         if (ch + 1 < nch) gload_rg(ch + 1);
;         ssq += __shfl_xor(ssq, 16); ssq += __shfl_xor(ssq, 32);
;         if (g4 == 0 && (!dry || ssq == 1.2345e30f)) unsafeAtomicAdd(ssqr + orow * 4 + h, ssq);
	v_mfma_f32_16x16x32_bf16 v[214:217], v[214:217], v[100:103], 0
	v_mfma_f32_16x16x32_bf16 v[222:225], v[238:241], v[80:83], v[222:225]
	v_mul_f32_e64 v238, v144, v218
	v_mul_f32_e64 v239, v145, v219
	ds_read_b64_tr_b16 v[230:231], v200 offset:9216
	ds_read_b64_tr_b16 v[232:233], v200 offset:9792
	ds_read_b64_tr_b16 v[218:219], v200 offset:32832
	ds_read_b64_tr_b16 v[234:235], v200 offset:13824
	ds_read_b64_tr_b16 v[236:237], v200 offset:14400
	s_waitcnt lgkmcnt(5)
	v_mfma_f32_16x16x32_bf16 v[214:217], v[226:229], v[96:99], v[214:217]
	v_mul_f32_e64 v240, v146, v220
	v_mul_f32_e64 v241, v147, v221
	v_cvt_pk_bf16_f32 v228, v246, v247
	v_cvt_pk_bf16_f32 v229, v248, v249
	v_mfma_f32_16x16x32_bf16 v[222:225], v[242:245], v[72:75], v[222:225]
	s_waitcnt lgkmcnt(3)
	v_mfma_f32_16x16x32_bf16 v[214:217], v[230:233], v[92:95], v[214:217]
	v_cvt_pk_bf16_f32 v230, v250, v251
	s_nop 4
	v_pk_mul_f32 v[242:243], v[148:149], v[222:223]
	ds_read_b64_tr_b16 v[220:221], v200 offset:18432
	ds_read_b64_tr_b16 v[222:223], v200 offset:19008
	s_waitcnt lgkmcnt(2)
	v_mfma_f32_16x16x32_bf16 v[214:217], v[234:237], v[84:87], v[214:217]
	v_mul_f32_e64 v244, v150, v224
	v_mul_f32_e64 v245, v151, v225
	ds_read_b64_tr_b16 v[224:225], v200 offset:23040
	ds_read_b64_tr_b16 v[226:227], v200 offset:23616
	ds_read_b64_tr_b16 v[232:233], v200 offset:27648
	ds_read_b64_tr_b16 v[234:235], v200 offset:28224
	s_waitcnt lgkmcnt(4)
	v_mfma_f32_16x16x32_bf16 v[220:223], v[220:223], v[88:91], v[214:217]
	v_cvt_pk_bf16_f32 v231, v252, v253
	s_nop 1
	ds_read_b64_tr_b16 v[216:217], v200 offset:32256
	s_waitcnt lgkmcnt(3)
	v_mfma_f32_16x16x32_bf16 v[220:223], v[224:227], v[76:79], v[220:223]
	ds_read_b64_tr_b16 v[224:225], v199
	ds_read_b64_tr_b16 v[226:227], v199 offset:2560
	v_cvt_pk_bf16_f32 v214, v238, v239
	v_cvt_pk_bf16_f32 v215, v240, v241
	s_waitcnt lgkmcnt(3)
	v_mfma_f32_16x16x32_bf16 v[220:223], v[232:235], v[80:83], v[220:223]
	ds_read_b64_tr_b16 v[232:233], v199 offset:5120
	ds_read_b64_tr_b16 v[234:235], v199 offset:7680
	ds_read_b64_tr_b16 v[236:237], v0
	ds_read_b64_tr_b16 v[238:239], v0 offset:576
	v_add_u32_e32 v0, s30, v108
	s_waitcnt lgkmcnt(6)
	v_mfma_f32_16x16x32_bf16 v[218:221], v[216:219], v[72:75], v[220:223]
	v_cvt_pk_bf16_f32 v216, v242, v243
	v_cvt_pk_bf16_f32 v217, v244, v245
	s_waitcnt lgkmcnt(4)
	v_mfma_f32_16x16x32_bf16 v[222:225], v[224:227], v[228:231], 0
	s_waitcnt lgkmcnt(0)
	v_mfma_f32_16x16x32_bf16 v[100:103], v[236:239], v[100:103], 0
	v_mfma_f32_16x16x32_bf16 v[222:225], v[232:235], v[214:217], v[222:225]
	ds_read_b64_tr_b16 v[232:233], v203
	ds_read_b64_tr_b16 v[234:235], v203 offset:576
	ds_read_b64_tr_b16 v[240:241], v204 offset:9216
	ds_read_b64_tr_b16 v[242:243], v204 offset:9792
	ds_read_b64_tr_b16 v[236:237], v204 offset:13824
	ds_read_b64_tr_b16 v[238:239], v204 offset:14400
	s_waitcnt lgkmcnt(4)
	v_mfma_f32_16x16x32_bf16 v[96:99], v[232:235], v[96:99], v[100:103]
	s_nop 2
	ds_read_b64_tr_b16 v[100:101], v204 offset:18432
	ds_read_b64_tr_b16 v[102:103], v204 offset:19008
	ds_read_b64_tr_b16 v[226:227], v204 offset:32832
	ds_read_b64_tr_b16 v[232:233], v204 offset:23040
	ds_read_b64_tr_b16 v[234:235], v204 offset:23616
	s_waitcnt lgkmcnt(7)
	v_mfma_f32_16x16x32_bf16 v[94:97], v[240:243], v[92:95], v[96:99]
	v_fma_f32 v92, v132, v220, v224
	v_fma_f32 v93, v133, v221, v225
	s_waitcnt lgkmcnt(5)
	v_mfma_f32_16x16x32_bf16 v[94:97], v[236:239], v[84:87], v[94:97]
	v_fma_f32 v84, v2, v218, v222
	v_fma_f32 v85, v3, v219, v223
	ds_read_b64_tr_b16 v[218:219], v204 offset:27648
	ds_read_b64_tr_b16 v[220:221], v204 offset:28224
	ds_read_b64_tr_b16 v[224:225], v204 offset:32256
	s_waitcnt lgkmcnt(6)
	v_mfma_f32_16x16x32_bf16 v[86:89], v[100:103], v[88:91], v[94:97]
	s_cbranch_vccnz .Lret_wa_last
	s_waitcnt vmcnt(10)
	s_branch .Lret_wa_done
.Lret_wa_last:
	s_waitcnt vmcnt(1)
.Lret_wa_done:
	v_lshlrev_b32_e32 v90, 16, v124
	v_and_b32_e32 v91, 0xffff0000, v124
	v_pk_mul_f32 v[90:91], v[84:85], v[90:91]
	s_waitcnt lgkmcnt(3)
	v_mfma_f32_16x16x32_bf16 v[76:79], v[232:235], v[76:79], v[86:89]
	s_nop 2
	ds_read_b64_tr_b16 v[86:87], v201
	ds_read_b64_tr_b16 v[88:89], v201 offset:2560
	v_lshlrev_b32_e32 v94, 16, v125
	v_and_b32_e32 v95, 0xffff0000, v125
	s_waitcnt lgkmcnt(3)
	v_mfma_f32_16x16x32_bf16 v[76:79], v[218:221], v[80:83], v[76:79]
	ds_read_b64_tr_b16 v[80:81], v202 offset:5120
	ds_read_b64_tr_b16 v[82:83], v202 offset:7680
	s_waitcnt lgkmcnt(2)
	v_mfma_f32_16x16x32_bf16 v[86:89], v[86:89], v[228:231], 0
	v_mfma_f32_16x16x32_bf16 v[74:77], v[224:227], v[72:75], v[76:79]
	v_mul_f32_e64 v72, v92, v94
	v_mul_f32_e64 v73, v93, v95
	s_nop 0
	v_cvt_pk_bf16_f32 v78, v90, v91
	v_cvt_pk_bf16_f32 v79, v72, v73
	v_lshl_add_u64 v[90:91], v[0:1], 1, s[14:15]
	global_store_dwordx2 v[90:91], v[78:79], off
	s_waitcnt lgkmcnt(0)
	v_mfma_f32_16x16x32_bf16 v[78:81], v[80:83], v[214:217], v[86:89]
	s_nop 7
	v_pk_fma_f32 v[72:73], v[132:133], v[76:77], v[80:81]
	v_pk_fma_f32 v[74:75], v[2:3], v[74:75], v[78:79]
	s_cbranch_vccnz .Lret_wb_last
	s_waitcnt vmcnt(10)
	s_branch .Lret_wb_done

; DI float bf_lo(unsigned w) { return __uint_as_float(w << 16); }
; DI float bf_hi(unsigned w) { return __uint_as_float(w & 0xffff0000u); }
; DI float dot4(f32x4 a) { return (a.x * a.x + a.y * a.y) + (a.z * a.z + a.w * a.w); }
; DI u32x2 pack4(f32x4 a) { u32x2 w; w.x = cvt_pk_bf16(a.x, a.y); w.y = cvt_pk_bf16(a.z, a.w); return w; }
;     ...
;             const f32x4 og = (f32x4){o.x * bf_lo(rgc[mi].x), o.y * bf_hi(rgc[mi].x), o.z * bf_lo(rgc[mi].y), o.w * bf_hi(rgc[mi].y)};
;             if (!dry || o.x == 1.2345e30f) *(u32x2*)(Vb + ((unsigned)ch * 65536u + ooff + 16 * mi)) = pack4(og);
;             ssq += dot4(o); }
;         if (ch + 1 < nch) gload_rg(ch + 1);
.Lret_wb_done:
	v_lshlrev_b32_e32 v76, 16, v126
	v_and_b32_e32 v77, 0xffff0000, v126
	v_lshlrev_b32_e32 v78, 16, v127
	v_and_b32_e32 v79, 0xffff0000, v127
	v_pk_mul_f32 v[76:77], v[74:75], v[76:77]
	v_pk_mul_f32 v[78:79], v[72:73], v[78:79]
	v_cvt_pk_bf16_f32 v76, v76, v77
	v_cvt_pk_bf16_f32 v77, v78, v79
	global_store_dwordx2 v[90:91], v[76:77], off offset:32
	s_cbranch_vccnz .LBB0_567
	v_add_u32_e32 v0, 0x10000, v0
	v_lshl_add_u64 v[76:77], v[0:1], 1, s[16:17]
	v_lshl_add_u64 v[78:79], s[94:95], 0, v[156:157]
	global_load_dwordx2 v[124:125], v[76:77], off
	global_load_dwordx2 v[126:127], v[78:79], off

; __global__ void __launch_bounds__(512, 2) fwd_mega(Params p) {
;     ...
;     if (IN(9)) {
;         pg8::Gemm g{P + G_RQ, DM, (const bf16_t*)(ws + WS_WGU), MP, 2 * DFF, DM}; pg8::StaticOrder S; S.init(MP, 2 * DFF, G, cb);
;         EpiGateUp E{P, (const float*)(ws + WS_SSQ3)}; pg8::gemm_phase<EpiGateUp, true>(L, g, S, E);
.LBB0_1271:
	s_cmp_lt_i32 s66, 10
	s_cselect_b64 s[2:3], -1, 0
	s_and_b64 s[4:5], s[2:3], s[0:1]
	s_andn2_b64 vcc, exec, s[4:5]
	s_cbranch_vccnz .LBB0_1305
	s_and_b32 s98, s64, 7
	s_cmp_eq_u32 s98, 0
	s_cbranch_scc1 .Lstg9_done

; #define PG8_WAIT_V(n) asm volatile("s_waitcnt vmcnt(" #n ")" ::: "memory")
; #define PG8_BAR __builtin_amdgcn_s_barrier()
; template <class Epi, bool ALIGN_EPI>
; DI void gemm_phase(lptr lds, const Gemm g, const StaticOrder& S, const Epi& E) {
;     const int tid = threadIdx.x, wid = __builtin_amdgcn_readfirstlane(tid >> 6), lane = tid & 63, wr = wid >> 2, wc = wid & 3, fr = lane & 15, fq = lane >> 4;
;     const int K = g.K, nt = K / BK, lda = g.lda;
;     unsigned voffA[2], voffB[2];
; #pragma unroll
;     for (int i = 0; i < 2; ++i) { int R, C; stage_rc(tid * 16 + i * 8192, R, C); const int Rb = (R & ~31) + perm32(R & 31);
;         voffA[i] = (unsigned)(R * lda + C) * 2u; voffB[i] = (unsigned)(Rb * K + C) * 2u; }
;     const size_t kstep = (size_t)(BK * 2);
;     const size_t hstepA = (size_t)HALF * lda * 2, hstepB = (size_t)HALF * K * 2, tstepA = 2 * hstepA, tstepB = 2 * hstepB;
;     const unsigned ldsw = (unsigned)wid * 1024u;
;     const int aoff = lds_byte(wr * 64 + fr, fq * 8), boff = lds_byte(wc * 32 + fr, fq * 8);
;     ...
;     Unit cur, nxt; int ui = 0;
;     if (!S.next(0, cur)) return;
;     f32x4 acc[2][2][4][2];
; #pragma unroll
;     for (int a = 0; a < 2; ++a)
; #pragma unroll
;         for (int b = 0; b < 2; ++b)
; #pragma unroll
;             for (int m = 0; m < 4; ++m)
; #pragma unroll
;                 for (int n = 0; n < 2; ++n) acc[a][b][m][n] = (f32x4){0.f, 0.f, 0.f, 0.f};
;     bf16x8 At[4][2], B0[2][2], B1[2][2];
;     const char* cA = (const char*)g.A + (size_t)cur.pm * tstepA; const char* cB = (const char*)g.Bt + (size_t)cur.pn * tstepB;
;     if constexpr (Epi::RESCALE) E.prep(cur, tid);
;     PG8_STAGE(PG8_SB(0, 0), cB, voffB); PG8_STAGE(PG8_SB(0, 1), cB + hstepB, voffB); PG8_STAGE(PG8_SA(0, 0), cA, voffA); PG8_STAGE(PG8_SA(0, 1), cA + hstepA, voffA);
;     if (wr == 1) PG8_BAR;
;     PG8_WAIT_V(2); PG8_BAR;
;     PG8_STAGE(PG8_SB(1, 0), cB + kstep, voffB); PG8_STAGE(PG8_SA(1, 0), cA + kstep, voffA); PG8_STAGE(PG8_SB(1, 1), cB + hstepB + kstep, voffB);
;     PG8_WAIT_V(6); PG8_BAR;
; __global__ void __launch_bounds__(512, 2) fwd_mega(Params p) {
;     ...
;         pg8::Gemm g{P + G_RQ, DM, (const bf16_t*)(ws + WS_WGU), MP, 2 * DFF, DM}; pg8::StaticOrder S; S.init(MP, 2 * DFF, G, cb);
;         EpiGateUp E{P, (const float*)(ws + WS_SSQ3)}; pg8::gemm_phase<EpiGateUp, true>(L, g, S, E);
.Lstg9_done:
	s_add_u32 s0, s94, 0x1e80000
	s_addc_u32 s1, s95, 0
	s_add_u32 s6, s94, 0x145000
	s_addc_u32 s7, s95, 0
	s_waitcnt vmcnt(0)
	v_lshrrev_b32_e32 v0, 1, v153
	v_readfirstlane_b32 s3, v153
	v_lshlrev_b32_e32 v162, 4, v153
	v_lshrrev_b32_e32 v168, 3, v153
	v_and_b32_e32 v161, 15, v153
	s_cmpk_gt_i32 s64, 0x15ff
	v_and_b32_e32 v160, 24, v0
	s_cbranch_scc1 .LBB0_1288
	v_lshrrev_b32_e32 v0, 5, v153
	v_and_b32_e32 v0, 4, v0
	s_waitcnt lgkmcnt(0)
	v_bfe_u32 v1, v153, 2, 2
	v_add_u32_e32 v8, 0x2000, v162
	v_or3_b32 v0, v0, v1, v160
	v_lshrrev_b32_e32 v1, 7, v8
	s_movk_i32 s2, 0xe0
	v_and_or_b32 v2, v1, s2, v0
	v_and_b32_e32 v3, 32, v153
	v_bfe_u32 v11, v153, 2, 4
	s_movk_i32 s2, 0xf0
	v_bitop3_b32 v9, v162, v3, 48 bitop3:0x6c
	v_and_b32_e32 v10, 64, v153
	v_and_or_b32 v1, v1, s2, v11
	s_movk_i32 s2, 0x60
	v_or_b32_e32 v3, v9, v10
	v_and_or_b32 v0, v168, s2, v0
	s_movk_i32 s2, 0x70
	s_ashr_i32 s31, s64, 31
	v_lshl_or_b32 v132, v0, 11, v3
	v_and_or_b32 v0, v168, s2, v11
	s_lshr_b32 s2, s31, 29
	s_add_i32 s2, s64, s2
	s_lshr_b32 s13, s3, 6
	s_ashr_i32 s8, s2, 3
	s_and_b32 s2, s2, -8
	s_lshr_b32 s12, s3, 8
	s_lshl_b32 s30, s13, 10
	s_sub_i32 s2, s64, s2
	s_cmp_lt_i32 s2, 0
	s_movk_i32 s34, 0x2c1
	s_cselect_b32 s9, s34, 0x2c0
	s_mul_i32 s2, s2, s9
	s_add_i32 s2, s2, s8
	s_mul_hi_i32 s8, s2, 0x2e8ba2e9
	s_lshr_b32 s9, s8, 31
	s_ashr_i32 s8, s8, 5
	s_add_i32 s8, s8, s9
	s_lshl_b32 s9, s8, 3
	s_mulk_i32 s8, 0xb0
	s_sub_i32 s8, s2, s8
	s_sext_i32_i16 s2, s8
	s_bfe_u32 s2, s2, 0x3001c
	s_add_i32 s10, s8, s2
	s_sext_i32_i16 s2, s10
	s_and_b32 s10, s10, 0xfff8
	s_sub_i32 s8, s8, s10
	s_sext_i32_i16 s8, s8
	s_lshr_b32 s2, s2, 3
	s_add_i32 s10, s9, s8
	s_ashr_i32 s11, s10, 31
	s_bfe_i64 s[14:15], s[2:3], 0x100000
	s_lshl_b64 s[8:9], s[10:11], 19
	s_lshl_b64 s[14:15], s[14:15], 19
	s_add_u32 s26, s0, s14
	s_addc_u32 s27, s1, s15
	s_add_i32 s35, s30, 0
	s_add_i32 m0, s35, 0x10000
	v_lshl_or_b32 v128, v2, 11, v3
	global_load_lds_dwordx4 v132, s[26:27]
	s_add_i32 m0, s35, 0x12000
	s_add_u32 s14, s26, 0x40000
	global_load_lds_dwordx4 v128, s[26:27]
	s_addc_u32 s15, s27, 0
	s_add_i32 m0, s35, 0x14000
	v_lshl_or_b32 v134, v0, 11, v3
	global_load_lds_dwordx4 v132, s[14:15]
	s_add_i32 m0, s35, 0x16000
	s_add_u32 s24, s82, s8
	s_addc_u32 s25, s83, s9
	s_add_i32 s36, s35, 0x2000
	global_load_lds_dwordx4 v128, s[14:15]
	s_mov_b32 m0, s35
	s_add_u32 s8, s24, 0x40000
	v_lshl_or_b32 v130, v1, 11, v3
	global_load_lds_dwordx4 v134, s[24:25]
	s_mov_b32 m0, s36
	s_addc_u32 s9, s25, 0
	s_add_i32 s37, s35, 0x4000
	global_load_lds_dwordx4 v130, s[24:25]
	s_mov_b32 m0, s37
	s_add_i32 s38, s35, 0x6000
	global_load_lds_dwordx4 v134, s[8:9]
	s_mov_b32 m0, s38
	v_mov_b32_e32 v133, 0
	global_load_lds_dwordx4 v130, s[8:9]
	v_mov_b32_e32 v129, v133
	v_mov_b32_e32 v135, v133
	v_mov_b32_e32 v131, v133
	s_cmp_eq_u32 s12, 1
	s_mov_b32 s39, 0
	v_lshl_add_u64 v[6:7], s[26:27], 0, v[132:133]
	v_lshl_add_u64 v[4:5], s[26:27], 0, v[128:129]
	v_lshl_add_u64 v[0:1], s[24:25], 0, v[134:135]
	s_cselect_b64 s[8:9], -1, 0
	s_cmp_lg_u32 s12, 1
	v_lshl_add_u64 v[2:3], s[24:25], 0, v[130:131]
	s_cbranch_scc1 .LBB0_1275
	s_barrier

; #define PG8_STAGE(bufoff, gbase, voff) do { _Pragma("unroll") for (int _i = 0; _i < 2; ++_i) \
;         __builtin_amdgcn_global_load_lds((const unsigned*)((const char*)(gbase) + (voff)[_i]), (LAS unsigned*)(lds + (bufoff) + ldsw + _i * 8192), 16, 0, 0); } while (0)
; #define PG8_LDA(dst, b, h) do { _Pragma("unroll") for (int m = 0; m < 4; ++m) _Pragma("unroll") for (int k = 0; k < 2; ++k) dst[m][k] = *(const LAS bf16x8*)(lds + PG8_SA(b, h) + aoff + m * 2048 + k * 1024); } while (0)
; #define PG8_LDB(dst, b, h) do { _Pragma("unroll") for (int n = 0; n < 2; ++n) _Pragma("unroll") for (int k = 0; k < 2; ++k) dst[n][k] = *(const LAS bf16x8*)(lds + PG8_SB(b, h) + boff + n * 2048 + k * 1024); } while (0)
; #define PG8_MMA(ai, bj, At, Bt) do { __builtin_amdgcn_s_setprio(1); _Pragma("unroll") for (int m = 0; m < 4; ++m) _Pragma("unroll") for (int n = 0; n < 2; ++n) _Pragma("unroll") for (int k = 0; k < 2; ++k) \
;         acc[ai][bj][m][n] = __builtin_amdgcn_mfma_f32_16x16x32_bf16(Bt[n][k], At[m][k], acc[ai][bj][m][n], 0, 0, 0); __builtin_amdgcn_s_setprio(0); } while (0)
; #define PG8_WAIT_V(n) asm volatile("s_waitcnt vmcnt(" #n ")" ::: "memory")
; #define PG8_WAIT_L(n) asm volatile("s_waitcnt lgkmcnt(" #n ")" ::: "memory")
; #define PG8_BAR __builtin_amdgcn_s_barrier()
; #define PG8_SCHED __builtin_amdgcn_sched_barrier(0)
; template <class Epi, bool ALIGN_EPI>
; DI void gemm_phase(lptr lds, const Gemm g, const StaticOrder& S, const Epi& E) {
;     ...
;             PG8_LDB(B0, 0, 0); PG8_LDB(B1, 0, 1); PG8_SCHED; PG8_LDA(At, 0, 0); PG8_STAGE(PG8_SA(1, 1), a1 + hstepA, voffA);
;             PG8_WAIT_V(8); PG8_WAIT_L(0); PG8_BAR; PG8_MMA(0, 0, At, B0); PG8_MMA(0, 1, At, B1); PG8_BAR; PG8_SCHED;
;             PG8_LDA(At, 0, 1); PG8_STAGE(PG8_SB(0, 0), b2, voffB); PG8_STAGE(PG8_SB(0, 1), b2 + hstepB, voffB); PG8_STAGE(PG8_SA(0, 0), a2, voffA);
;             PG8_WAIT_V(8); PG8_WAIT_L(0); PG8_BAR; PG8_MMA(1, 0, At, B0); PG8_MMA(1, 1, At, B1); PG8_BAR; PG8_SCHED;
.LBB0_1281:
	ds_read_b128 v[144:147], v166
	ds_read_b128 v[148:151], v166 offset:1024
	ds_read_b128 v[154:157], v166 offset:2048
	ds_read_b128 v[172:175], v166 offset:3072
	ds_read_b128 v[176:179], v167
	ds_read_b128 v[180:183], v167 offset:1024
	ds_read_b128 v[184:187], v167 offset:2048
	ds_read_b128 v[188:191], v167 offset:3072
	s_add_u32 s26, s24, 0xfffc0080
	s_addc_u32 s27, s25, -1
	s_cmp_eq_u32 s52, 12
	s_cselect_b32 s29, s19, s27
	s_cselect_b32 s28, s48, s26
	s_cselect_b32 s27, s17, s51
	s_cselect_b32 s26, s49, s50
	v_lshl_add_u64 v[158:159], s[24:25], 0, v[136:137]
	s_add_i32 m0, s35, 0xc000
	ds_read_b128 v[192:195], v169
	ds_read_b128 v[196:199], v169 offset:1024
	ds_read_b128 v[200:203], v169 offset:2048
	ds_read_b128 v[204:207], v169 offset:3072
	ds_read_b128 v[208:211], v169 offset:4096
	ds_read_b128 v[212:215], v169 offset:5120
	ds_read_b128 v[216:219], v169 offset:6144
	ds_read_b128 v[220:223], v169 offset:7168
	global_load_lds_dwordx4 v[158:159], off
	v_lshl_add_u64 v[158:159], s[24:25], 0, v[138:139]
	s_add_i32 m0, s35, 0xe000
	s_nop 0
	global_load_lds_dwordx4 v[158:159], off
	s_waitcnt vmcnt(8)
	s_waitcnt lgkmcnt(0)
	s_barrier
	s_setprio 1
	s_waitcnt lgkmcnt(0)
	v_mfma_f32_16x16x32_bf16 v[124:127], v[144:147], v[192:195], v[124:127]
	v_mfma_f32_16x16x32_bf16 v[120:123], v[154:157], v[192:195], v[120:123]
	v_mfma_f32_16x16x32_bf16 v[116:119], v[144:147], v[200:203], v[116:119]
	v_mfma_f32_16x16x32_bf16 v[112:115], v[154:157], v[200:203], v[112:115]
	v_mfma_f32_16x16x32_bf16 v[92:95], v[144:147], v[208:211], v[92:95]
	v_mfma_f32_16x16x32_bf16 v[88:91], v[154:157], v[208:211], v[88:91]
	v_mfma_f32_16x16x32_bf16 v[76:79], v[144:147], v[216:219], v[76:79]
	v_mfma_f32_16x16x32_bf16 v[72:75], v[154:157], v[216:219], v[72:75]
	v_mfma_f32_16x16x32_bf16 v[124:127], v[148:151], v[196:199], v[124:127]
	v_mfma_f32_16x16x32_bf16 v[120:123], v[172:175], v[196:199], v[120:123]
	v_mfma_f32_16x16x32_bf16 v[116:119], v[148:151], v[204:207], v[116:119]
	v_mfma_f32_16x16x32_bf16 v[112:115], v[172:175], v[204:207], v[112:115]
	v_mfma_f32_16x16x32_bf16 v[92:95], v[148:151], v[212:215], v[92:95]
	v_mfma_f32_16x16x32_bf16 v[88:91], v[172:175], v[212:215], v[88:91]
	v_mfma_f32_16x16x32_bf16 v[76:79], v[148:151], v[220:223], v[76:79]
	v_mfma_f32_16x16x32_bf16 v[72:75], v[172:175], v[220:223], v[72:75]
	s_setprio 0
	s_setprio 1
	v_mfma_f32_16x16x32_bf16 v[108:111], v[176:179], v[192:195], v[108:111]
	v_mfma_f32_16x16x32_bf16 v[104:107], v[184:187], v[192:195], v[104:107]
	v_mfma_f32_16x16x32_bf16 v[100:103], v[176:179], v[200:203], v[100:103]
	v_mfma_f32_16x16x32_bf16 v[96:99], v[184:187], v[200:203], v[96:99]
	v_mfma_f32_16x16x32_bf16 v[84:87], v[176:179], v[208:211], v[84:87]
	v_mfma_f32_16x16x32_bf16 v[80:83], v[184:187], v[208:211], v[80:83]
	v_mfma_f32_16x16x32_bf16 v[68:71], v[176:179], v[216:219], v[68:71]
	v_mfma_f32_16x16x32_bf16 v[64:67], v[184:187], v[216:219], v[64:67]
	v_mfma_f32_16x16x32_bf16 v[108:111], v[180:183], v[196:199], v[108:111]
	v_mfma_f32_16x16x32_bf16 v[104:107], v[188:191], v[196:199], v[104:107]
	v_mfma_f32_16x16x32_bf16 v[100:103], v[180:183], v[204:207], v[100:103]
	v_mfma_f32_16x16x32_bf16 v[96:99], v[188:191], v[204:207], v[96:99]
	v_mfma_f32_16x16x32_bf16 v[84:87], v[180:183], v[212:215], v[84:87]
	v_mfma_f32_16x16x32_bf16 v[80:83], v[188:191], v[212:215], v[80:83]
	v_mfma_f32_16x16x32_bf16 v[68:71], v[180:183], v[220:223], v[68:71]
	v_mfma_f32_16x16x32_bf16 v[64:67], v[188:191], v[220:223], v[64:67]
	s_setprio 0
	s_barrier
	s_add_i32 s53, s42, s30
	v_lshl_add_u64 v[158:159], s[26:27], 0, v[132:133]
	s_mov_b32 m0, s53
	ds_read_b128 v[192:195], v169 offset:16384
	ds_read_b128 v[196:199], v169 offset:17408
	ds_read_b128 v[200:203], v169 offset:18432
	ds_read_b128 v[204:207], v169 offset:19456
	ds_read_b128 v[208:211], v169 offset:20480
	ds_read_b128 v[212:215], v169 offset:21504
	ds_read_b128 v[216:219], v169 offset:22528
	ds_read_b128 v[220:223], v169 offset:23552
	global_load_lds_dwordx4 v[158:159], off
	s_add_i32 m0, s53, 0x2000
	s_add_u32 s54, s26, 0x40000
	v_lshl_add_u64 v[224:225], s[26:27], 0, v[128:129]
	s_addc_u32 s55, s27, 0
	s_add_i32 s53, s43, s30
	global_load_lds_dwordx4 v[224:225], off
	v_lshl_add_u64 v[226:227], s[54:55], 0, v[132:133]
	s_mov_b32 m0, s53
	v_lshl_add_u64 v[228:229], s[28:29], 0, v[130:131]
	global_load_lds_dwordx4 v[226:227], off
	v_lshl_add_u64 v[226:227], s[54:55], 0, v[128:129]
	s_add_i32 m0, s53, 0x2000
	s_nop 0
	global_load_lds_dwordx4 v[226:227], off
	v_lshl_add_u64 v[226:227], s[28:29], 0, v[134:135]
	s_mov_b32 m0, s35
	s_nop 0
	global_load_lds_dwordx4 v[226:227], off
	s_mov_b32 m0, s36
	s_nop 0
	global_load_lds_dwordx4 v[228:229], off
	s_waitcnt vmcnt(8)
	s_waitcnt lgkmcnt(0)
	s_barrier
; #define PG8_STAGE(bufoff, gbase, voff) do { _Pragma("unroll") for (int _i = 0; _i < 2; ++_i) \
;         __builtin_amdgcn_global_load_lds((const unsigned*)((const char*)(gbase) + (voff)[_i]), (LAS unsigned*)(lds + (bufoff) + ldsw + _i * 8192), 16, 0, 0); } while (0)
; #define PG8_LDA(dst, b, h) do { _Pragma("unroll") for (int m = 0; m < 4; ++m) _Pragma("unroll") for (int k = 0; k < 2; ++k) dst[m][k] = *(const LAS bf16x8*)(lds + PG8_SA(b, h) + aoff + m * 2048 + k * 1024); } while (0)
; #define PG8_LDB(dst, b, h) do { _Pragma("unroll") for (int n = 0; n < 2; ++n) _Pragma("unroll") for (int k = 0; k < 2; ++k) dst[n][k] = *(const LAS bf16x8*)(lds + PG8_SB(b, h) + boff + n * 2048 + k * 1024); } while (0)
; #define PG8_MMA(ai, bj, At, Bt) do { __builtin_amdgcn_s_setprio(1); _Pragma("unroll") for (int m = 0; m < 4; ++m) _Pragma("unroll") for (int n = 0; n < 2; ++n) _Pragma("unroll") for (int k = 0; k < 2; ++k) \
;         acc[ai][bj][m][n] = __builtin_amdgcn_mfma_f32_16x16x32_bf16(Bt[n][k], At[m][k], acc[ai][bj][m][n], 0, 0, 0); __builtin_amdgcn_s_setprio(0); } while (0)
; #define PG8_WAIT_V(n) asm volatile("s_waitcnt vmcnt(" #n ")" ::: "memory")
; #define PG8_WAIT_L(n) asm volatile("s_waitcnt lgkmcnt(" #n ")" ::: "memory")
; #define PG8_BAR __builtin_amdgcn_s_barrier()
; #define PG8_SCHED __builtin_amdgcn_sched_barrier(0)
; template <class Epi, bool ALIGN_EPI>
; DI void gemm_phase(lptr lds, const Gemm g, const StaticOrder& S, const Epi& E) {
;     ...
;             PG8_LDA(At, 0, 1); PG8_STAGE(PG8_SB(0, 0), b2, voffB); PG8_STAGE(PG8_SB(0, 1), b2 + hstepB, voffB); PG8_STAGE(PG8_SA(0, 0), a2, voffA);
;             PG8_WAIT_V(8); PG8_WAIT_L(0); PG8_BAR; PG8_MMA(1, 0, At, B0); PG8_MMA(1, 1, At, B1); PG8_BAR; PG8_SCHED;
;             PG8_LDB(B0, 1, 0); PG8_LDB(B1, 1, 1); PG8_SCHED; PG8_LDA(At, 1, 0); PG8_STAGE(PG8_SA(0, 1), a2 + hstepA, voffA);
;             PG8_WAIT_V(8); PG8_WAIT_L(0); PG8_BAR; PG8_MMA(0, 0, At, B0); PG8_MMA(0, 1, At, B1); PG8_BAR; PG8_SCHED;
;             PG8_LDA(At, 1, 1); PG8_STAGE(PG8_SB(1, 0), b3, voffB); PG8_STAGE(PG8_SB(1, 1), b3 + hstepB, voffB); PG8_STAGE(PG8_SA(1, 0), a3, voffA);
;             PG8_WAIT_V(8); PG8_WAIT_L(0); PG8_BAR; PG8_MMA(1, 0, At, B0); PG8_MMA(1, 1, At, B1); PG8_BAR; PG8_SCHED;
	s_setprio 1
	s_waitcnt lgkmcnt(0)
	v_mfma_f32_16x16x32_bf16 v[60:63], v[144:147], v[192:195], v[60:63]
	v_mfma_f32_16x16x32_bf16 v[56:59], v[154:157], v[192:195], v[56:59]
	v_mfma_f32_16x16x32_bf16 v[44:47], v[144:147], v[200:203], v[44:47]
	v_mfma_f32_16x16x32_bf16 v[40:43], v[154:157], v[200:203], v[40:43]
	v_mfma_f32_16x16x32_bf16 v[28:31], v[144:147], v[208:211], v[28:31]
	v_mfma_f32_16x16x32_bf16 v[24:27], v[154:157], v[208:211], v[24:27]
	v_mfma_f32_16x16x32_bf16 v[12:15], v[144:147], v[216:219], v[12:15]
	v_mfma_f32_16x16x32_bf16 v[8:11], v[154:157], v[216:219], v[8:11]
	v_mfma_f32_16x16x32_bf16 v[60:63], v[148:151], v[196:199], v[60:63]
	v_mfma_f32_16x16x32_bf16 v[56:59], v[172:175], v[196:199], v[56:59]
	v_mfma_f32_16x16x32_bf16 v[44:47], v[148:151], v[204:207], v[44:47]
	v_mfma_f32_16x16x32_bf16 v[40:43], v[172:175], v[204:207], v[40:43]
	v_mfma_f32_16x16x32_bf16 v[28:31], v[148:151], v[212:215], v[28:31]
	v_mfma_f32_16x16x32_bf16 v[24:27], v[172:175], v[212:215], v[24:27]
	v_mfma_f32_16x16x32_bf16 v[12:15], v[148:151], v[220:223], v[12:15]
	v_mfma_f32_16x16x32_bf16 v[8:11], v[172:175], v[220:223], v[8:11]
	s_setprio 0
	s_setprio 1
	v_mfma_f32_16x16x32_bf16 v[52:55], v[176:179], v[192:195], v[52:55]
	v_mfma_f32_16x16x32_bf16 v[48:51], v[184:187], v[192:195], v[48:51]
	v_mfma_f32_16x16x32_bf16 v[36:39], v[176:179], v[200:203], v[36:39]
	v_mfma_f32_16x16x32_bf16 v[32:35], v[184:187], v[200:203], v[32:35]
	v_mfma_f32_16x16x32_bf16 v[20:23], v[176:179], v[208:211], v[20:23]
	v_mfma_f32_16x16x32_bf16 v[16:19], v[184:187], v[208:211], v[16:19]
	v_mfma_f32_16x16x32_bf16 v[4:7], v[176:179], v[216:219], v[4:7]
	v_mfma_f32_16x16x32_bf16 v[0:3], v[184:187], v[216:219], v[0:3]
	v_mfma_f32_16x16x32_bf16 v[52:55], v[180:183], v[196:199], v[52:55]
	v_mfma_f32_16x16x32_bf16 v[48:51], v[188:191], v[196:199], v[48:51]
	v_mfma_f32_16x16x32_bf16 v[36:39], v[180:183], v[204:207], v[36:39]
	v_mfma_f32_16x16x32_bf16 v[32:35], v[188:191], v[204:207], v[32:35]
	v_mfma_f32_16x16x32_bf16 v[20:23], v[180:183], v[212:215], v[20:23]
	v_mfma_f32_16x16x32_bf16 v[16:19], v[188:191], v[212:215], v[16:19]
	v_mfma_f32_16x16x32_bf16 v[4:7], v[180:183], v[220:223], v[4:7]
	v_mfma_f32_16x16x32_bf16 v[0:3], v[188:191], v[220:223], v[0:3]
	s_setprio 0
	s_barrier
	s_add_i32 s53, 0, 0x18000
	v_add_u32_e32 v171, s53, v164
	s_add_i32 s54, 0, 0x1c000
	ds_read_b128 v[144:147], v171
	ds_read_b128 v[148:151], v171 offset:1024
	ds_read_b128 v[154:157], v171 offset:2048
	ds_read_b128 v[172:175], v171 offset:3072
	v_add_u32_e32 v171, s54, v164
	ds_read_b128 v[176:179], v171
	ds_read_b128 v[180:183], v171 offset:1024
	ds_read_b128 v[184:187], v171 offset:2048
	ds_read_b128 v[188:191], v171 offset:3072
	s_add_u32 s28, s28, 0x40000
	s_addc_u32 s29, s29, 0
	s_mov_b32 m0, s37
	v_lshl_add_u64 v[230:231], s[28:29], 0, v[134:135]
	ds_read_b128 v[192:195], v169 offset:32768
	ds_read_b128 v[196:199], v169 offset:33792
	ds_read_b128 v[200:203], v169 offset:34816
	ds_read_b128 v[204:207], v169 offset:35840
	ds_read_b128 v[208:211], v169 offset:36864
	ds_read_b128 v[212:215], v169 offset:37888
	ds_read_b128 v[216:219], v169 offset:38912
	ds_read_b128 v[220:223], v169 offset:39936
	global_load_lds_dwordx4 v[230:231], off
	v_lshl_add_u64 v[230:231], s[28:29], 0, v[130:131]
	s_mov_b32 m0, s38
	s_nop 0
	global_load_lds_dwordx4 v[230:231], off
	s_waitcnt vmcnt(8)
	s_waitcnt lgkmcnt(0)
	s_barrier
	s_setprio 1
	s_waitcnt lgkmcnt(0)
	v_mfma_f32_16x16x32_bf16 v[124:127], v[144:147], v[192:195], v[124:127]
	v_mfma_f32_16x16x32_bf16 v[120:123], v[154:157], v[192:195], v[120:123]
	v_mfma_f32_16x16x32_bf16 v[116:119], v[144:147], v[200:203], v[116:119]
	v_mfma_f32_16x16x32_bf16 v[112:115], v[154:157], v[200:203], v[112:115]
	v_mfma_f32_16x16x32_bf16 v[92:95], v[144:147], v[208:211], v[92:95]
	v_mfma_f32_16x16x32_bf16 v[88:91], v[154:157], v[208:211], v[88:91]
	v_mfma_f32_16x16x32_bf16 v[76:79], v[144:147], v[216:219], v[76:79]
	v_mfma_f32_16x16x32_bf16 v[72:75], v[154:157], v[216:219], v[72:75]
	v_mfma_f32_16x16x32_bf16 v[124:127], v[148:151], v[196:199], v[124:127]
	v_mfma_f32_16x16x32_bf16 v[120:123], v[172:175], v[196:199], v[120:123]
	v_mfma_f32_16x16x32_bf16 v[116:119], v[148:151], v[204:207], v[116:119]
	v_mfma_f32_16x16x32_bf16 v[112:115], v[172:175], v[204:207], v[112:115]
	v_mfma_f32_16x16x32_bf16 v[92:95], v[148:151], v[212:215], v[92:95]
	v_mfma_f32_16x16x32_bf16 v[88:91], v[172:175], v[212:215], v[88:91]
	v_mfma_f32_16x16x32_bf16 v[76:79], v[148:151], v[220:223], v[76:79]
	v_mfma_f32_16x16x32_bf16 v[72:75], v[172:175], v[220:223], v[72:75]
	s_setprio 0
	s_setprio 1
	v_mfma_f32_16x16x32_bf16 v[108:111], v[176:179], v[192:195], v[108:111]
	v_mfma_f32_16x16x32_bf16 v[104:107], v[184:187], v[192:195], v[104:107]
	v_mfma_f32_16x16x32_bf16 v[100:103], v[176:179], v[200:203], v[100:103]
	v_mfma_f32_16x16x32_bf16 v[96:99], v[184:187], v[200:203], v[96:99]
	v_mfma_f32_16x16x32_bf16 v[84:87], v[176:179], v[208:211], v[84:87]
	v_mfma_f32_16x16x32_bf16 v[80:83], v[184:187], v[208:211], v[80:83]
	v_mfma_f32_16x16x32_bf16 v[68:71], v[176:179], v[216:219], v[68:71]
	v_mfma_f32_16x16x32_bf16 v[64:67], v[184:187], v[216:219], v[64:67]
	v_mfma_f32_16x16x32_bf16 v[108:111], v[180:183], v[196:199], v[108:111]
	v_mfma_f32_16x16x32_bf16 v[104:107], v[188:191], v[196:199], v[104:107]
	v_mfma_f32_16x16x32_bf16 v[100:103], v[180:183], v[204:207], v[100:103]
	v_mfma_f32_16x16x32_bf16 v[96:99], v[188:191], v[204:207], v[96:99]
	v_mfma_f32_16x16x32_bf16 v[84:87], v[180:183], v[212:215], v[84:87]
	v_mfma_f32_16x16x32_bf16 v[80:83], v[188:191], v[212:215], v[80:83]
	v_mfma_f32_16x16x32_bf16 v[68:71], v[180:183], v[220:223], v[68:71]
	v_mfma_f32_16x16x32_bf16 v[64:67], v[188:191], v[220:223], v[64:67]
	s_setprio 0
	s_barrier
; #define PG8_MMA(ai, bj, At, Bt) do { __builtin_amdgcn_s_setprio(1); _Pragma("unroll") for (int m = 0; m < 4; ++m) _Pragma("unroll") for (int n = 0; n < 2; ++n) _Pragma("unroll") for (int k = 0; k < 2; ++k) \
;         acc[ai][bj][m][n] = __builtin_amdgcn_mfma_f32_16x16x32_bf16(Bt[n][k], At[m][k], acc[ai][bj][m][n], 0, 0, 0); __builtin_amdgcn_s_setprio(0); } while (0)
; #define PG8_WAIT_V(n) asm volatile("s_waitcnt vmcnt(" #n ")" ::: "memory")
; #define PG8_WAIT_L(n) asm volatile("s_waitcnt lgkmcnt(" #n ")" ::: "memory")
; #define PG8_BAR __builtin_amdgcn_s_barrier()
; #define PG8_SCHED __builtin_amdgcn_sched_barrier(0)
; template <class Epi, bool ALIGN_EPI>
; DI void gemm_phase(lptr lds, const Gemm g, const StaticOrder& S, const Epi& E) {
;     ...
;             PG8_WAIT_V(8); PG8_WAIT_L(0); PG8_BAR; PG8_MMA(1, 0, At, B0); PG8_MMA(1, 1, At, B1); PG8_BAR; PG8_SCHED;
;         }
;         if constexpr (ALIGN_EPI) { if (wr == 0) PG8_BAR; }
;     template <int NAI> DI void run(AccRef acc, const Unit& u, int wr, int wc, int fr, int fq) const {
;         const int cl = u.pn * 128 + wc * 32 + fq * 8;
;         float rsv[2][4];
; #pragma unroll
;         for (int ai = 0; ai < NAI; ++ai)
; #pragma unroll
;             for (int m = 0; m < 4; ++m) rsv[ai][m] = ssq[EPI_ROW(ai, m)];
; #pragma unroll
;         for (int ai = 0; ai < NAI; ++ai)
; #pragma unroll
;             for (int m = 0; m < 4; ++m) {
;                 const int row = EPI_ROW(ai, m); const float rs = __builtin_amdgcn_rsqf(rsv[ai][m] * (1.f / DM) + EPS);
	s_add_i32 s28, s53, s30
	v_lshl_add_u64 v[158:159], v[158:159], 0, s[10:11]
	s_mov_b32 m0, s28
	ds_read_b128 v[192:195], v169 offset:49152
	ds_read_b128 v[196:199], v169 offset:50176
	ds_read_b128 v[200:203], v169 offset:51200
	ds_read_b128 v[204:207], v169 offset:52224
	ds_read_b128 v[208:211], v169 offset:53248
	ds_read_b128 v[212:215], v169 offset:54272
	ds_read_b128 v[216:219], v169 offset:55296
	ds_read_b128 v[220:223], v169 offset:56320
	global_load_lds_dwordx4 v[158:159], off
	s_add_i32 m0, s28, 0x2000
	s_add_u32 s26, s26, 0x40080
	v_lshl_add_u64 v[158:159], v[224:225], 0, s[10:11]
	s_addc_u32 s27, s27, 0
	s_add_i32 s28, s54, s30
	global_load_lds_dwordx4 v[158:159], off
	v_lshl_add_u64 v[158:159], s[26:27], 0, v[132:133]
	s_mov_b32 m0, s28
	s_nop 0
	global_load_lds_dwordx4 v[158:159], off
	v_lshl_add_u64 v[158:159], s[26:27], 0, v[128:129]
	s_add_i32 m0, s28, 0x2000
	s_nop 0
	global_load_lds_dwordx4 v[158:159], off
	v_lshl_add_u64 v[158:159], v[226:227], 0, s[10:11]
	s_mov_b32 m0, s33
	s_nop 0
	global_load_lds_dwordx4 v[158:159], off
	v_lshl_add_u64 v[158:159], v[228:229], 0, s[10:11]
	s_mov_b32 m0, s40
	s_nop 0
	global_load_lds_dwordx4 v[158:159], off
	s_waitcnt vmcnt(8)
	s_waitcnt lgkmcnt(0)
	s_barrier
	s_setprio 1
	s_waitcnt lgkmcnt(0)
	v_mfma_f32_16x16x32_bf16 v[60:63], v[144:147], v[192:195], v[60:63]
	v_mfma_f32_16x16x32_bf16 v[56:59], v[154:157], v[192:195], v[56:59]
	v_mfma_f32_16x16x32_bf16 v[44:47], v[144:147], v[200:203], v[44:47]
	v_mfma_f32_16x16x32_bf16 v[40:43], v[154:157], v[200:203], v[40:43]
	v_mfma_f32_16x16x32_bf16 v[28:31], v[144:147], v[208:211], v[28:31]
	v_mfma_f32_16x16x32_bf16 v[24:27], v[154:157], v[208:211], v[24:27]
	v_mfma_f32_16x16x32_bf16 v[12:15], v[144:147], v[216:219], v[12:15]
	v_mfma_f32_16x16x32_bf16 v[8:11], v[154:157], v[216:219], v[8:11]
	v_mfma_f32_16x16x32_bf16 v[60:63], v[148:151], v[196:199], v[60:63]
	v_mfma_f32_16x16x32_bf16 v[56:59], v[172:175], v[196:199], v[56:59]
	v_mfma_f32_16x16x32_bf16 v[44:47], v[148:151], v[204:207], v[44:47]
	v_mfma_f32_16x16x32_bf16 v[40:43], v[172:175], v[204:207], v[40:43]
	v_mfma_f32_16x16x32_bf16 v[28:31], v[148:151], v[212:215], v[28:31]
	v_mfma_f32_16x16x32_bf16 v[24:27], v[172:175], v[212:215], v[24:27]
	v_mfma_f32_16x16x32_bf16 v[12:15], v[148:151], v[220:223], v[12:15]
	v_mfma_f32_16x16x32_bf16 v[8:11], v[172:175], v[220:223], v[8:11]
	s_setprio 0
	s_setprio 1
	v_mfma_f32_16x16x32_bf16 v[52:55], v[176:179], v[192:195], v[52:55]
	v_mfma_f32_16x16x32_bf16 v[48:51], v[184:187], v[192:195], v[48:51]
	v_mfma_f32_16x16x32_bf16 v[36:39], v[176:179], v[200:203], v[36:39]
	v_mfma_f32_16x16x32_bf16 v[32:35], v[184:187], v[200:203], v[32:35]
	v_mfma_f32_16x16x32_bf16 v[20:23], v[176:179], v[208:211], v[20:23]
	v_mfma_f32_16x16x32_bf16 v[16:19], v[184:187], v[208:211], v[16:19]
	v_mfma_f32_16x16x32_bf16 v[4:7], v[176:179], v[216:219], v[4:7]
	v_mfma_f32_16x16x32_bf16 v[0:3], v[184:187], v[216:219], v[0:3]
	v_mfma_f32_16x16x32_bf16 v[52:55], v[180:183], v[196:199], v[52:55]
	v_mfma_f32_16x16x32_bf16 v[48:51], v[188:191], v[196:199], v[48:51]
	v_mfma_f32_16x16x32_bf16 v[36:39], v[180:183], v[204:207], v[36:39]
	v_mfma_f32_16x16x32_bf16 v[32:35], v[188:191], v[204:207], v[32:35]
	v_mfma_f32_16x16x32_bf16 v[20:23], v[180:183], v[212:215], v[20:23]
	v_mfma_f32_16x16x32_bf16 v[16:19], v[188:191], v[212:215], v[16:19]
	v_mfma_f32_16x16x32_bf16 v[4:7], v[180:183], v[220:223], v[4:7]
	v_mfma_f32_16x16x32_bf16 v[0:3], v[188:191], v[220:223], v[0:3]
	s_setprio 0
	s_barrier
	s_add_i32 s52, s52, 2
	s_add_u32 s24, s24, 0x100
	s_addc_u32 s25, s25, 0
	s_add_u32 s50, s50, 0x100
	s_addc_u32 s51, s51, 0
	s_cmp_gt_u32 s52, 13
	s_cbranch_scc0 .LBB0_1281
	s_and_b64 vcc, exec, s[12:13]
	s_cbranch_vccz .LBB0_1284
	s_barrier
.LBB0_1284:
	v_add_u32_e32 v148, s46, v163
	v_ashrrev_i32_e32 v149, 31, v148
	v_lshl_add_u64 v[144:145], v[148:149], 2, s[6:7]
	v_add_u32_e32 v172, 16, v148
	global_load_dword v171, v[144:145], off
	v_ashrrev_i32_e32 v173, 31, v172
	v_lshl_add_u64 v[144:145], v[172:173], 2, s[6:7]
	global_load_dword v173, v[144:145], off
	v_lshl_or_b32 v174, s47, 7, v165
	v_add_u32_e32 v176, 32, v148
	v_mov_b64_e32 v[144:145], s[14:15]
	v_add_u32_e32 v158, 48, v148
	v_add_u32_e32 v156, 0x80, v148
	v_add_u32_e32 v154, 0x90, v148
	v_add_u32_e32 v150, 0xa0, v148
	v_add_u32_e32 v146, 0xb0, v148
	v_ashrrev_i32_e32 v175, 31, v174
	v_ashrrev_i32_e32 v177, 31, v176
	v_mad_i64_i32 v[178:179], s[24:25], v148, s44, v[144:145]
	v_ashrrev_i32_e32 v159, 31, v158
	v_ashrrev_i32_e32 v157, 31, v156
	v_ashrrev_i32_e32 v155, 31, v154
	v_ashrrev_i32_e32 v151, 31, v150
	v_ashrrev_i32_e32 v147, 31, v146
	v_lshlrev_b64 v[148:149], 1, v[174:175]
	v_lshl_add_u64 v[174:175], v[176:177], 2, s[6:7]
	v_lshl_add_u64 v[180:181], v[158:159], 2, s[6:7]
	v_lshl_add_u64 v[182:183], v[156:157], 2, s[6:7]
	v_lshl_add_u64 v[184:185], v[154:155], 2, s[6:7]
	v_lshl_add_u64 v[186:187], v[150:151], 2, s[6:7]
	v_lshl_add_u64 v[188:189], v[146:147], 2, s[6:7]
	global_load_dword v155, v[174:175], off
	global_load_dword v157, v[180:181], off
	global_load_dword v159, v[182:183], off
	global_load_dword v177, v[184:185], off
	global_load_dword v151, v[186:187], off
	global_load_dword v147, v[188:189], off
	v_lshl_add_u64 v[178:179], v[178:179], 0, v[148:149]
	s_andn2_b64 vcc, exec, s[2:3]
	s_mov_b64 s[2:3], -1
	s_waitcnt vmcnt(0)
; DI void st8(bf16_t* p, f32x4 a, f32x4 b) { u32x4 w; w.x = cvt_pk_bf16(a.x, a.y); w.y = cvt_pk_bf16(a.z, a.w); w.z = cvt_pk_bf16(b.x, b.y); w.w = cvt_pk_bf16(b.z, b.w); *(u32x4*)p = w; }
; DI f32x4 sigm4(f32x4 v) { f32x4 r; r.x = sigm(v.x); r.y = sigm(v.y); r.z = sigm(v.z); r.w = sigm(v.w); return r; }
;     template <int NAI> DI void run(AccRef acc, const Unit& u, int wr, int wc, int fr, int fq) const {
;         const int cl = u.pn * 128 + wc * 32 + fq * 8;
;         float rsv[2][4];
; #pragma unroll
;         for (int ai = 0; ai < NAI; ++ai)
; #pragma unroll
;             for (int m = 0; m < 4; ++m) rsv[ai][m] = ssq[EPI_ROW(ai, m)];
; #pragma unroll
;         for (int ai = 0; ai < NAI; ++ai)
; #pragma unroll
;             for (int m = 0; m < 4; ++m) {
;                 const int row = EPI_ROW(ai, m); const float rs = __builtin_amdgcn_rsqf(rsv[ai][m] * (1.f / DM) + EPS);
;                 const f32x4 g0 = acc[ai][0][m][0] * rs, g1 = acc[ai][0][m][1] * rs, u0 = acc[ai][1][m][0] * rs, u1 = acc[ai][1][m][1] * rs;
;                 st8(P + G_RV + (size_t)row * DFF + cl, g0 * sigm4(g0) * u0, g1 * sigm4(g1) * u1);
;             }
	v_fmamk_f32 v171, v171, 0x3a800000, v170
	v_rsq_f32_e32 v174, v171
	v_fmamk_f32 v171, v173, 0x3a800000, v170
	v_rsq_f32_e32 v180, v171
	v_pk_mul_f32 v[126:127], v[126:127], v[174:175] op_sel_hi:[1,0]
	v_pk_mul_f32 v[124:125], v[124:125], v[174:175] op_sel_hi:[1,0]
	v_pk_mul_f32 v[122:123], v[122:123], v[174:175] op_sel_hi:[1,0]
	v_pk_mul_f32 v[120:121], v[120:121], v[174:175] op_sel_hi:[1,0]
	v_mul_f32_e32 v171, 0xbfb8aa3b, v124
	v_mul_f32_e32 v173, 0xbfb8aa3b, v125
	v_mul_f32_e32 v181, 0xbfb8aa3b, v126
	v_mul_f32_e32 v184, 0xbfb8aa3b, v127
	v_mul_f32_e32 v185, 0xbfb8aa3b, v120
	v_mul_f32_e32 v186, 0xbfb8aa3b, v121
	v_mul_f32_e32 v187, 0xbfb8aa3b, v122
	v_mul_f32_e32 v188, 0xbfb8aa3b, v123
	v_pk_mul_f32 v[108:109], v[108:109], v[174:175] op_sel_hi:[1,0]
	v_pk_mul_f32 v[110:111], v[110:111], v[174:175] op_sel_hi:[1,0]
	v_pk_mul_f32 v[104:105], v[104:105], v[174:175] op_sel_hi:[1,0]
	v_pk_mul_f32 v[106:107], v[106:107], v[174:175] op_sel_hi:[1,0]
	v_pk_mul_f32 v[118:119], v[118:119], v[180:181] op_sel_hi:[1,0]
	v_pk_mul_f32 v[116:117], v[116:117], v[180:181] op_sel_hi:[1,0]
	v_pk_mul_f32 v[114:115], v[114:115], v[180:181] op_sel_hi:[1,0]
	v_pk_mul_f32 v[112:113], v[112:113], v[180:181] op_sel_hi:[1,0]
	v_pk_mul_f32 v[174:175], v[100:101], v[180:181] op_sel_hi:[1,0]
	v_pk_mul_f32 v[182:183], v[102:103], v[180:181] op_sel_hi:[1,0]
	v_pk_mul_f32 v[96:97], v[96:97], v[180:181] op_sel_hi:[1,0]
	v_exp_f32_e32 v100, v171
	v_exp_f32_e32 v101, v173
	v_exp_f32_e32 v102, v181
	v_exp_f32_e32 v103, v184
	v_exp_f32_e32 v171, v185
	v_exp_f32_e32 v173, v186
	v_exp_f32_e32 v181, v187
	v_exp_f32_e32 v184, v188
	v_add_f32_e32 v100, 1.0, v100
	v_add_f32_e32 v101, 1.0, v101
	v_add_f32_e32 v102, 1.0, v102
	v_add_f32_e32 v103, 1.0, v103
	v_add_f32_e32 v171, 1.0, v171
	v_add_f32_e32 v173, 1.0, v173
	v_add_f32_e32 v181, 1.0, v181
	v_add_f32_e32 v187, 1.0, v184
	v_rcp_f32_e32 v100, v100
	v_rcp_f32_e32 v101, v101
	v_rcp_f32_e32 v102, v102
	v_rcp_f32_e32 v103, v103
	v_rcp_f32_e32 v184, v171
	v_rcp_f32_e32 v185, v173
	v_rcp_f32_e32 v186, v181
	v_rcp_f32_e32 v187, v187
	v_pk_mul_f32 v[100:101], v[124:125], v[100:101]
	v_pk_mul_f32 v[102:103], v[126:127], v[102:103]
	v_pk_mul_f32 v[120:121], v[120:121], v[184:185]
	v_pk_mul_f32 v[122:123], v[122:123], v[186:187]
	v_pk_mul_f32 v[102:103], v[110:111], v[102:103]
	v_pk_mul_f32 v[100:101], v[108:109], v[100:101]
	v_pk_mul_f32 v[106:107], v[106:107], v[122:123]
	v_pk_mul_f32 v[104:105], v[104:105], v[120:121]
	v_cvt_pk_bf16_f32 v100, v100, v101
	v_cvt_pk_bf16_f32 v101, v102, v103
	v_cvt_pk_bf16_f32 v102, v104, v105
	v_cvt_pk_bf16_f32 v103, v106, v107
	global_store_dwordx4 v[178:179], v[100:103], off
	v_mul_f32_e32 v106, 0xbfb8aa3b, v112
	v_mul_f32_e32 v107, 0xbfb8aa3b, v113
	v_mul_f32_e32 v102, 0xbfb8aa3b, v116
	v_mul_f32_e32 v103, 0xbfb8aa3b, v117
	v_exp_f32_e32 v102, v102
	v_exp_f32_e32 v103, v103
	v_mul_f32_e32 v108, 0xbfb8aa3b, v114
	v_mul_f32_e32 v109, 0xbfb8aa3b, v115
	v_exp_f32_e32 v106, v106
	v_exp_f32_e32 v107, v107
	v_exp_f32_e32 v108, v108
	v_exp_f32_e32 v109, v109
	v_add_f32_e32 v102, 1.0, v102
	v_add_f32_e32 v103, 1.0, v103
	v_mul_f32_e32 v104, 0xbfb8aa3b, v118
	v_mul_f32_e32 v105, 0xbfb8aa3b, v119
	v_rcp_f32_e32 v102, v102
	v_exp_f32_e32 v104, v104
	v_exp_f32_e32 v105, v105
	v_rcp_f32_e32 v103, v103
	v_add_f32_e32 v106, 1.0, v106
	v_add_f32_e32 v107, 1.0, v107
	v_add_f32_e32 v108, 1.0, v108
	v_add_f32_e32 v109, 1.0, v109
	v_rcp_f32_e32 v106, v106
	v_rcp_f32_e32 v107, v107
	v_rcp_f32_e32 v108, v108
	v_rcp_f32_e32 v109, v109
	v_add_f32_e32 v104, 1.0, v104
	v_add_f32_e32 v105, 1.0, v105
	v_pk_mul_f32 v[102:103], v[116:117], v[102:103]
	v_pk_mul_f32 v[98:99], v[98:99], v[180:181] op_sel_hi:[1,0]
	v_rcp_f32_e32 v104, v104
	v_rcp_f32_e32 v105, v105
	v_pk_mul_f32 v[102:103], v[174:175], v[102:103]
	v_pk_mul_f32 v[106:107], v[112:113], v[106:107]
	v_pk_mul_f32 v[108:109], v[114:115], v[108:109]
	v_pk_mul_f32 v[104:105], v[118:119], v[104:105]
	v_pk_mul_f32 v[108:109], v[98:99], v[108:109]
	v_pk_mul_f32 v[98:99], v[96:97], v[106:107]
	v_cvt_pk_bf16_f32 v96, v102, v103
	v_fmamk_f32 v102, v155, 0x3a800000, v170
	v_rsq_f32_e32 v102, v102
	v_mad_i64_i32 v[100:101], s[24:25], v172, s44, v[144:145]
	v_pk_mul_f32 v[104:105], v[182:183], v[104:105]
	v_lshl_add_u64 v[100:101], v[100:101], 0, v[148:149]
	v_cvt_pk_bf16_f32 v97, v104, v105
	v_cvt_pk_bf16_f32 v98, v98, v99
	v_cvt_pk_bf16_f32 v99, v108, v109
	v_pk_mul_f32 v[94:95], v[94:95], v[102:103] op_sel_hi:[1,0]
	v_pk_mul_f32 v[92:93], v[92:93], v[102:103] op_sel_hi:[1,0]
	global_store_dwordx4 v[100:101], v[96:99], off
	v_mul_f32_e32 v100, 0xbfb8aa3b, v94
	v_mul_f32_e32 v101, 0xbfb8aa3b, v95
	v_mul_f32_e32 v98, 0xbfb8aa3b, v92
	v_mul_f32_e32 v99, 0xbfb8aa3b, v93
	v_exp_f32_e32 v98, v98
	v_exp_f32_e32 v99, v99
	v_exp_f32_e32 v100, v100
	v_exp_f32_e32 v101, v101
	v_add_f32_e32 v98, 1.0, v98
	v_add_f32_e32 v99, 1.0, v99
	v_add_f32_e32 v100, 1.0, v100
	v_add_f32_e32 v101, 1.0, v101
	v_rcp_f32_e32 v98, v98
	v_rcp_f32_e32 v99, v99
	v_rcp_f32_e32 v100, v100
	v_rcp_f32_e32 v101, v101
	v_pk_mul_f32 v[90:91], v[90:91], v[102:103] op_sel_hi:[1,0]
	v_pk_mul_f32 v[88:89], v[88:89], v[102:103] op_sel_hi:[1,0]
	v_pk_mul_f32 v[92:93], v[92:93], v[98:99]
	v_mul_f32_e32 v98, 0xbfb8aa3b, v88
	v_mul_f32_e32 v99, 0xbfb8aa3b, v89
	v_pk_mul_f32 v[94:95], v[94:95], v[100:101]
	v_mul_f32_e32 v100, 0xbfb8aa3b, v90
	v_mul_f32_e32 v101, 0xbfb8aa3b, v91
	v_exp_f32_e32 v98, v98
	v_exp_f32_e32 v99, v99
	v_exp_f32_e32 v100, v100
	v_exp_f32_e32 v101, v101
	v_add_f32_e32 v98, 1.0, v98
	v_add_f32_e32 v99, 1.0, v99
	v_add_f32_e32 v100, 1.0, v100
	v_add_f32_e32 v101, 1.0, v101
	v_rcp_f32_e32 v98, v98
; DI void st8(bf16_t* p, f32x4 a, f32x4 b) { u32x4 w; w.x = cvt_pk_bf16(a.x, a.y); w.y = cvt_pk_bf16(a.z, a.w); w.z = cvt_pk_bf16(b.x, b.y); w.w = cvt_pk_bf16(b.z, b.w); *(u32x4*)p = w; }
; DI f32x4 sigm4(f32x4 v) { f32x4 r; r.x = sigm(v.x); r.y = sigm(v.y); r.z = sigm(v.z); r.w = sigm(v.w); return r; }
;     template <int NAI> DI void run(AccRef acc, const Unit& u, int wr, int wc, int fr, int fq) const {
;         const int cl = u.pn * 128 + wc * 32 + fq * 8;
;         float rsv[2][4];
; #pragma unroll
;         for (int ai = 0; ai < NAI; ++ai)
; #pragma unroll
;             for (int m = 0; m < 4; ++m) rsv[ai][m] = ssq[EPI_ROW(ai, m)];
; #pragma unroll
;         for (int ai = 0; ai < NAI; ++ai)
; #pragma unroll
;             for (int m = 0; m < 4; ++m) {
;                 const int row = EPI_ROW(ai, m); const float rs = __builtin_amdgcn_rsqf(rsv[ai][m] * (1.f / DM) + EPS);
;                 const f32x4 g0 = acc[ai][0][m][0] * rs, g1 = acc[ai][0][m][1] * rs, u0 = acc[ai][1][m][0] * rs, u1 = acc[ai][1][m][1] * rs;
;                 st8(P + G_RV + (size_t)row * DFF + cl, g0 * sigm4(g0) * u0, g1 * sigm4(g1) * u1);
;             }
	v_rcp_f32_e32 v99, v99
	v_rcp_f32_e32 v100, v100
	v_rcp_f32_e32 v101, v101
	v_pk_mul_f32 v[84:85], v[84:85], v[102:103] op_sel_hi:[1,0]
	v_pk_mul_f32 v[80:81], v[80:81], v[102:103] op_sel_hi:[1,0]
	v_pk_mul_f32 v[82:83], v[82:83], v[102:103] op_sel_hi:[1,0]
	v_pk_mul_f32 v[84:85], v[84:85], v[92:93]
	v_pk_mul_f32 v[88:89], v[88:89], v[98:99]
	v_pk_mul_f32 v[90:91], v[90:91], v[100:101]
	v_pk_mul_f32 v[86:87], v[86:87], v[102:103] op_sel_hi:[1,0]
	v_pk_mul_f32 v[90:91], v[82:83], v[90:91]
	v_pk_mul_f32 v[82:83], v[80:81], v[88:89]
	v_cvt_pk_bf16_f32 v80, v84, v85
	v_fmamk_f32 v84, v157, 0x3a800000, v170
	v_rsq_f32_e32 v84, v84
	v_mad_i64_i32 v[96:97], s[24:25], v176, s44, v[144:145]
	v_pk_mul_f32 v[86:87], v[86:87], v[94:95]
	v_lshl_add_u64 v[96:97], v[96:97], 0, v[148:149]
	v_cvt_pk_bf16_f32 v81, v86, v87
	v_cvt_pk_bf16_f32 v82, v82, v83
	v_cvt_pk_bf16_f32 v83, v90, v91
	v_pk_mul_f32 v[78:79], v[78:79], v[84:85] op_sel_hi:[1,0]
	v_pk_mul_f32 v[76:77], v[76:77], v[84:85] op_sel_hi:[1,0]
	global_store_dwordx4 v[96:97], v[80:83], off
	v_pk_mul_f32 v[74:75], v[74:75], v[84:85] op_sel_hi:[1,0]
	v_pk_mul_f32 v[72:73], v[72:73], v[84:85] op_sel_hi:[1,0]
	v_pk_mul_f32 v[68:69], v[68:69], v[84:85] op_sel_hi:[1,0]
	v_pk_mul_f32 v[70:71], v[70:71], v[84:85] op_sel_hi:[1,0]
	v_pk_mul_f32 v[64:65], v[64:65], v[84:85] op_sel_hi:[1,0]
	v_pk_mul_f32 v[66:67], v[66:67], v[84:85] op_sel_hi:[1,0]
	v_mul_f32_e32 v82, 0xbfb8aa3b, v76
	v_mul_f32_e32 v83, 0xbfb8aa3b, v77
	v_mul_f32_e32 v84, 0xbfb8aa3b, v78
	v_mul_f32_e32 v85, 0xbfb8aa3b, v79
	v_exp_f32_e32 v82, v82
	v_exp_f32_e32 v83, v83
	v_exp_f32_e32 v84, v84
	v_exp_f32_e32 v85, v85
	v_add_f32_e32 v82, 1.0, v82
	v_add_f32_e32 v83, 1.0, v83
	v_add_f32_e32 v84, 1.0, v84
	v_add_f32_e32 v85, 1.0, v85
	v_rcp_f32_e32 v82, v82
	v_rcp_f32_e32 v83, v83
	v_rcp_f32_e32 v84, v84
	v_rcp_f32_e32 v85, v85
	v_mad_i64_i32 v[80:81], s[24:25], v158, s44, v[144:145]
	v_pk_mul_f32 v[76:77], v[76:77], v[82:83]
	v_mul_f32_e32 v82, 0xbfb8aa3b, v72
	v_mul_f32_e32 v83, 0xbfb8aa3b, v73
	v_pk_mul_f32 v[78:79], v[78:79], v[84:85]
	v_mul_f32_e32 v84, 0xbfb8aa3b, v74
	v_mul_f32_e32 v85, 0xbfb8aa3b, v75
	v_exp_f32_e32 v82, v82
	v_exp_f32_e32 v83, v83
	v_exp_f32_e32 v84, v84
	v_exp_f32_e32 v85, v85
	v_add_f32_e32 v82, 1.0, v82
	v_add_f32_e32 v83, 1.0, v83
	v_add_f32_e32 v84, 1.0, v84
	v_add_f32_e32 v85, 1.0, v85
	v_rcp_f32_e32 v82, v82
	v_rcp_f32_e32 v83, v83
	v_rcp_f32_e32 v84, v84
	v_rcp_f32_e32 v85, v85
	v_pk_mul_f32 v[68:69], v[68:69], v[76:77]
	v_pk_mul_f32 v[72:73], v[72:73], v[82:83]
	v_pk_mul_f32 v[70:71], v[70:71], v[78:79]
	v_pk_mul_f32 v[74:75], v[74:75], v[84:85]
	v_lshl_add_u64 v[80:81], v[80:81], 0, v[148:149]
	v_pk_mul_f32 v[74:75], v[66:67], v[74:75]
	v_pk_mul_f32 v[66:67], v[64:65], v[72:73]
	v_cvt_pk_bf16_f32 v64, v68, v69
	v_fmamk_f32 v68, v159, 0x3a800000, v170
	v_rsq_f32_e32 v68, v68
	v_cvt_pk_bf16_f32 v65, v70, v71
	v_cvt_pk_bf16_f32 v66, v66, v67
	v_cvt_pk_bf16_f32 v67, v74, v75
	v_pk_mul_f32 v[62:63], v[62:63], v[68:69] op_sel_hi:[1,0]
	v_pk_mul_f32 v[60:61], v[60:61], v[68:69] op_sel_hi:[1,0]
	global_store_dwordx4 v[80:81], v[64:67], off
	v_pk_mul_f32 v[58:59], v[58:59], v[68:69] op_sel_hi:[1,0]
	v_pk_mul_f32 v[56:57], v[56:57], v[68:69] op_sel_hi:[1,0]
	v_pk_mul_f32 v[52:53], v[52:53], v[68:69] op_sel_hi:[1,0]
	v_pk_mul_f32 v[54:55], v[54:55], v[68:69] op_sel_hi:[1,0]
	v_pk_mul_f32 v[48:49], v[48:49], v[68:69] op_sel_hi:[1,0]
	v_pk_mul_f32 v[50:51], v[50:51], v[68:69] op_sel_hi:[1,0]
	v_mul_f32_e32 v66, 0xbfb8aa3b, v60
	v_mul_f32_e32 v67, 0xbfb8aa3b, v61
	v_mul_f32_e32 v68, 0xbfb8aa3b, v62
	v_mul_f32_e32 v69, 0xbfb8aa3b, v63
	v_exp_f32_e32 v66, v66
	v_exp_f32_e32 v67, v67
	v_exp_f32_e32 v68, v68
	v_exp_f32_e32 v69, v69
	v_add_f32_e32 v66, 1.0, v66
	v_add_f32_e32 v67, 1.0, v67
	v_add_f32_e32 v68, 1.0, v68
	v_add_f32_e32 v69, 1.0, v69
	v_rcp_f32_e32 v66, v66
	v_rcp_f32_e32 v67, v67
	v_rcp_f32_e32 v68, v68
	v_rcp_f32_e32 v69, v69
	v_mad_i64_i32 v[64:65], s[24:25], v156, s44, v[144:145]
	v_pk_mul_f32 v[60:61], v[60:61], v[66:67]
	v_mul_f32_e32 v66, 0xbfb8aa3b, v56
	v_mul_f32_e32 v67, 0xbfb8aa3b, v57
	v_pk_mul_f32 v[62:63], v[62:63], v[68:69]
	v_mul_f32_e32 v68, 0xbfb8aa3b, v58
	v_mul_f32_e32 v69, 0xbfb8aa3b, v59
	v_exp_f32_e32 v66, v66
	v_exp_f32_e32 v67, v67
	v_exp_f32_e32 v68, v68
	v_exp_f32_e32 v69, v69
	v_add_f32_e32 v66, 1.0, v66
	v_add_f32_e32 v67, 1.0, v67
	v_add_f32_e32 v68, 1.0, v68
	v_add_f32_e32 v69, 1.0, v69
	v_rcp_f32_e32 v66, v66
	v_rcp_f32_e32 v67, v67
	v_rcp_f32_e32 v68, v68
	v_rcp_f32_e32 v69, v69
	v_pk_mul_f32 v[52:53], v[52:53], v[60:61]
	v_pk_mul_f32 v[56:57], v[56:57], v[66:67]
	v_pk_mul_f32 v[54:55], v[54:55], v[62:63]
	v_pk_mul_f32 v[58:59], v[58:59], v[68:69]
	v_lshl_add_u64 v[64:65], v[64:65], 0, v[148:149]
	v_pk_mul_f32 v[58:59], v[50:51], v[58:59]
	v_pk_mul_f32 v[50:51], v[48:49], v[56:57]
	v_cvt_pk_bf16_f32 v48, v52, v53
	v_fmamk_f32 v52, v177, 0x3a800000, v170
	v_rsq_f32_e32 v52, v52
	v_cvt_pk_bf16_f32 v49, v54, v55
	v_cvt_pk_bf16_f32 v50, v50, v51
	v_cvt_pk_bf16_f32 v51, v58, v59
	v_pk_mul_f32 v[46:47], v[46:47], v[52:53] op_sel_hi:[1,0]
	v_pk_mul_f32 v[44:45], v[44:45], v[52:53] op_sel_hi:[1,0]
	global_store_dwordx4 v[64:65], v[48:51], off
	v_pk_mul_f32 v[42:43], v[42:43], v[52:53] op_sel_hi:[1,0]
	v_pk_mul_f32 v[40:41], v[40:41], v[52:53] op_sel_hi:[1,0]
	v_pk_mul_f32 v[36:37], v[36:37], v[52:53] op_sel_hi:[1,0]
	v_pk_mul_f32 v[38:39], v[38:39], v[52:53] op_sel_hi:[1,0]
	v_pk_mul_f32 v[32:33], v[32:33], v[52:53] op_sel_hi:[1,0]
	v_pk_mul_f32 v[34:35], v[34:35], v[52:53] op_sel_hi:[1,0]
	v_mul_f32_e32 v50, 0xbfb8aa3b, v44
	v_mul_f32_e32 v51, 0xbfb8aa3b, v45
	v_mul_f32_e32 v52, 0xbfb8aa3b, v46
; DI void st8(bf16_t* p, f32x4 a, f32x4 b) { u32x4 w; w.x = cvt_pk_bf16(a.x, a.y); w.y = cvt_pk_bf16(a.z, a.w); w.z = cvt_pk_bf16(b.x, b.y); w.w = cvt_pk_bf16(b.z, b.w); *(u32x4*)p = w; }
; DI f32x4 sigm4(f32x4 v) { f32x4 r; r.x = sigm(v.x); r.y = sigm(v.y); r.z = sigm(v.z); r.w = sigm(v.w); return r; }
; #define PG8_BAR __builtin_amdgcn_s_barrier()
;     DI void prep(const Unit& u, int tid) const { if (tid < 256) *(LAS f32x4*)(tbl + (u.ui & 1) * 4096 + tid * 16) = factors(u.r0 + tid); }
; template <class Epi, bool ALIGN_EPI>
; DI void gemm_phase(lptr lds, const Gemm g, const StaticOrder& S, const Epi& E) {
;     ...
;         if (!has_next) break;
; #pragma unroll
;         for (int a = 0; a < 2; ++a)
; #pragma unroll
;             for (int b = 0; b < 2; ++b)
; #pragma unroll
;                 for (int m = 0; m < 4; ++m)
; #pragma unroll
;                     for (int n = 0; n < 2; ++n) acc[a][b][m][n] = (f32x4){0.f, 0.f, 0.f, 0.f};
;         cur = nxt; cA = nA; cB = nB; ++ui;
;         if constexpr (Epi::RESCALE) E.prep(cur, tid);
;         if constexpr (ALIGN_EPI) { if (wr == 1) PG8_BAR; }
;     template <int NAI> DI void run(AccRef acc, const Unit& u, int wr, int wc, int fr, int fq) const {
;     ...
;         for (int ai = 0; ai < NAI; ++ai)
; #pragma unroll
;             for (int m = 0; m < 4; ++m) {
;                 const int row = EPI_ROW(ai, m); const float rs = __builtin_amdgcn_rsqf(rsv[ai][m] * (1.f / DM) + EPS);
;                 const f32x4 g0 = acc[ai][0][m][0] * rs, g1 = acc[ai][0][m][1] * rs, u0 = acc[ai][1][m][0] * rs, u1 = acc[ai][1][m][1] * rs;
;                 st8(P + G_RV + (size_t)row * DFF + cl, g0 * sigm4(g0) * u0, g1 * sigm4(g1) * u1);
;             }
	v_mul_f32_e32 v53, 0xbfb8aa3b, v47
	v_exp_f32_e32 v50, v50
	v_exp_f32_e32 v51, v51
	v_exp_f32_e32 v52, v52
	v_exp_f32_e32 v53, v53
	v_add_f32_e32 v50, 1.0, v50
	v_add_f32_e32 v51, 1.0, v51
	v_add_f32_e32 v52, 1.0, v52
	v_add_f32_e32 v53, 1.0, v53
	v_rcp_f32_e32 v50, v50
	v_rcp_f32_e32 v51, v51
	v_rcp_f32_e32 v52, v52
	v_rcp_f32_e32 v53, v53
	v_mad_i64_i32 v[48:49], s[24:25], v154, s44, v[144:145]
	v_pk_mul_f32 v[44:45], v[44:45], v[50:51]
	v_mul_f32_e32 v50, 0xbfb8aa3b, v40
	v_mul_f32_e32 v51, 0xbfb8aa3b, v41
	v_pk_mul_f32 v[46:47], v[46:47], v[52:53]
	v_mul_f32_e32 v52, 0xbfb8aa3b, v42
	v_mul_f32_e32 v53, 0xbfb8aa3b, v43
	v_exp_f32_e32 v50, v50
	v_exp_f32_e32 v51, v51
	v_exp_f32_e32 v52, v52
	v_exp_f32_e32 v53, v53
	v_add_f32_e32 v50, 1.0, v50
	v_add_f32_e32 v51, 1.0, v51
	v_add_f32_e32 v52, 1.0, v52
	v_add_f32_e32 v53, 1.0, v53
	v_rcp_f32_e32 v50, v50
	v_rcp_f32_e32 v51, v51
	v_rcp_f32_e32 v52, v52
	v_rcp_f32_e32 v53, v53
	v_pk_mul_f32 v[36:37], v[36:37], v[44:45]
	v_pk_mul_f32 v[40:41], v[40:41], v[50:51]
	v_pk_mul_f32 v[38:39], v[38:39], v[46:47]
	v_pk_mul_f32 v[42:43], v[42:43], v[52:53]
	v_lshl_add_u64 v[48:49], v[48:49], 0, v[148:149]
	v_pk_mul_f32 v[42:43], v[34:35], v[42:43]
	v_pk_mul_f32 v[34:35], v[32:33], v[40:41]
	v_cvt_pk_bf16_f32 v32, v36, v37
	v_fmamk_f32 v36, v151, 0x3a800000, v170
	v_rsq_f32_e32 v36, v36
	v_cvt_pk_bf16_f32 v33, v38, v39
	v_cvt_pk_bf16_f32 v34, v34, v35
	v_cvt_pk_bf16_f32 v35, v42, v43
	v_pk_mul_f32 v[30:31], v[30:31], v[36:37] op_sel_hi:[1,0]
	v_pk_mul_f32 v[28:29], v[28:29], v[36:37] op_sel_hi:[1,0]
	global_store_dwordx4 v[48:49], v[32:35], off
	v_pk_mul_f32 v[26:27], v[26:27], v[36:37] op_sel_hi:[1,0]
	v_pk_mul_f32 v[24:25], v[24:25], v[36:37] op_sel_hi:[1,0]
	v_pk_mul_f32 v[20:21], v[20:21], v[36:37] op_sel_hi:[1,0]
	v_pk_mul_f32 v[22:23], v[22:23], v[36:37] op_sel_hi:[1,0]
	v_pk_mul_f32 v[16:17], v[16:17], v[36:37] op_sel_hi:[1,0]
	v_pk_mul_f32 v[18:19], v[18:19], v[36:37] op_sel_hi:[1,0]
	v_mul_f32_e32 v34, 0xbfb8aa3b, v28
	v_mul_f32_e32 v35, 0xbfb8aa3b, v29
	v_mul_f32_e32 v36, 0xbfb8aa3b, v30
	v_mul_f32_e32 v37, 0xbfb8aa3b, v31
	v_exp_f32_e32 v34, v34
	v_exp_f32_e32 v35, v35
	v_exp_f32_e32 v36, v36
	v_exp_f32_e32 v37, v37
	v_add_f32_e32 v34, 1.0, v34
	v_add_f32_e32 v35, 1.0, v35
	v_add_f32_e32 v36, 1.0, v36
	v_add_f32_e32 v37, 1.0, v37
	v_rcp_f32_e32 v34, v34
	v_rcp_f32_e32 v35, v35
	v_rcp_f32_e32 v36, v36
	v_rcp_f32_e32 v37, v37
	v_mad_i64_i32 v[32:33], s[24:25], v150, s44, v[144:145]
	v_pk_mul_f32 v[28:29], v[28:29], v[34:35]
	v_mul_f32_e32 v34, 0xbfb8aa3b, v24
	v_mul_f32_e32 v35, 0xbfb8aa3b, v25
	v_pk_mul_f32 v[30:31], v[30:31], v[36:37]
	v_mul_f32_e32 v36, 0xbfb8aa3b, v26
	v_mul_f32_e32 v37, 0xbfb8aa3b, v27
	v_exp_f32_e32 v34, v34
	v_exp_f32_e32 v35, v35
	v_exp_f32_e32 v36, v36
	v_exp_f32_e32 v37, v37
	v_add_f32_e32 v34, 1.0, v34
	v_add_f32_e32 v35, 1.0, v35
	v_add_f32_e32 v36, 1.0, v36
	v_add_f32_e32 v37, 1.0, v37
	v_rcp_f32_e32 v34, v34
	v_rcp_f32_e32 v35, v35
	v_rcp_f32_e32 v36, v36
	v_rcp_f32_e32 v37, v37
	v_pk_mul_f32 v[20:21], v[20:21], v[28:29]
	v_pk_mul_f32 v[24:25], v[24:25], v[34:35]
	v_pk_mul_f32 v[22:23], v[22:23], v[30:31]
	v_pk_mul_f32 v[26:27], v[26:27], v[36:37]
	v_lshl_add_u64 v[32:33], v[32:33], 0, v[148:149]
	v_pk_mul_f32 v[26:27], v[18:19], v[26:27]
	v_pk_mul_f32 v[18:19], v[16:17], v[24:25]
	v_cvt_pk_bf16_f32 v16, v20, v21
	v_fmamk_f32 v20, v147, 0x3a800000, v170
	v_rsq_f32_e32 v20, v20
	v_cvt_pk_bf16_f32 v17, v22, v23
	v_cvt_pk_bf16_f32 v18, v18, v19
	v_cvt_pk_bf16_f32 v19, v26, v27
	v_pk_mul_f32 v[14:15], v[14:15], v[20:21] op_sel_hi:[1,0]
	v_pk_mul_f32 v[12:13], v[12:13], v[20:21] op_sel_hi:[1,0]
	global_store_dwordx4 v[32:33], v[16:19], off
	v_pk_mul_f32 v[10:11], v[10:11], v[20:21] op_sel_hi:[1,0]
	v_pk_mul_f32 v[8:9], v[8:9], v[20:21] op_sel_hi:[1,0]
	v_pk_mul_f32 v[4:5], v[4:5], v[20:21] op_sel_hi:[1,0]
	v_pk_mul_f32 v[6:7], v[6:7], v[20:21] op_sel_hi:[1,0]
	v_pk_mul_f32 v[0:1], v[0:1], v[20:21] op_sel_hi:[1,0]
	v_pk_mul_f32 v[2:3], v[2:3], v[20:21] op_sel_hi:[1,0]
	v_mul_f32_e32 v18, 0xbfb8aa3b, v12
	v_mul_f32_e32 v19, 0xbfb8aa3b, v13
	v_mul_f32_e32 v20, 0xbfb8aa3b, v14
	v_mul_f32_e32 v21, 0xbfb8aa3b, v15
	v_exp_f32_e32 v18, v18
	v_exp_f32_e32 v19, v19
	v_exp_f32_e32 v20, v20
	v_exp_f32_e32 v21, v21
	v_add_f32_e32 v18, 1.0, v18
	v_add_f32_e32 v19, 1.0, v19
	v_add_f32_e32 v20, 1.0, v20
	v_add_f32_e32 v21, 1.0, v21
	v_rcp_f32_e32 v18, v18
	v_rcp_f32_e32 v19, v19
	v_rcp_f32_e32 v20, v20
	v_rcp_f32_e32 v21, v21
	v_mad_i64_i32 v[16:17], s[24:25], v146, s44, v[144:145]
	v_pk_mul_f32 v[12:13], v[12:13], v[18:19]
	v_mul_f32_e32 v18, 0xbfb8aa3b, v8
	v_mul_f32_e32 v19, 0xbfb8aa3b, v9
	v_pk_mul_f32 v[14:15], v[14:15], v[20:21]
	v_mul_f32_e32 v20, 0xbfb8aa3b, v10
	v_mul_f32_e32 v21, 0xbfb8aa3b, v11
	v_exp_f32_e32 v18, v18
	v_exp_f32_e32 v19, v19
	v_exp_f32_e32 v20, v20
	v_exp_f32_e32 v21, v21
	v_add_f32_e32 v18, 1.0, v18
	v_add_f32_e32 v19, 1.0, v19
	v_add_f32_e32 v20, 1.0, v20
	v_add_f32_e32 v21, 1.0, v21
	v_rcp_f32_e32 v18, v18
	v_rcp_f32_e32 v19, v19
	v_rcp_f32_e32 v20, v20
	v_rcp_f32_e32 v21, v21
	v_pk_mul_f32 v[6:7], v[6:7], v[14:15]
	v_pk_mul_f32 v[8:9], v[8:9], v[18:19]
	v_pk_mul_f32 v[4:5], v[4:5], v[12:13]
	v_pk_mul_f32 v[10:11], v[10:11], v[20:21]
	v_lshl_add_u64 v[16:17], v[16:17], 0, v[148:149]
	v_pk_mul_f32 v[10:11], v[2:3], v[10:11]
	v_pk_mul_f32 v[2:3], v[0:1], v[8:9]
	v_cvt_pk_bf16_f32 v0, v4, v5
	v_cvt_pk_bf16_f32 v1, v6, v7
	v_cvt_pk_bf16_f32 v2, v2, v3
	v_cvt_pk_bf16_f32 v3, v10, v11
	global_store_dwordx4 v[16:17], v[0:3], off
	s_cbranch_vccnz .LBB0_1277
	s_andn2_b64 vcc, exec, s[8:9]
	s_cbranch_vccnz .LBB0_1276
	s_barrier
	s_branch .LBB0_1276
; #define PG8_WAIT_V(n) asm volatile("s_waitcnt vmcnt(" #n ")" ::: "memory")
; #define PG8_BAR __builtin_amdgcn_s_barrier()
; template <class Epi, bool ALIGN_EPI>
; DI void gemm_phase(lptr lds, const Gemm g, const StaticOrder& S, const Epi& E) {
;     ...
;     PG8_WAIT_V(0);
;     if constexpr (!ALIGN_EPI) { if (wr == 0) PG8_BAR; }
;     PG8_BAR;
; template <class Epi>
; DI void mini_gemm_phase(lptr L, const pg8::Gemm g, const int row_base, const Epi& E) {
;     const int tid = threadIdx.x, wid = __builtin_amdgcn_readfirstlane(tid >> 6), lane = tid & 63, kh = wid >> 2, wc = wid & 3, fr = lane & 15, fq = lane >> 4;
;     const int nN = g.N / 256, nItems = (g.M / 64) * nN, G = gridDim.x, nt = g.K / 64;
;     constexpr int PB = 144, ST_A = 0, ST_B = 9216, ST_SZ = 46080;
;     const int arow = tid >> 3, ach = tid & 7;
;     for (int it = blockIdx.x; it < nItems; it += G) {
;         const int im = it / nN, in = it % nN;
;         const bf16_t* Ab = g.A + (size_t)(im * 64 + arow) * g.lda + ach * 8;
;         const bf16_t* Bb = g.Bt + (size_t)(in * 256 + arow) * g.K + ach * 8;
.LBB0_1287:
	s_waitcnt vmcnt(0)
	s_barrier
.LBB0_1288:
	s_cmpk_gt_i32 s64, 0x15f
	v_readfirstlane_b32 s8, v153
	s_cbranch_scc1 .LBB0_1305
	v_and_b32_e32 v0, 7, v153
	s_lshr_b32 s10, s8, 8
	v_lshlrev_b32_e32 v154, 4, v0
	v_mov_b32_e32 v155, 0
	s_lshr_b32 s12, s8, 6
	s_bfe_u32 s9, s8, 0x20006
	s_waitcnt lgkmcnt(0)
	v_lshl_add_u64 v[0:1], s[94:95], 0, v[154:155]
	s_mov_b64 s[2:3], 0xb000000
	v_lshl_add_u64 v[158:159], s[0:1], 0, v[154:155]
	s_lshl_b32 s1, s10, 6
	v_lshl_add_u64 v[156:157], v[0:1], 0, s[2:3]
	v_lshlrev_b32_e32 v1, 1, v153
	s_cmp_eq_u32 s10, 1
	v_and_b32_e32 v1, 24, v1
	s_cselect_b64 s[2:3], -1, 0
	s_lshl_b32 s20, s9, 14
	v_and_or_b32 v1, v153, 3, v1
	s_cmpk_lt_u32 s8, 0x100
	v_lshl_or_b32 v1, s9, 5, v1
	s_cselect_b64 s[8:9], -1, 0
	s_lshl_b32 s21, s12, 14
	s_add_u32 s10, s94, 0x13400000
	s_movk_i32 s0, 0x90
	v_and_b32_e32 v0, 48, v153
	v_and_b32_e32 v2, 0x3f0, v162
	s_addc_u32 s11, s95, 0
	v_add_u32_e32 v172, 0, v154
	s_add_i32 s1, s1, 0
	v_mov_b32_e32 v5, 0x4800
	v_mov_b32_e32 v6, 0x4a40
	v_mul_u32_u24_e32 v170, 0x90, v168
	v_add_u32_e32 v171, 0, v2
	v_mad_u32_u24 v2, v168, s0, 0
	v_add_u32_e32 v0, s1, v0
	v_mul_u32_u24_e32 v3, 0x90, v161
	v_mul_u32_u24_e32 v4, 0x90, v1
	v_mad_u32_u24 v5, v1, s0, v5
	v_mad_u32_u24 v1, v1, s0, v6
	v_add_u32_e32 v6, 0xd800, v172
	v_lshl_or_b32 v173, s12, 5, v160
	s_add_u32 s12, s94, 0xb000300
	v_or_b32_e32 v169, 0x10000, v161
	s_addc_u32 s13, s95, 0
	s_mov_b32 s22, 0x20000
	s_mov_b32 s23, 0x40000
	s_mov_b32 s24, 0x60000
	s_mov_b64 s[14:15], 0x200
	v_mov_b32_e32 v174, 0x358637bd
	s_movk_i32 s25, 0x1600
	v_add_u32_e32 v175, v2, v154
	v_add_u32_e32 v176, v0, v3
	v_add_u32_e32 v177, v0, v4
	v_add_u32_e32 v178, v6, v170
	v_add_u32_e32 v179, v0, v5
	v_add_u32_e32 v180, v0, v1
	s_mov_b32 s26, s64
	s_branch .LBB0_1291

; __global__ void __launch_bounds__(512, 2) fwd_mega(Params p) {
	.amdhsa_kernel _Z8fwd_mega6Params
		.amdhsa_group_segment_fixed_size 0
		.amdhsa_private_segment_fixed_size 0
		.amdhsa_kernarg_size 488
		.amdhsa_user_sgpr_count 2
		.amdhsa_user_sgpr_dispatch_ptr 0
		.amdhsa_user_sgpr_queue_ptr 0
		.amdhsa_user_sgpr_kernarg_segment_ptr 1
		.amdhsa_user_sgpr_dispatch_id 0
		.amdhsa_user_sgpr_kernarg_preload_length 0
		.amdhsa_user_sgpr_kernarg_preload_offset 0
		.amdhsa_user_sgpr_private_segment_size 0
		.amdhsa_uses_dynamic_stack 0
		.amdhsa_enable_private_segment 0
		.amdhsa_system_sgpr_workgroup_id_x 1
		.amdhsa_system_sgpr_workgroup_id_y 0
		.amdhsa_system_sgpr_workgroup_id_z 0
		.amdhsa_system_sgpr_workgroup_info 0
		.amdhsa_system_vgpr_workitem_id 2
		.amdhsa_next_free_vgpr 255
		.amdhsa_next_free_sgpr 99
		.amdhsa_accum_offset 256
		.amdhsa_reserve_vcc 1
		.amdhsa_float_round_mode_32 0
		.amdhsa_float_round_mode_16_64 0
		.amdhsa_float_denorm_mode_32 3
		.amdhsa_float_denorm_mode_16_64 3
		.amdhsa_dx10_clamp 1
		.amdhsa_ieee_mode 1
		.amdhsa_fp16_overflow 0
		.amdhsa_tg_split 0
		.amdhsa_exception_fp_ieee_invalid_op 0
		.amdhsa_exception_fp_denorm_src 0
		.amdhsa_exception_fp_ieee_div_zero 0
		.amdhsa_exception_fp_ieee_overflow 0
		.amdhsa_exception_fp_ieee_underflow 0
		.amdhsa_exception_fp_ieee_inexact 0
		.amdhsa_exception_int_div_zero 0
	.end_amdhsa_kernel

; __global__ void __launch_bounds__(512, 2) fwd_mega(Params p) {
amdhsa.kernels:
  - .agpr_count:     0
    .args:
      - .offset:         0
        .size:           232
        .value_kind:     by_value
      - .offset:         232
        .size:           4
        .value_kind:     hidden_block_count_x
      - .offset:         236
        .size:           4
        .value_kind:     hidden_block_count_y
      - .offset:         240
        .size:           4
        .value_kind:     hidden_block_count_z
      - .offset:         244
        .size:           2
        .value_kind:     hidden_group_size_x
      - .offset:         246
        .size:           2
        .value_kind:     hidden_group_size_y
      - .offset:         248
        .size:           2
        .value_kind:     hidden_group_size_z
      - .offset:         250
        .size:           2
        .value_kind:     hidden_remainder_x
      - .offset:         252
        .size:           2
        .value_kind:     hidden_remainder_y
      - .offset:         254
        .size:           2
        .value_kind:     hidden_remainder_z
      - .offset:         272
        .size:           8
        .value_kind:     hidden_global_offset_x
      - .offset:         280
        .size:           8
        .value_kind:     hidden_global_offset_y
      - .offset:         288
        .size:           8
        .value_kind:     hidden_global_offset_z
      - .offset:         296
        .size:           2
        .value_kind:     hidden_grid_dims
      - .offset:         320
        .size:           8
        .value_kind:     hidden_multigrid_sync_arg
      - .offset:         352
        .size:           4
        .value_kind:     hidden_dynamic_lds_size
    .group_segment_fixed_size: 0
    .kernarg_segment_align: 8
    .kernarg_segment_size: 488
    .language:       OpenCL C
    .language_version:
      - 2
      - 0
    .max_flat_workgroup_size: 512
    .name:           _Z8fwd_mega6Params
    .private_segment_fixed_size: 0
    .sgpr_count:     105
    .sgpr_spill_count: 35
    .symbol:         _Z8fwd_mega6Params.kd
    .uniform_work_group_size: 1
    .uses_dynamic_stack: false
    .vgpr_count:     255
    .vgpr_spill_count: 0
    .wavefront_size: 64
